# kprio4 + MLA/RET/S5 units assigned statically by workgroup id (one unit per workgroup, RET reversed) instead of atomic queue pops
# speedup vs baseline: 1.0064x; 1.0049x over previous
; __device__ __forceinline__ unsigned cvt_pk(float lo, float hi) { f32x2_t v = {lo, hi}; bf16x2_t b = __builtin_convertvector(v, bf16x2_t); return __builtin_bit_cast(unsigned, b); }
; template <int MODE>
; __device__ __forceinline__ void flash_unit(ArgsP A, int l, int b, int h, int qb, unsigned char* lds) {
;     ...
;     __syncthreads();
;     if (MODE == 0) {
;         const float inv = 1.f / (l_run + __shfl_xor(l_run, 32));
;         bf16_t* op = MIX + (size_t)qrow * DM + 512 + 128 * h;
; #pragma unroll
;         for (int c = 0; c < 4; ++c)
; #pragma unroll
;             for (int g4 = 0; g4 < 4; ++g4) { u32x2 w; w.x = cvt_pk(oacc[c][4 * g4] * inv, oacc[c][4 * g4 + 1] * inv); w.y = cvt_pk(oacc[c][4 * g4 + 2] * inv, oacc[c][4 * g4 + 3] * inv);
;                 *(u32x2*)(op + 32 * c + 8 * g4 + 4 * hh) = w; }
.LBB0_729:
	v_and_b32_e32 v65, 64, v179
	v_xor_b32_e32 v64, 32, v179
	v_add_u32_e32 v65, 64, v65
	v_cmp_lt_i32_e32 vcc, v64, v65
	s_lshl_b32 s18, s29, 8
	v_lshlrev_b32_e32 v176, 1, v164
	v_cndmask_b32_e32 v64, v179, v64, vcc
	v_lshlrev_b32_e32 v64, 2, v64
	ds_bpermute_b32 v64, v64, v171
	s_waitcnt lgkmcnt(0)
	s_barrier
	v_readlane_b32 s76, v255, 0
	v_add_f32_e32 v64, v171, v64
	v_div_scale_f32 v65, s[2:3], v64, v64, 1.0
	v_rcp_f32_e32 v66, v65
	s_mov_b64 s[2:3], 0x24f90400
	v_readlane_b32 s77, v255, 1
	v_readlane_b32 s58, v255, 2
	v_fma_f32 v67, -v65, v66, 1.0
	v_fmac_f32_e32 v66, v67, v66
	v_div_scale_f32 v67, vcc, 1.0, v64, 1.0
	v_mul_f32_e32 v68, v67, v66
	v_fma_f32 v69, -v65, v68, v67
	v_fmac_f32_e32 v68, v69, v66
	v_fma_f32 v65, -v65, v68, v67
	v_div_fmas_f32 v65, v65, v66, v68
	v_lshlrev_b64 v[66:67], 12, v[144:145]
	v_lshl_add_u64 v[66:67], s[40:41], 0, v[66:67]
	v_lshl_add_u64 v[66:67], v[66:67], 0, s[18:19]
	v_div_fixup_f32 v64, v65, v64, 1.0
	v_lshl_add_u64 v[66:67], v[66:67], 0, v[176:177]
	v_lshl_add_u64 v[68:69], v[66:67], 0, s[2:3]
	v_pk_mul_f32 v[48:49], v[48:49], v[64:65] op_sel_hi:[1,0]
	v_pk_mul_f32 v[50:51], v[50:51], v[64:65] op_sel_hi:[1,0]
	s_mov_b32 s2, 0x24f90000
	v_cvt_pk_bf16_f32 v48, v48, v49
	v_cvt_pk_bf16_f32 v49, v50, v51
	v_add_co_u32_e32 v50, vcc, s2, v66
	v_pk_mul_f32 v[32:33], v[32:33], v[64:65] op_sel_hi:[1,0]
	v_pk_mul_f32 v[34:35], v[34:35], v[64:65] op_sel_hi:[1,0]
	v_pk_mul_f32 v[16:17], v[16:17], v[64:65] op_sel_hi:[1,0]
	v_pk_mul_f32 v[18:19], v[18:19], v[64:65] op_sel_hi:[1,0]
	v_pk_mul_f32 v[0:1], v[0:1], v[64:65] op_sel_hi:[1,0]
	v_pk_mul_f32 v[2:3], v[2:3], v[64:65] op_sel_hi:[1,0]
	v_addc_co_u32_e32 v51, vcc, 0, v67, vcc
	v_cvt_pk_bf16_f32 v32, v32, v33
	v_cvt_pk_bf16_f32 v33, v34, v35
	v_cvt_pk_bf16_f32 v16, v16, v17
	v_cvt_pk_bf16_f32 v17, v18, v19
	v_cvt_pk_bf16_f32 v0, v0, v1
	v_cvt_pk_bf16_f32 v1, v2, v3
	global_store_dwordx2 v[50:51], v[48:49], off offset:1024
	v_pk_mul_f32 v[48:49], v[52:53], v[64:65] op_sel_hi:[1,0]
	v_pk_mul_f32 v[50:51], v[54:55], v[64:65] op_sel_hi:[1,0]
	global_store_dwordx2 v[68:69], v[32:33], off offset:64
	v_pk_mul_f32 v[32:33], v[36:37], v[64:65] op_sel_hi:[1,0]
	v_pk_mul_f32 v[34:35], v[38:39], v[64:65] op_sel_hi:[1,0]
	global_store_dwordx2 v[68:69], v[16:17], off offset:128
	v_pk_mul_f32 v[16:17], v[20:21], v[64:65] op_sel_hi:[1,0]
	v_pk_mul_f32 v[18:19], v[22:23], v[64:65] op_sel_hi:[1,0]
	global_store_dwordx2 v[68:69], v[0:1], off offset:192
	v_pk_mul_f32 v[0:1], v[4:5], v[64:65] op_sel_hi:[1,0]
	v_pk_mul_f32 v[2:3], v[6:7], v[64:65] op_sel_hi:[1,0]
	v_cvt_pk_bf16_f32 v48, v48, v49
	v_cvt_pk_bf16_f32 v49, v50, v51
	v_cvt_pk_bf16_f32 v32, v32, v33
	v_cvt_pk_bf16_f32 v33, v34, v35
	v_cvt_pk_bf16_f32 v16, v16, v17
	v_cvt_pk_bf16_f32 v17, v18, v19
	v_cvt_pk_bf16_f32 v0, v0, v1
	v_cvt_pk_bf16_f32 v1, v2, v3
	global_store_dwordx2 v[68:69], v[48:49], off offset:16
	v_pk_mul_f32 v[48:49], v[56:57], v[64:65] op_sel_hi:[1,0]
	v_pk_mul_f32 v[50:51], v[58:59], v[64:65] op_sel_hi:[1,0]
	global_store_dwordx2 v[68:69], v[32:33], off offset:80
	v_pk_mul_f32 v[32:33], v[40:41], v[64:65] op_sel_hi:[1,0]
	v_pk_mul_f32 v[34:35], v[42:43], v[64:65] op_sel_hi:[1,0]
	global_store_dwordx2 v[68:69], v[16:17], off offset:144
	v_pk_mul_f32 v[16:17], v[24:25], v[64:65] op_sel_hi:[1,0]
	v_pk_mul_f32 v[18:19], v[26:27], v[64:65] op_sel_hi:[1,0]
	global_store_dwordx2 v[68:69], v[0:1], off offset:208
	v_pk_mul_f32 v[0:1], v[8:9], v[64:65] op_sel_hi:[1,0]
	v_pk_mul_f32 v[2:3], v[10:11], v[64:65] op_sel_hi:[1,0]
	v_cvt_pk_bf16_f32 v48, v48, v49
	v_cvt_pk_bf16_f32 v49, v50, v51
	v_cvt_pk_bf16_f32 v32, v32, v33
	v_cvt_pk_bf16_f32 v33, v34, v35
	v_cvt_pk_bf16_f32 v16, v16, v17
	v_cvt_pk_bf16_f32 v17, v18, v19
	v_cvt_pk_bf16_f32 v0, v0, v1
	v_cvt_pk_bf16_f32 v1, v2, v3
	global_store_dwordx2 v[68:69], v[48:49], off offset:32
	v_pk_mul_f32 v[48:49], v[60:61], v[64:65] op_sel_hi:[1,0]
	v_pk_mul_f32 v[50:51], v[62:63], v[64:65] op_sel_hi:[1,0]
	global_store_dwordx2 v[68:69], v[32:33], off offset:96
	v_pk_mul_f32 v[32:33], v[44:45], v[64:65] op_sel_hi:[1,0]
	v_pk_mul_f32 v[34:35], v[46:47], v[64:65] op_sel_hi:[1,0]
	global_store_dwordx2 v[68:69], v[16:17], off offset:160
	v_pk_mul_f32 v[16:17], v[28:29], v[64:65] op_sel_hi:[1,0]
	v_pk_mul_f32 v[18:19], v[30:31], v[64:65] op_sel_hi:[1,0]
	global_store_dwordx2 v[68:69], v[0:1], off offset:224
	v_pk_mul_f32 v[0:1], v[12:13], v[64:65] op_sel_hi:[1,0]
	v_pk_mul_f32 v[2:3], v[14:15], v[64:65] op_sel_hi:[1,0]
	v_readlane_b32 s60, v255, 4
	v_readlane_b32 s64, v255, 8
	v_readlane_b32 s66, v255, 11
	v_readlane_b32 s26, v255, 29
	v_readlane_b32 s30, v255, 31
	v_cvt_pk_bf16_f32 v48, v48, v49
	v_cvt_pk_bf16_f32 v49, v50, v51
	v_cvt_pk_bf16_f32 v32, v32, v33
	v_cvt_pk_bf16_f32 v33, v34, v35
	v_cvt_pk_bf16_f32 v16, v16, v17
	v_cvt_pk_bf16_f32 v17, v18, v19
	v_cvt_pk_bf16_f32 v0, v0, v1
	v_cvt_pk_bf16_f32 v1, v2, v3
	s_mov_b64 s[2:3], -1
	v_readlane_b32 s74, v254, 63
	v_readlane_b32 s59, v255, 3
	v_readlane_b32 s61, v255, 5
	v_readlane_b32 s57, v255, 6
	v_readlane_b32 s62, v255, 7
	v_readlane_b32 s65, v255, 9
	v_readlane_b32 s63, v255, 10
	v_readlane_b32 s67, v255, 12
	s_movk_i32 s68, 0x100
	v_readlane_b32 s69, v255, 13
	s_mov_b32 s70, 0x80000
	s_mov_b32 s71, 0x90000
	s_mov_b32 s72, 0xa0000
	s_mov_b32 s73, 0xb0000
	s_movk_i32 s75, 0x1000
	s_mov_b32 s77, 0xf800000
	s_mov_b64 s[78:79], 0x80000
	s_mov_b64 s[80:81], 0x90000
	s_mov_b64 s[82:83], 0xa0000
	s_mov_b64 s[84:85], 0xb0000
	s_mov_b32 s86, 0x3b000000
	s_mov_b64 s[88:89], 0xb80
	s_mov_b64 s[90:91], 0xd80
	v_readlane_b32 s92, v255, 27
	v_readlane_b32 s27, v255, 30
	v_readlane_b32 s31, v255, 32
	global_store_dwordx2 v[68:69], v[48:49], off offset:48
	global_store_dwordx2 v[68:69], v[32:33], off offset:112
	global_store_dwordx2 v[68:69], v[16:17], off offset:176
	global_store_dwordx2 v[68:69], v[0:1], off offset:240
	v_readlane_b32 s93, v255, 28

; #define QLOOP2(qi_, r2_, n_, ...) for (;;) { if (tid == 0) s_item = (int)atomicAdd(ctr + 64 * (qi_) + 32 * (r2_), 1u); __syncthreads(); const int item = s_item; __syncthreads(); if (item >= (n_)) break; __VA_ARGS__ }
; template <int PHM, int MIXM>
; __global__ void __launch_bounds__(512, 2) mega(Args Aval) {
;     ...
;             for (int r2 = 0; r2 < ((PROBE_DUP & 16) ? 2 : 1); ++r2) if (MIXM & 1) QLOOP2(0, r2, 256, { const int L = 15 - (item >> 4), r = item & 15; flash_unit<0>(A, l, r >> 2, r & 3, L, lds); })
.LBB0_731:
	s_waitcnt lgkmcnt(0)
	s_barrier
	v_readlane_b32 s4, v255, 41
	s_mov_b64 s[2:3], -1
	v_readfirstlane_b32 s100, v238
	s_cmp_lt_u32 s100, 0x100
	s_cbranch_scc1 .Lprio_skip_mla
	s_setprio 1

; __device__ __forceinline__ unsigned cvt_pk(float lo, float hi) { f32x2_t v = {lo, hi}; bf16x2_t b = __builtin_convertvector(v, bf16x2_t); return __builtin_bit_cast(unsigned, b); }
; __device__ __forceinline__ float bflo(unsigned w) { return __uint_as_float(w << 16); }
; __device__ __forceinline__ float bfhi(unsigned w) { return __uint_as_float(w & 0xffff0000u); }
; __device__ __forceinline__ float sigmoidf_(float x) { return fast_rcp(1.f + fast_exp2(-x * LOG2E)); }
; template <int MODE>
; __device__ __forceinline__ void flash_unit(ArgsP A, int l, int b, int h, int qb, unsigned char* lds) {
;     ...
;         float s = 0.f;
; #pragma unroll
;         for (int c = 0; c < 4; ++c)
; #pragma unroll
;             for (int i = 0; i < 16; ++i) s += oacc[c][i];
;         s += __shfl_xor(s, 32);
;         const float mu = s * (1.f / 128); float v = 0.f;
; #pragma unroll
;         for (int c = 0; c < 4; ++c)
; #pragma unroll
;             for (int i = 0; i < 16; ++i) { const float d = oacc[c][i] - mu; oacc[c][i] = d; v += d * d; }
;         v += __shfl_xor(v, 32);
;         const float r = 1.f / sqrtf(v * (1.f / 128) + 1e-5f);
;         bf16_t* op = MIX + (size_t)qrow * DM + 1024 + 128 * h; const bf16_t* gp = PROJ + (size_t)qrow * INWP + C_RG + 128 * h;
;         u32x2 gwv[4][4];
; #pragma unroll
;         for (int c = 0; c < 4; ++c)
; #pragma unroll
;             for (int g4 = 0; g4 < 4; ++g4) gwv[c][g4] = *(const u32x2*)(gp + 32 * c + 8 * g4 + 4 * hh);
; #pragma unroll
;         for (int c = 0; c < 4; ++c)
; #pragma unroll
;             for (int g4 = 0; g4 < 4; ++g4) { const int d = 32 * c + 8 * g4 + 4 * hh; const u32x2 gw = gwv[c][g4];
;                 const float g0 = bflo(gw.x), g1 = bfhi(gw.x), g2 = bflo(gw.y), g3 = bfhi(gw.y);
;                 u32x2 w; w.x = cvt_pk(oacc[c][4 * g4] * r * g0 * sigmoidf_(g0), oacc[c][4 * g4 + 1] * r * g1 * sigmoidf_(g1));
.LBB0_759:
	s_nop 2
	v_add_f32_e32 v64, 0, v48
	v_add_f32_e32 v64, v49, v64
	v_add_f32_e32 v64, v50, v64
	v_add_f32_e32 v64, v51, v64
	v_add_f32_e32 v64, v52, v64
	v_add_f32_e32 v64, v53, v64
	v_add_f32_e32 v64, v54, v64
	v_add_f32_e32 v64, v55, v64
	v_add_f32_e32 v64, v56, v64
	v_add_f32_e32 v64, v57, v64
	v_add_f32_e32 v64, v58, v64
	v_add_f32_e32 v64, v59, v64
	v_add_f32_e32 v64, v60, v64
	v_add_f32_e32 v64, v61, v64
	v_add_f32_e32 v64, v62, v64
	v_add_f32_e32 v64, v63, v64
	v_add_f32_e32 v64, v32, v64
	v_add_f32_e32 v64, v33, v64
	v_add_f32_e32 v64, v34, v64
	v_add_f32_e32 v64, v35, v64
	v_add_f32_e32 v64, v36, v64
	v_add_f32_e32 v64, v37, v64
	v_add_f32_e32 v64, v38, v64
	s_lshl_b32 s18, s18, 1
	v_add_f32_e32 v68, v39, v64
	v_lshl_add_u64 v[64:65], v[162:163], 0, s[18:19]
	v_lshlrev_b32_e32 v176, 1, v198
	v_lshl_add_u64 v[64:65], v[64:65], 0, v[176:177]
	v_add_co_u32_e32 v66, vcc, s75, v64
	s_nop 1
	v_addc_co_u32_e32 v67, vcc, 0, v65, vcc
	s_barrier
	global_load_dwordx2 v[74:75], v[66:67], off offset:384
	v_add_f32_e32 v66, v40, v68
	v_add_f32_e32 v66, v41, v66
	v_add_f32_e32 v66, v42, v66
	v_add_f32_e32 v66, v43, v66
	v_add_f32_e32 v66, v44, v66
	v_add_f32_e32 v66, v45, v66
	v_add_f32_e32 v66, v46, v66
	v_add_f32_e32 v66, v47, v66
	v_add_f32_e32 v66, v16, v66
	v_add_f32_e32 v66, v17, v66
	v_add_f32_e32 v66, v18, v66
	v_add_f32_e32 v66, v19, v66
	v_add_f32_e32 v66, v20, v66
	v_add_f32_e32 v66, v21, v66
	v_add_f32_e32 v66, v22, v66
	v_add_f32_e32 v66, v23, v66
	v_add_f32_e32 v66, v24, v66
	v_add_f32_e32 v66, v25, v66
	v_add_f32_e32 v66, v26, v66
	s_mov_b64 s[4:5], 0x1180
	v_add_f32_e32 v66, v27, v66
	v_lshl_add_u64 v[68:69], v[64:65], 0, s[4:5]
	v_add_f32_e32 v66, v28, v66
	global_load_dwordx2 v[90:91], v[68:69], off offset:16
	global_load_dwordx2 v[98:99], v[68:69], off offset:32
	v_add_f32_e32 v66, v29, v66
	v_add_f32_e32 v66, v30, v66
	v_add_f32_e32 v66, v31, v66
	v_add_f32_e32 v64, v0, v66
	v_add_f32_e32 v64, v1, v64
	v_add_f32_e32 v64, v2, v64
	v_add_f32_e32 v64, v3, v64
	v_add_f32_e32 v64, v4, v64
	v_add_f32_e32 v64, v5, v64
	v_add_f32_e32 v64, v6, v64
	v_add_f32_e32 v64, v7, v64
	v_add_f32_e32 v64, v8, v64
	v_add_f32_e32 v64, v9, v64
	v_add_f32_e32 v64, v10, v64
	v_add_f32_e32 v64, v11, v64
	v_and_b32_e32 v66, 64, v179
	v_add_f32_e32 v64, v12, v64
	v_xor_b32_e32 v65, 32, v179
	v_add_u32_e32 v66, 64, v66
	v_add_f32_e32 v64, v13, v64
	v_cmp_lt_i32_e32 vcc, v65, v66
	v_add_f32_e32 v64, v14, v64
	v_add_f32_e32 v64, v15, v64
	v_cndmask_b32_e32 v65, v179, v65, vcc
	v_lshlrev_b32_e32 v243, 2, v65
	ds_bpermute_b32 v65, v243, v64
	v_mov_b32_e32 v244, v179
	s_waitcnt lgkmcnt(0)
	v_add_f32_e32 v64, v64, v65
	v_mul_f32_e32 v128, 0x3c000000, v64
	v_pk_add_f32 v[142:143], v[14:15], v[128:129] op_sel_hi:[1,0] neg_lo:[0,1] neg_hi:[0,1]
	v_lshlrev_b64 v[14:15], 12, v[160:161]
	v_lshl_add_u64 v[70:71], s[2:3], 0, v[14:15]
	global_load_dwordx2 v[106:107], v[68:69], off offset:48
	global_load_dwordx2 v[120:121], v[68:69], off offset:64
	global_load_dwordx2 v[134:135], v[68:69], off offset:80
	global_load_dwordx2 v[146:147], v[68:69], off offset:96
	global_load_dwordx2 v[158:159], v[68:69], off offset:112
	global_load_dwordx2 v[170:171], v[68:69], off offset:128
	global_load_dwordx2 v[190:191], v[68:69], off offset:144
	global_load_dwordx2 v[200:201], v[68:69], off offset:160
	global_load_dwordx2 v[174:175], v[68:69], off offset:176
	global_load_dwordx2 v[130:131], v[68:69], off offset:192
	global_load_dwordx2 v[114:115], v[68:69], off offset:208
	global_load_dwordx2 v[66:67], v[68:69], off offset:224
	global_load_dwordx2 v[14:15], v[68:69], off offset:240
	v_lshl_add_u64 v[76:77], v[70:71], 0, s[18:19]
	v_pk_add_f32 v[70:71], v[48:49], v[128:129] op_sel_hi:[1,0] neg_lo:[0,1] neg_hi:[0,1]
	v_pk_add_f32 v[64:65], v[10:11], v[128:129] op_sel_hi:[1,0] neg_lo:[0,1] neg_hi:[0,1]
	v_pk_add_f32 v[12:13], v[12:13], v[128:129] op_sel_hi:[1,0] neg_lo:[0,1] neg_hi:[0,1]
	v_pk_add_f32 v[50:51], v[50:51], v[128:129] op_sel_hi:[1,0] neg_lo:[0,1] neg_hi:[0,1]
	v_pk_add_f32 v[54:55], v[54:55], v[128:129] op_sel_hi:[1,0] neg_lo:[0,1] neg_hi:[0,1]
	v_pk_add_f32 v[52:53], v[52:53], v[128:129] op_sel_hi:[1,0] neg_lo:[0,1] neg_hi:[0,1]
	v_pk_add_f32 v[58:59], v[58:59], v[128:129] op_sel_hi:[1,0] neg_lo:[0,1] neg_hi:[0,1]
	v_pk_add_f32 v[56:57], v[56:57], v[128:129] op_sel_hi:[1,0] neg_lo:[0,1] neg_hi:[0,1]
	v_pk_add_f32 v[62:63], v[62:63], v[128:129] op_sel_hi:[1,0] neg_lo:[0,1] neg_hi:[0,1]
	v_pk_add_f32 v[60:61], v[60:61], v[128:129] op_sel_hi:[1,0] neg_lo:[0,1] neg_hi:[0,1]
	v_pk_add_f32 v[34:35], v[34:35], v[128:129] op_sel_hi:[1,0] neg_lo:[0,1] neg_hi:[0,1]
	v_pk_add_f32 v[32:33], v[32:33], v[128:129] op_sel_hi:[1,0] neg_lo:[0,1] neg_hi:[0,1]
	v_pk_add_f32 v[38:39], v[38:39], v[128:129] op_sel_hi:[1,0] neg_lo:[0,1] neg_hi:[0,1]
	v_pk_add_f32 v[36:37], v[36:37], v[128:129] op_sel_hi:[1,0] neg_lo:[0,1] neg_hi:[0,1]
	v_pk_mul_f32 v[118:119], v[70:71], v[70:71]
	v_pk_mul_f32 v[108:109], v[50:51], v[50:51]
	v_pk_mul_f32 v[136:137], v[52:53], v[52:53]
	s_waitcnt vmcnt(15)
	v_lshlrev_b32_e32 v72, 16, v74
	v_and_b32_e32 v73, 0xffff0000, v74
	v_mul_f32_e32 v48, 0xbfb8aa3b, v72
	v_exp_f32_e32 v48, v48
	v_mul_f32_e32 v49, 0xbfb8aa3b, v73
	v_exp_f32_e32 v49, v49
	v_lshlrev_b32_e32 v68, 16, v75
	v_add_f32_e32 v48, 1.0, v48
	v_and_b32_e32 v69, 0xffff0000, v75
	v_rcp_f32_e32 v74, v48
	v_add_f32_e32 v48, 1.0, v49
	v_mul_f32_e32 v49, 0xbfb8aa3b, v68
	v_exp_f32_e32 v49, v49
	v_mul_f32_e32 v75, 0xbfb8aa3b, v69
	v_exp_f32_e32 v78, v75
	v_rcp_f32_e32 v75, v48
	v_add_f32_e32 v48, 1.0, v49
	v_rcp_f32_e32 v86, v48
	v_add_f32_e32 v48, 1.0, v78
	v_lshl_add_u64 v[78:79], v[76:77], 0, v[176:177]
	v_pk_mul_f32 v[126:127], v[54:55], v[54:55]
	v_pk_mul_f32 v[148:149], v[56:57], v[56:57]
	v_pk_mul_f32 v[80:81], v[58:59], v[58:59]
	v_pk_mul_f32 v[164:165], v[60:61], v[60:61]
	s_waitcnt vmcnt(14)
; __device__ __forceinline__ unsigned cvt_pk(float lo, float hi) { f32x2_t v = {lo, hi}; bf16x2_t b = __builtin_convertvector(v, bf16x2_t); return __builtin_bit_cast(unsigned, b); }
; __device__ __forceinline__ float bflo(unsigned w) { return __uint_as_float(w << 16); }
; __device__ __forceinline__ float bfhi(unsigned w) { return __uint_as_float(w & 0xffff0000u); }
; __device__ __forceinline__ float sigmoidf_(float x) { return fast_rcp(1.f + fast_exp2(-x * LOG2E)); }
; template <int MODE>
; __device__ __forceinline__ void flash_unit(ArgsP A, int l, int b, int h, int qb, unsigned char* lds) {
;     ...
;         const float mu = s * (1.f / 128); float v = 0.f;
; #pragma unroll
;         for (int c = 0; c < 4; ++c)
; #pragma unroll
;             for (int i = 0; i < 16; ++i) { const float d = oacc[c][i] - mu; oacc[c][i] = d; v += d * d; }
;         v += __shfl_xor(v, 32);
;         const float r = 1.f / sqrtf(v * (1.f / 128) + 1e-5f);
;         bf16_t* op = MIX + (size_t)qrow * DM + 1024 + 128 * h; const bf16_t* gp = PROJ + (size_t)qrow * INWP + C_RG + 128 * h;
;         u32x2 gwv[4][4];
; #pragma unroll
;         for (int c = 0; c < 4; ++c)
; #pragma unroll
;             for (int g4 = 0; g4 < 4; ++g4) gwv[c][g4] = *(const u32x2*)(gp + 32 * c + 8 * g4 + 4 * hh);
; #pragma unroll
;         for (int c = 0; c < 4; ++c)
; #pragma unroll
;             for (int g4 = 0; g4 < 4; ++g4) { const int d = 32 * c + 8 * g4 + 4 * hh; const u32x2 gw = gwv[c][g4];
;                 const float g0 = bflo(gw.x), g1 = bfhi(gw.x), g2 = bflo(gw.y), g3 = bfhi(gw.y);
;                 u32x2 w; w.x = cvt_pk(oacc[c][4 * g4] * r * g0 * sigmoidf_(g0), oacc[c][4 * g4 + 1] * r * g1 * sigmoidf_(g1));
	v_lshlrev_b32_e32 v76, 16, v91
	v_and_b32_e32 v77, 0xffff0000, v91
	v_mul_f32_e32 v92, 0xbfb8aa3b, v76
	v_exp_f32_e32 v92, v92
	v_mul_f32_e32 v93, 0xbfb8aa3b, v77
	v_exp_f32_e32 v93, v93
	v_pk_mul_f32 v[156:157], v[62:63], v[62:63]
	v_add_f32_e32 v92, 1.0, v92
	v_rcp_f32_e32 v94, v92
	v_add_f32_e32 v92, 1.0, v93
	v_rcp_f32_e32 v95, v92
	s_waitcnt vmcnt(13)
	v_lshlrev_b32_e32 v92, 16, v99
	v_and_b32_e32 v93, 0xffff0000, v99
	v_mul_f32_e32 v100, 0xbfb8aa3b, v92
	v_exp_f32_e32 v100, v100
	v_mul_f32_e32 v101, 0xbfb8aa3b, v93
	v_exp_f32_e32 v101, v101
	v_pk_mul_f32 v[186:187], v[32:33], v[32:33]
	v_add_f32_e32 v100, 1.0, v100
	v_rcp_f32_e32 v102, v100
	v_add_f32_e32 v100, 1.0, v101
	v_rcp_f32_e32 v103, v100
	v_pk_mul_f32 v[168:169], v[34:35], v[34:35]
	v_pk_mul_f32 v[202:203], v[36:37], v[36:37]
	v_pk_mul_f32 v[192:193], v[38:39], v[38:39]
	s_waitcnt vmcnt(12)
	v_lshlrev_b32_e32 v100, 16, v107
	v_and_b32_e32 v101, 0xffff0000, v107
	v_mul_f32_e32 v110, 0xbfb8aa3b, v100
	v_exp_f32_e32 v110, v110
	v_mul_f32_e32 v111, 0xbfb8aa3b, v101
	v_exp_f32_e32 v111, v111
	s_waitcnt vmcnt(10)
	v_lshlrev_b32_e32 v132, 16, v134
	v_add_f32_e32 v110, 1.0, v110
	v_rcp_f32_e32 v112, v110
	v_add_f32_e32 v110, 1.0, v111
	v_rcp_f32_e32 v113, v110
	v_lshlrev_b32_e32 v110, 16, v121
	v_and_b32_e32 v111, 0xffff0000, v121
	v_mul_f32_e32 v122, 0xbfb8aa3b, v110
	v_exp_f32_e32 v122, v122
	v_mul_f32_e32 v123, 0xbfb8aa3b, v111
	v_exp_f32_e32 v123, v123
	v_and_b32_e32 v133, 0xffff0000, v134
	v_add_f32_e32 v122, 1.0, v122
	v_mul_f32_e32 v129, 0xbfb8aa3b, v132
	v_rcp_f32_e32 v124, v122
	v_add_f32_e32 v122, 1.0, v123
	v_exp_f32_e32 v129, v129
	v_mul_f32_e32 v134, 0xbfb8aa3b, v133
	v_rcp_f32_e32 v125, v122
	v_lshlrev_b32_e32 v122, 16, v135
	v_and_b32_e32 v123, 0xffff0000, v135
	v_exp_f32_e32 v135, v134
	v_add_f32_e32 v129, 1.0, v129
	v_rcp_f32_e32 v134, v129
	s_waitcnt vmcnt(9)
	v_lshlrev_b32_e32 v144, 16, v146
	v_add_f32_e32 v129, 1.0, v135
	v_mul_f32_e32 v135, 0xbfb8aa3b, v122
	v_exp_f32_e32 v138, v135
	v_mul_f32_e32 v135, 0xbfb8aa3b, v123
	v_exp_f32_e32 v139, v135
	v_rcp_f32_e32 v135, v129
	v_add_f32_e32 v129, 1.0, v138
	v_rcp_f32_e32 v140, v129
	v_add_f32_e32 v129, 1.0, v139
	v_rcp_f32_e32 v141, v129
	v_pk_add_f32 v[42:43], v[42:43], v[128:129] op_sel_hi:[1,0] neg_lo:[0,1] neg_hi:[0,1]
	v_pk_add_f32 v[40:41], v[40:41], v[128:129] op_sel_hi:[1,0] neg_lo:[0,1] neg_hi:[0,1]
	v_and_b32_e32 v145, 0xffff0000, v146
	v_mul_f32_e32 v129, 0xbfb8aa3b, v144
	v_exp_f32_e32 v129, v129
	v_mul_f32_e32 v146, 0xbfb8aa3b, v145
	v_lshlrev_b32_e32 v138, 16, v147
	v_and_b32_e32 v139, 0xffff0000, v147
	v_exp_f32_e32 v147, v146
	v_add_f32_e32 v129, 1.0, v129
	v_rcp_f32_e32 v146, v129
	s_waitcnt vmcnt(8)
	v_lshlrev_b32_e32 v154, 16, v158
	v_add_f32_e32 v129, 1.0, v147
	v_mul_f32_e32 v147, 0xbfb8aa3b, v138
	v_exp_f32_e32 v150, v147
	v_mul_f32_e32 v147, 0xbfb8aa3b, v139
	v_exp_f32_e32 v151, v147
	v_rcp_f32_e32 v147, v129
	v_add_f32_e32 v129, 1.0, v150
	v_rcp_f32_e32 v152, v129
	v_add_f32_e32 v129, 1.0, v151
	v_rcp_f32_e32 v153, v129
	v_pk_add_f32 v[46:47], v[46:47], v[128:129] op_sel_hi:[1,0] neg_lo:[0,1] neg_hi:[0,1]
	v_pk_add_f32 v[44:45], v[44:45], v[128:129] op_sel_hi:[1,0] neg_lo:[0,1] neg_hi:[0,1]
	v_and_b32_e32 v155, 0xffff0000, v158
	v_mul_f32_e32 v129, 0xbfb8aa3b, v154
	v_exp_f32_e32 v129, v129
	v_mul_f32_e32 v158, 0xbfb8aa3b, v155
	v_lshlrev_b32_e32 v150, 16, v159
	v_and_b32_e32 v151, 0xffff0000, v159
	v_exp_f32_e32 v159, v158
	v_add_f32_e32 v129, 1.0, v129
	v_rcp_f32_e32 v158, v129
	s_waitcnt vmcnt(7)
	v_lshlrev_b32_e32 v166, 16, v170
	v_add_f32_e32 v129, 1.0, v159
	v_mul_f32_e32 v159, 0xbfb8aa3b, v150
	v_exp_f32_e32 v160, v159
	v_mul_f32_e32 v159, 0xbfb8aa3b, v151
	v_exp_f32_e32 v161, v159
	v_rcp_f32_e32 v159, v129
	v_add_f32_e32 v129, 1.0, v160
	v_rcp_f32_e32 v162, v129
	v_add_f32_e32 v129, 1.0, v161
	v_rcp_f32_e32 v163, v129
	v_pk_add_f32 v[18:19], v[18:19], v[128:129] op_sel_hi:[1,0] neg_lo:[0,1] neg_hi:[0,1]
	v_pk_add_f32 v[16:17], v[16:17], v[128:129] op_sel_hi:[1,0] neg_lo:[0,1] neg_hi:[0,1]
	v_and_b32_e32 v167, 0xffff0000, v170
	v_mul_f32_e32 v129, 0xbfb8aa3b, v166
	v_exp_f32_e32 v129, v129
	v_mul_f32_e32 v170, 0xbfb8aa3b, v167
	v_lshlrev_b32_e32 v160, 16, v171
	v_and_b32_e32 v161, 0xffff0000, v171
	v_exp_f32_e32 v171, v170
	v_add_f32_e32 v129, 1.0, v129
	v_rcp_f32_e32 v170, v129
	s_waitcnt vmcnt(6)
	v_lshlrev_b32_e32 v188, 16, v190
	v_add_f32_e32 v129, 1.0, v171
	v_mul_f32_e32 v171, 0xbfb8aa3b, v160
	v_exp_f32_e32 v172, v171
	v_mul_f32_e32 v171, 0xbfb8aa3b, v161
	v_exp_f32_e32 v173, v171
	v_rcp_f32_e32 v171, v129
	v_add_f32_e32 v129, 1.0, v172
	v_rcp_f32_e32 v184, v129
	v_add_f32_e32 v129, 1.0, v173
	v_rcp_f32_e32 v185, v129
	v_pk_add_f32 v[22:23], v[22:23], v[128:129] op_sel_hi:[1,0] neg_lo:[0,1] neg_hi:[0,1]
	v_pk_add_f32 v[20:21], v[20:21], v[128:129] op_sel_hi:[1,0] neg_lo:[0,1] neg_hi:[0,1]
	v_and_b32_e32 v189, 0xffff0000, v190
	v_mul_f32_e32 v129, 0xbfb8aa3b, v188
	v_exp_f32_e32 v129, v129
	v_mul_f32_e32 v176, 0xbfb8aa3b, v189
	v_exp_f32_e32 v176, v176
	v_lshlrev_b32_e32 v172, 16, v191
	v_add_f32_e32 v129, 1.0, v129
	v_and_b32_e32 v173, 0xffff0000, v191
	v_rcp_f32_e32 v190, v129
	v_add_f32_e32 v129, 1.0, v176
	v_mul_f32_e32 v176, 0xbfb8aa3b, v172
	v_exp_f32_e32 v176, v176
	v_mul_f32_e32 v180, 0xbfb8aa3b, v173
	v_exp_f32_e32 v180, v180
	v_rcp_f32_e32 v191, v129
	v_add_f32_e32 v129, 1.0, v176
	v_rcp_f32_e32 v196, v129
	v_add_f32_e32 v129, 1.0, v180
	s_waitcnt vmcnt(5)
; __device__ __forceinline__ unsigned cvt_pk(float lo, float hi) { f32x2_t v = {lo, hi}; bf16x2_t b = __builtin_convertvector(v, bf16x2_t); return __builtin_bit_cast(unsigned, b); }
; __device__ __forceinline__ float bflo(unsigned w) { return __uint_as_float(w << 16); }
; __device__ __forceinline__ float bfhi(unsigned w) { return __uint_as_float(w & 0xffff0000u); }
; __device__ __forceinline__ float sigmoidf_(float x) { return fast_rcp(1.f + fast_exp2(-x * LOG2E)); }
; template <int MODE>
; __device__ __forceinline__ void flash_unit(ArgsP A, int l, int b, int h, int qb, unsigned char* lds) {
;     ...
;         const float mu = s * (1.f / 128); float v = 0.f;
; #pragma unroll
;         for (int c = 0; c < 4; ++c)
; #pragma unroll
;             for (int i = 0; i < 16; ++i) { const float d = oacc[c][i] - mu; oacc[c][i] = d; v += d * d; }
;         v += __shfl_xor(v, 32);
;         const float r = 1.f / sqrtf(v * (1.f / 128) + 1e-5f);
;         bf16_t* op = MIX + (size_t)qrow * DM + 1024 + 128 * h; const bf16_t* gp = PROJ + (size_t)qrow * INWP + C_RG + 128 * h;
;         u32x2 gwv[4][4];
; #pragma unroll
;         for (int c = 0; c < 4; ++c)
; #pragma unroll
;             for (int g4 = 0; g4 < 4; ++g4) gwv[c][g4] = *(const u32x2*)(gp + 32 * c + 8 * g4 + 4 * hh);
; #pragma unroll
;         for (int c = 0; c < 4; ++c)
; #pragma unroll
;             for (int g4 = 0; g4 < 4; ++g4) { const int d = 32 * c + 8 * g4 + 4 * hh; const u32x2 gw = gwv[c][g4];
;                 const float g0 = bflo(gw.x), g1 = bfhi(gw.x), g2 = bflo(gw.y), g3 = bfhi(gw.y);
;                 u32x2 w; w.x = cvt_pk(oacc[c][4 * g4] * r * g0 * sigmoidf_(g0), oacc[c][4 * g4 + 1] * r * g1 * sigmoidf_(g1));
	v_lshlrev_b32_e32 v198, 16, v200
	v_rcp_f32_e32 v197, v129
	v_pk_add_f32 v[26:27], v[26:27], v[128:129] op_sel_hi:[1,0] neg_lo:[0,1] neg_hi:[0,1]
	v_pk_add_f32 v[24:25], v[24:25], v[128:129] op_sel_hi:[1,0] neg_lo:[0,1] neg_hi:[0,1]
	v_and_b32_e32 v199, 0xffff0000, v200
	v_mul_f32_e32 v129, 0xbfb8aa3b, v198
	v_exp_f32_e32 v129, v129
	v_mul_f32_e32 v176, 0xbfb8aa3b, v199
	v_exp_f32_e32 v176, v176
	v_lshlrev_b32_e32 v194, 16, v201
	v_add_f32_e32 v129, 1.0, v129
	v_and_b32_e32 v195, 0xffff0000, v201
	v_rcp_f32_e32 v200, v129
	v_add_f32_e32 v129, 1.0, v176
	v_mul_f32_e32 v176, 0xbfb8aa3b, v194
	v_exp_f32_e32 v176, v176
	v_mul_f32_e32 v180, 0xbfb8aa3b, v195
	v_exp_f32_e32 v180, v180
	v_rcp_f32_e32 v201, v129
	v_add_f32_e32 v129, 1.0, v176
	v_rcp_f32_e32 v204, v129
	v_add_f32_e32 v129, 1.0, v180
	s_waitcnt vmcnt(4)
	v_lshlrev_b32_e32 v210, 16, v174
	v_rcp_f32_e32 v205, v129
	v_pk_add_f32 v[30:31], v[30:31], v[128:129] op_sel_hi:[1,0] neg_lo:[0,1] neg_hi:[0,1]
	v_pk_add_f32 v[208:209], v[28:29], v[128:129] op_sel_hi:[1,0] neg_lo:[0,1] neg_hi:[0,1]
	v_and_b32_e32 v211, 0xffff0000, v174
	v_mul_f32_e32 v129, 0xbfb8aa3b, v210
	v_exp_f32_e32 v129, v129
	v_mul_f32_e32 v174, 0xbfb8aa3b, v211
	v_lshlrev_b32_e32 v28, 16, v175
	v_and_b32_e32 v29, 0xffff0000, v175
	v_exp_f32_e32 v175, v174
	v_pk_add_f32 v[2:3], v[2:3], v[128:129] op_sel_hi:[1,0] neg_lo:[0,1] neg_hi:[0,1]
	v_pk_add_f32 v[0:1], v[0:1], v[128:129] op_sel_hi:[1,0] neg_lo:[0,1] neg_hi:[0,1]
	v_pk_add_f32 v[6:7], v[6:7], v[128:129] op_sel_hi:[1,0] neg_lo:[0,1] neg_hi:[0,1]
	v_pk_add_f32 v[4:5], v[4:5], v[128:129] op_sel_hi:[1,0] neg_lo:[0,1] neg_hi:[0,1]
	v_pk_add_f32 v[8:9], v[8:9], v[128:129] op_sel_hi:[1,0] neg_lo:[0,1] neg_hi:[0,1]
	v_add_f32_e32 v128, 1.0, v129
	v_mul_f32_e32 v129, 0xbfb8aa3b, v28
	v_rcp_f32_e32 v174, v128
	v_add_f32_e32 v128, 1.0, v175
	v_exp_f32_e32 v129, v129
	v_mul_f32_e32 v175, 0xbfb8aa3b, v29
	v_exp_f32_e32 v176, v175
	v_rcp_f32_e32 v175, v128
	v_add_f32_e32 v128, 1.0, v129
	v_rcp_f32_e32 v226, v128
	v_add_f32_e32 v128, 1.0, v176
	s_waitcnt vmcnt(3)
	v_and_b32_e32 v225, 0xffff0000, v130
	v_rcp_f32_e32 v227, v128
	v_lshlrev_b32_e32 v128, 16, v131
	v_and_b32_e32 v129, 0xffff0000, v131
	v_mul_f32_e32 v131, 0xbfb8aa3b, v225
	v_exp_f32_e32 v131, v131
	s_waitcnt vmcnt(2)
	v_lshlrev_b32_e32 v230, 16, v114
	v_pk_mul_f32 v[212:213], v[40:41], v[40:41]
	v_pk_mul_f32 v[206:207], v[42:43], v[42:43]
	v_add_f32_e32 v176, 1.0, v131
	v_rcp_f32_e32 v229, v176
	v_add_f32_e32 v176, v118, v119
	v_add_f32_e32 v108, v108, v176
	v_add_f32_e32 v108, v109, v108
	v_mul_f32_e32 v109, 0xbfb8aa3b, v230
	v_exp_f32_e32 v109, v109
	v_add_f32_e32 v108, v136, v108
	v_add_f32_e32 v176, v137, v108
	v_pk_mul_f32 v[216:217], v[44:45], v[44:45]
	v_add_f32_e32 v108, 1.0, v109
	v_add_f32_e32 v109, v126, v176
	v_add_f32_e32 v109, v127, v109
	v_add_f32_e32 v109, v148, v109
	v_add_f32_e32 v109, v149, v109
	v_add_f32_e32 v109, v80, v109
	v_add_f32_e32 v109, v81, v109
	v_add_f32_e32 v109, v164, v109
	v_add_f32_e32 v109, v165, v109
	v_add_f32_e32 v109, v156, v109
	v_add_f32_e32 v109, v157, v109
	v_add_f32_e32 v109, v186, v109
	v_add_f32_e32 v109, v187, v109
	v_add_f32_e32 v109, v168, v109
	v_add_f32_e32 v109, v169, v109
	v_add_f32_e32 v109, v202, v109
	v_add_f32_e32 v109, v203, v109
	v_add_f32_e32 v109, v192, v109
	v_add_f32_e32 v109, v193, v109
	v_add_f32_e32 v109, v212, v109
	v_add_f32_e32 v109, v213, v109
	v_add_f32_e32 v109, v206, v109
	v_add_f32_e32 v109, v207, v109
	v_add_f32_e32 v109, v216, v109
	v_pk_mul_f32 v[214:215], v[46:47], v[46:47]
	v_add_f32_e32 v109, v217, v109
	v_add_f32_e32 v109, v214, v109
	v_pk_mul_f32 v[220:221], v[16:17], v[16:17]
	v_add_f32_e32 v109, v215, v109
	v_add_f32_e32 v109, v220, v109
	v_pk_mul_f32 v[218:219], v[18:19], v[18:19]
	v_add_f32_e32 v109, v221, v109
	v_add_f32_e32 v109, v218, v109
	v_pk_mul_f32 v[250:251], v[20:21], v[20:21]
	v_add_f32_e32 v109, v219, v109
	v_add_f32_e32 v109, v250, v109
	v_pk_mul_f32 v[222:223], v[22:23], v[22:23]
	v_add_f32_e32 v109, v251, v109
	v_add_f32_e32 v109, v222, v109
	v_pk_mul_f32 v[246:247], v[24:25], v[24:25]
	v_add_f32_e32 v109, v223, v109
	v_add_f32_e32 v109, v246, v109
	v_pk_mul_f32 v[248:249], v[26:27], v[26:27]
	v_add_f32_e32 v109, v247, v109
	v_add_f32_e32 v109, v248, v109
	v_pk_mul_f32 v[180:181], v[208:209], v[208:209]
	v_add_f32_e32 v109, v249, v109
	v_add_f32_e32 v109, v180, v109
	v_pk_mul_f32 v[10:11], v[30:31], v[30:31]
	v_add_f32_e32 v109, v181, v109
	v_add_f32_e32 v109, v10, v109
	v_pk_mul_f32 v[178:179], v[0:1], v[0:1]
	v_add_f32_e32 v109, v11, v109
	v_add_f32_e32 v109, v178, v109
	v_pk_mul_f32 v[182:183], v[2:3], v[2:3]
	v_add_f32_e32 v109, v179, v109
	v_add_f32_e32 v109, v182, v109
	v_pk_mul_f32 v[136:137], v[4:5], v[4:5]
	v_add_f32_e32 v109, v183, v109
	v_add_f32_e32 v109, v136, v109
	v_and_b32_e32 v231, 0xffff0000, v114
	v_pk_mul_f32 v[118:119], v[6:7], v[6:7]
	v_add_f32_e32 v109, v137, v109
	v_mul_f32_e32 v126, 0xbfb8aa3b, v231
	v_add_f32_e32 v109, v118, v109
	v_exp_f32_e32 v176, v126
	v_pk_mul_f32 v[126:127], v[8:9], v[8:9]
	v_add_f32_e32 v109, v119, v109
	v_add_f32_e32 v109, v126, v109
	v_add_f32_e32 v109, v127, v109
	v_pk_mul_f32 v[10:11], v[64:65], v[64:65]
	v_pk_mul_f32 v[82:83], v[12:13], v[12:13]
	v_add_f32_e32 v80, v10, v109
	v_add_f32_e32 v80, v11, v80
	v_add_f32_e32 v80, v82, v80
	v_pk_mul_f32 v[84:85], v[142:143], v[142:143]
	v_add_f32_e32 v80, v83, v80
	v_add_f32_e32 v80, v84, v80
	v_add_f32_e32 v80, v85, v80
	ds_bpermute_b32 v81, v243, v80
	s_mov_b64 s[2:3], 0x24f90800
	v_rcp_f32_e32 v87, v48
	v_lshl_add_u64 v[48:49], v[78:79], 0, s[2:3]
	v_lshlrev_b32_e32 v224, 16, v130
	s_waitcnt lgkmcnt(0)
; __device__ __forceinline__ unsigned cvt_pk(float lo, float hi) { f32x2_t v = {lo, hi}; bf16x2_t b = __builtin_convertvector(v, bf16x2_t); return __builtin_bit_cast(unsigned, b); }
; __device__ __forceinline__ float bflo(unsigned w) { return __uint_as_float(w << 16); }
; __device__ __forceinline__ float bfhi(unsigned w) { return __uint_as_float(w & 0xffff0000u); }
; __device__ __forceinline__ float sigmoidf_(float x) { return fast_rcp(1.f + fast_exp2(-x * LOG2E)); }
; template <int MODE>
; __device__ __forceinline__ void flash_unit(ArgsP A, int l, int b, int h, int qb, unsigned char* lds) {
;     ...
;         v += __shfl_xor(v, 32);
;         const float r = 1.f / sqrtf(v * (1.f / 128) + 1e-5f);
;         bf16_t* op = MIX + (size_t)qrow * DM + 1024 + 128 * h; const bf16_t* gp = PROJ + (size_t)qrow * INWP + C_RG + 128 * h;
;         u32x2 gwv[4][4];
; #pragma unroll
;         for (int c = 0; c < 4; ++c)
; #pragma unroll
;             for (int g4 = 0; g4 < 4; ++g4) gwv[c][g4] = *(const u32x2*)(gp + 32 * c + 8 * g4 + 4 * hh);
; #pragma unroll
;         for (int c = 0; c < 4; ++c)
; #pragma unroll
;             for (int g4 = 0; g4 < 4; ++g4) { const int d = 32 * c + 8 * g4 + 4 * hh; const u32x2 gw = gwv[c][g4];
;                 const float g0 = bflo(gw.x), g1 = bfhi(gw.x), g2 = bflo(gw.y), g3 = bfhi(gw.y);
;                 u32x2 w; w.x = cvt_pk(oacc[c][4 * g4] * r * g0 * sigmoidf_(g0), oacc[c][4 * g4 + 1] * r * g1 * sigmoidf_(g1));
;                 w.y = cvt_pk(oacc[c][4 * g4 + 2] * r * g2 * sigmoidf_(g2), oacc[c][4 * g4 + 3] * r * g3 * sigmoidf_(g3));
;                 *(u32x2*)(op + d) = w; }
	v_add_f32_e32 v80, v80, v81
	v_fmamk_f32 v80, v80, 0x3c000000, v236
	v_mul_f32_e32 v81, 0x4f800000, v80
	v_cmp_gt_f32_e32 vcc, s77, v80
	v_mul_f32_e32 v130, 0xbfb8aa3b, v224
	v_exp_f32_e32 v130, v130
	v_cndmask_b32_e32 v80, v80, v81, vcc
	v_sqrt_f32_e32 v81, v80
	v_and_b32_e32 v131, 0xffff0000, v115
	v_add_f32_e32 v130, 1.0, v130
	v_rcp_f32_e32 v228, v130
	v_add_u32_e32 v84, -1, v81
	v_fma_f32 v85, -v84, v81, v80
	v_cmp_ge_f32_e64 s[2:3], 0, v85
	v_add_u32_e32 v85, 1, v81
	v_lshlrev_b32_e32 v130, 16, v115
	v_cndmask_b32_e64 v84, v81, v84, s[2:3]
	v_fma_f32 v81, -v85, v81, v80
	v_cmp_lt_f32_e64 s[2:3], 0, v81
	v_mul_f32_e32 v114, 0xbfb8aa3b, v128
	v_mul_f32_e32 v115, 0xbfb8aa3b, v129
	v_cndmask_b32_e64 v81, v84, v85, s[2:3]
	v_mul_f32_e32 v84, 0x37800000, v81
	v_cndmask_b32_e32 v81, v81, v84, vcc
	v_cmp_class_f32_e32 vcc, v80, v240
	v_exp_f32_e32 v114, v114
	v_exp_f32_e32 v115, v115
	v_cndmask_b32_e32 v80, v81, v80, vcc
	v_div_scale_f32 v81, s[2:3], v80, v80, 1.0
	v_rcp_f32_e32 v84, v81
	v_add_f32_e32 v82, 1.0, v176
	v_add_f32_e32 v114, 1.0, v114
	v_add_f32_e32 v115, 1.0, v115
	v_fma_f32 v85, -v81, v84, 1.0
	v_fmac_f32_e32 v84, v85, v84
	v_div_scale_f32 v85, vcc, 1.0, v80, 1.0
	v_mul_f32_e32 v118, v85, v84
	v_fma_f32 v119, -v81, v118, v85
	v_fmac_f32_e32 v118, v119, v84
	v_rcp_f32_e32 v109, v82
	v_mul_f32_e32 v82, 0xbfb8aa3b, v130
	v_mul_f32_e32 v83, 0xbfb8aa3b, v131
	v_fma_f32 v81, -v81, v118, v85
	v_rcp_f32_e32 v114, v114
	v_rcp_f32_e32 v115, v115
	v_exp_f32_e32 v82, v82
	v_exp_f32_e32 v83, v83
	v_div_fmas_f32 v81, v81, v84, v118
	v_div_fixup_f32 v80, v81, v80, 1.0
	v_pk_mul_f32 v[0:1], v[0:1], v[80:81] op_sel_hi:[1,0]
	v_pk_mul_f32 v[2:3], v[2:3], v[80:81] op_sel_hi:[1,0]
	v_pk_mul_f32 v[0:1], v[0:1], v[224:225]
	v_pk_mul_f32 v[2:3], v[2:3], v[128:129]
	v_rcp_f32_e32 v108, v108
	v_add_f32_e32 v82, 1.0, v82
	v_add_f32_e32 v83, 1.0, v83
	v_pk_mul_f32 v[0:1], v[228:229], v[0:1]
	v_pk_mul_f32 v[2:3], v[114:115], v[2:3]
	v_rcp_f32_e32 v82, v82
	v_rcp_f32_e32 v83, v83
	v_cvt_pk_bf16_f32 v0, v0, v1
	v_cvt_pk_bf16_f32 v1, v2, v3
	global_store_dwordx2 v[48:49], v[0:1], off offset:192
	v_pk_mul_f32 v[0:1], v[4:5], v[80:81] op_sel_hi:[1,0]
	v_pk_mul_f32 v[2:3], v[6:7], v[80:81] op_sel_hi:[1,0]
	v_pk_mul_f32 v[0:1], v[0:1], v[230:231]
	v_pk_mul_f32 v[2:3], v[2:3], v[130:131]
	v_pk_mul_f32 v[0:1], v[108:109], v[0:1]
	s_waitcnt vmcnt(2)
	v_lshlrev_b32_e32 v4, 16, v66
	v_cvt_pk_bf16_f32 v0, v0, v1
	v_pk_mul_f32 v[2:3], v[82:83], v[2:3]
	v_mul_f32_e32 v1, 0xbfb8aa3b, v4
	v_exp_f32_e32 v6, v1
	v_cvt_pk_bf16_f32 v1, v2, v3
	v_and_b32_e32 v5, 0xffff0000, v66
	global_store_dwordx2 v[48:49], v[0:1], off offset:208
	v_mul_f32_e32 v1, 0xbfb8aa3b, v5
	v_exp_f32_e32 v1, v1
	v_pk_mul_f32 v[2:3], v[8:9], v[80:81] op_sel_hi:[1,0]
	v_add_f32_e32 v0, 1.0, v6
	v_pk_mul_f32 v[2:3], v[2:3], v[4:5]
	v_lshlrev_b32_e32 v4, 16, v67
	v_and_b32_e32 v5, 0xffff0000, v67
	v_add_f32_e32 v1, 1.0, v1
	v_mul_f32_e32 v6, 0xbfb8aa3b, v4
	v_mul_f32_e32 v7, 0xbfb8aa3b, v5
	v_rcp_f32_e32 v0, v0
	v_rcp_f32_e32 v1, v1
	v_exp_f32_e32 v6, v6
	v_exp_f32_e32 v7, v7
	v_lshlrev_b32_e32 v116, 16, v120
	v_and_b32_e32 v117, 0xffff0000, v120
	v_pk_mul_f32 v[0:1], v[0:1], v[2:3]
	v_add_f32_e32 v2, 1.0, v6
	v_add_f32_e32 v3, 1.0, v7
	v_mul_f32_e32 v120, 0xbfb8aa3b, v116
	v_mul_f32_e32 v121, 0xbfb8aa3b, v117
	v_rcp_f32_e32 v2, v2
	v_rcp_f32_e32 v3, v3
	v_exp_f32_e32 v120, v120
	v_exp_f32_e32 v121, v121
	v_pk_mul_f32 v[6:7], v[64:65], v[80:81] op_sel_hi:[1,0]
	v_lshlrev_b32_e32 v88, 16, v90
	v_and_b32_e32 v89, 0xffff0000, v90
	v_pk_mul_f32 v[4:5], v[6:7], v[4:5]
	v_mul_f32_e32 v90, 0xbfb8aa3b, v88
	v_mul_f32_e32 v91, 0xbfb8aa3b, v89
	v_pk_mul_f32 v[2:3], v[2:3], v[4:5]
	s_waitcnt vmcnt(2)
	v_lshlrev_b32_e32 v4, 16, v14
	v_exp_f32_e32 v90, v90
	v_exp_f32_e32 v91, v91
	v_add_f32_e32 v120, 1.0, v120
	v_add_f32_e32 v121, 1.0, v121
	v_cvt_pk_bf16_f32 v0, v0, v1
	v_mul_f32_e32 v1, 0xbfb8aa3b, v4
	v_rcp_f32_e32 v120, v120
	v_rcp_f32_e32 v121, v121
	v_exp_f32_e32 v6, v1
	v_cvt_pk_bf16_f32 v1, v2, v3
	v_and_b32_e32 v5, 0xffff0000, v14
	v_lshlrev_b32_e32 v96, 16, v98
	v_and_b32_e32 v97, 0xffff0000, v98
	v_pk_mul_f32 v[70:71], v[70:71], v[80:81] op_sel_hi:[1,0]
	v_pk_mul_f32 v[50:51], v[50:51], v[80:81] op_sel_hi:[1,0]
	global_store_dwordx2 v[48:49], v[0:1], off offset:224
	v_mul_f32_e32 v1, 0xbfb8aa3b, v5
	v_mul_f32_e32 v98, 0xbfb8aa3b, v96
	v_mul_f32_e32 v99, 0xbfb8aa3b, v97
	v_pk_mul_f32 v[70:71], v[70:71], v[72:73]
	v_pk_mul_f32 v[50:51], v[50:51], v[68:69]
	v_pk_mul_f32 v[32:33], v[32:33], v[80:81] op_sel_hi:[1,0]
	v_pk_mul_f32 v[34:35], v[34:35], v[80:81] op_sel_hi:[1,0]
	v_pk_mul_f32 v[16:17], v[16:17], v[80:81] op_sel_hi:[1,0]
	v_pk_mul_f32 v[18:19], v[18:19], v[80:81] op_sel_hi:[1,0]
	v_exp_f32_e32 v1, v1
	v_add_f32_e32 v90, 1.0, v90
	v_add_f32_e32 v91, 1.0, v91
	v_exp_f32_e32 v98, v98
	v_exp_f32_e32 v99, v99
	v_pk_mul_f32 v[70:71], v[74:75], v[70:71]
	v_pk_mul_f32 v[50:51], v[86:87], v[50:51]
	s_mov_b32 s2, 0x24f90000
	v_pk_mul_f32 v[32:33], v[32:33], v[116:117]
	v_pk_mul_f32 v[34:35], v[34:35], v[110:111]
	v_pk_mul_f32 v[16:17], v[16:17], v[166:167]
	v_pk_mul_f32 v[18:19], v[18:19], v[160:161]
	v_rcp_f32_e32 v90, v90
	v_rcp_f32_e32 v91, v91
	v_cvt_pk_bf16_f32 v70, v70, v71
	v_cvt_pk_bf16_f32 v71, v50, v51
	v_add_co_u32_e32 v50, vcc, s2, v78
	v_pk_mul_f32 v[32:33], v[120:121], v[32:33]
	v_pk_mul_f32 v[34:35], v[124:125], v[34:35]
	v_pk_mul_f32 v[16:17], v[170:171], v[16:17]
; __device__ __forceinline__ unsigned cvt_pk(float lo, float hi) { f32x2_t v = {lo, hi}; bf16x2_t b = __builtin_convertvector(v, bf16x2_t); return __builtin_bit_cast(unsigned, b); }
; __device__ __forceinline__ float bflo(unsigned w) { return __uint_as_float(w << 16); }
; __device__ __forceinline__ float bfhi(unsigned w) { return __uint_as_float(w & 0xffff0000u); }
; __device__ __forceinline__ float sigmoidf_(float x) { return fast_rcp(1.f + fast_exp2(-x * LOG2E)); }
; template <int MODE>
; __device__ __forceinline__ void flash_unit(ArgsP A, int l, int b, int h, int qb, unsigned char* lds) {
;     ...
; #pragma unroll
;         for (int c = 0; c < 4; ++c)
; #pragma unroll
;             for (int g4 = 0; g4 < 4; ++g4) { const int d = 32 * c + 8 * g4 + 4 * hh; const u32x2 gw = gwv[c][g4];
;                 const float g0 = bflo(gw.x), g1 = bfhi(gw.x), g2 = bflo(gw.y), g3 = bfhi(gw.y);
;                 u32x2 w; w.x = cvt_pk(oacc[c][4 * g4] * r * g0 * sigmoidf_(g0), oacc[c][4 * g4 + 1] * r * g1 * sigmoidf_(g1));
;                 w.y = cvt_pk(oacc[c][4 * g4 + 2] * r * g2 * sigmoidf_(g2), oacc[c][4 * g4 + 3] * r * g3 * sigmoidf_(g3));
;                 *(u32x2*)(op + d) = w; }
	v_pk_mul_f32 v[18:19], v[184:185], v[18:19]
	v_pk_mul_f32 v[2:3], v[12:13], v[80:81] op_sel_hi:[1,0]
	v_lshlrev_b32_e32 v104, 16, v106
	v_and_b32_e32 v105, 0xffff0000, v106
	v_addc_co_u32_e32 v51, vcc, 0, v79, vcc
	v_cvt_pk_bf16_f32 v32, v32, v33
	v_cvt_pk_bf16_f32 v33, v34, v35
	v_cvt_pk_bf16_f32 v16, v16, v17
	v_cvt_pk_bf16_f32 v17, v18, v19
	v_pk_mul_f32 v[2:3], v[2:3], v[4:5]
	v_lshlrev_b32_e32 v4, 16, v15
	v_and_b32_e32 v5, 0xffff0000, v15
	v_mul_f32_e32 v106, 0xbfb8aa3b, v104
	v_mul_f32_e32 v107, 0xbfb8aa3b, v105
	global_store_dwordx2 v[50:51], v[70:71], off offset:2048
	v_pk_mul_f32 v[50:51], v[52:53], v[80:81] op_sel_hi:[1,0]
	v_pk_mul_f32 v[52:53], v[54:55], v[80:81] op_sel_hi:[1,0]
	global_store_dwordx2 v[48:49], v[32:33], off offset:64
	v_pk_mul_f32 v[32:33], v[36:37], v[80:81] op_sel_hi:[1,0]
	v_pk_mul_f32 v[34:35], v[38:39], v[80:81] op_sel_hi:[1,0]
	global_store_dwordx2 v[48:49], v[16:17], off offset:128
	v_pk_mul_f32 v[16:17], v[20:21], v[80:81] op_sel_hi:[1,0]
	v_pk_mul_f32 v[18:19], v[22:23], v[80:81] op_sel_hi:[1,0]
	v_add_f32_e32 v0, 1.0, v6
	v_add_f32_e32 v1, 1.0, v1
	v_mul_f32_e32 v6, 0xbfb8aa3b, v4
	v_mul_f32_e32 v7, 0xbfb8aa3b, v5
	v_add_f32_e32 v98, 1.0, v98
	v_add_f32_e32 v99, 1.0, v99
	v_exp_f32_e32 v106, v106
	v_exp_f32_e32 v107, v107
	v_pk_mul_f32 v[50:51], v[50:51], v[88:89]
	v_pk_mul_f32 v[52:53], v[52:53], v[76:77]
	v_pk_mul_f32 v[32:33], v[32:33], v[132:133]
	v_pk_mul_f32 v[34:35], v[34:35], v[122:123]
	v_pk_mul_f32 v[16:17], v[16:17], v[188:189]
	v_pk_mul_f32 v[18:19], v[18:19], v[172:173]
	v_rcp_f32_e32 v0, v0
	v_rcp_f32_e32 v1, v1
	v_exp_f32_e32 v6, v6
	v_exp_f32_e32 v7, v7
	v_rcp_f32_e32 v98, v98
	v_rcp_f32_e32 v99, v99
	v_pk_mul_f32 v[50:51], v[90:91], v[50:51]
	v_pk_mul_f32 v[52:53], v[94:95], v[52:53]
	v_pk_mul_f32 v[32:33], v[134:135], v[32:33]
	v_pk_mul_f32 v[34:35], v[140:141], v[34:35]
	v_pk_mul_f32 v[16:17], v[190:191], v[16:17]
	v_pk_mul_f32 v[18:19], v[196:197], v[18:19]
	v_cvt_pk_bf16_f32 v50, v50, v51
	v_cvt_pk_bf16_f32 v51, v52, v53
	v_cvt_pk_bf16_f32 v32, v32, v33
	v_cvt_pk_bf16_f32 v33, v34, v35
	v_cvt_pk_bf16_f32 v16, v16, v17
	v_cvt_pk_bf16_f32 v17, v18, v19
	global_store_dwordx2 v[48:49], v[50:51], off offset:16
	v_pk_mul_f32 v[50:51], v[56:57], v[80:81] op_sel_hi:[1,0]
	v_pk_mul_f32 v[52:53], v[58:59], v[80:81] op_sel_hi:[1,0]
	global_store_dwordx2 v[48:49], v[32:33], off offset:80
	v_pk_mul_f32 v[32:33], v[40:41], v[80:81] op_sel_hi:[1,0]
	v_pk_mul_f32 v[34:35], v[42:43], v[80:81] op_sel_hi:[1,0]
	global_store_dwordx2 v[48:49], v[16:17], off offset:144
	v_pk_mul_f32 v[16:17], v[24:25], v[80:81] op_sel_hi:[1,0]
	v_pk_mul_f32 v[18:19], v[26:27], v[80:81] op_sel_hi:[1,0]
	v_add_f32_e32 v106, 1.0, v106
	v_add_f32_e32 v107, 1.0, v107
	v_pk_mul_f32 v[50:51], v[50:51], v[96:97]
	v_pk_mul_f32 v[52:53], v[52:53], v[92:93]
	v_pk_mul_f32 v[32:33], v[32:33], v[144:145]
	v_pk_mul_f32 v[34:35], v[34:35], v[138:139]
	v_pk_mul_f32 v[16:17], v[16:17], v[198:199]
	v_pk_mul_f32 v[18:19], v[18:19], v[194:195]
	v_pk_mul_f32 v[0:1], v[0:1], v[2:3]
	v_add_f32_e32 v2, 1.0, v6
	v_add_f32_e32 v3, 1.0, v7
	v_rcp_f32_e32 v106, v106
	v_rcp_f32_e32 v107, v107
	v_pk_mul_f32 v[50:51], v[98:99], v[50:51]
	v_pk_mul_f32 v[52:53], v[102:103], v[52:53]
	v_pk_mul_f32 v[32:33], v[146:147], v[32:33]
	v_pk_mul_f32 v[34:35], v[152:153], v[34:35]
	v_pk_mul_f32 v[16:17], v[200:201], v[16:17]
	v_pk_mul_f32 v[18:19], v[204:205], v[18:19]
	v_rcp_f32_e32 v2, v2
	v_rcp_f32_e32 v3, v3
	v_cvt_pk_bf16_f32 v50, v50, v51
	v_cvt_pk_bf16_f32 v51, v52, v53
	v_cvt_pk_bf16_f32 v32, v32, v33
	v_cvt_pk_bf16_f32 v33, v34, v35
	v_cvt_pk_bf16_f32 v16, v16, v17
	v_cvt_pk_bf16_f32 v17, v18, v19
	global_store_dwordx2 v[48:49], v[50:51], off offset:32
	v_pk_mul_f32 v[50:51], v[60:61], v[80:81] op_sel_hi:[1,0]
	v_pk_mul_f32 v[52:53], v[62:63], v[80:81] op_sel_hi:[1,0]
	global_store_dwordx2 v[48:49], v[32:33], off offset:96
	v_pk_mul_f32 v[32:33], v[44:45], v[80:81] op_sel_hi:[1,0]
	v_pk_mul_f32 v[34:35], v[46:47], v[80:81] op_sel_hi:[1,0]
	global_store_dwordx2 v[48:49], v[16:17], off offset:160
	v_pk_mul_f32 v[16:17], v[208:209], v[80:81] op_sel_hi:[1,0]
	v_pk_mul_f32 v[18:19], v[30:31], v[80:81] op_sel_hi:[1,0]
	v_pk_mul_f32 v[6:7], v[142:143], v[80:81] op_sel_hi:[1,0]
	v_pk_mul_f32 v[50:51], v[50:51], v[104:105]
	v_pk_mul_f32 v[52:53], v[52:53], v[100:101]
	v_pk_mul_f32 v[32:33], v[32:33], v[154:155]
	v_pk_mul_f32 v[34:35], v[34:35], v[150:151]
	v_pk_mul_f32 v[16:17], v[16:17], v[210:211]
	v_pk_mul_f32 v[18:19], v[18:19], v[28:29]
	v_pk_mul_f32 v[4:5], v[6:7], v[4:5]
	v_pk_mul_f32 v[50:51], v[106:107], v[50:51]
	v_pk_mul_f32 v[52:53], v[112:113], v[52:53]
	v_pk_mul_f32 v[32:33], v[158:159], v[32:33]
	v_pk_mul_f32 v[34:35], v[162:163], v[34:35]
	v_pk_mul_f32 v[16:17], v[174:175], v[16:17]
	v_pk_mul_f32 v[18:19], v[226:227], v[18:19]
	v_pk_mul_f32 v[2:3], v[2:3], v[4:5]
	v_mov_b32_e32 v179, v244
	v_cvt_pk_bf16_f32 v50, v50, v51
	v_cvt_pk_bf16_f32 v51, v52, v53
	v_cvt_pk_bf16_f32 v32, v32, v33
	v_cvt_pk_bf16_f32 v33, v34, v35
	v_cvt_pk_bf16_f32 v16, v16, v17
	v_cvt_pk_bf16_f32 v17, v18, v19
	v_cvt_pk_bf16_f32 v0, v0, v1
	v_cvt_pk_bf16_f32 v1, v2, v3
	s_mov_b64 s[2:3], -1
	global_store_dwordx2 v[48:49], v[50:51], off offset:48
	global_store_dwordx2 v[48:49], v[32:33], off offset:112
	global_store_dwordx2 v[48:49], v[16:17], off offset:176
	global_store_dwordx2 v[48:49], v[0:1], off offset:240

; #define QLOOP2(qi_, r2_, n_, ...) for (;;) { if (tid == 0) s_item = (int)atomicAdd(ctr + 64 * (qi_) + 32 * (r2_), 1u); __syncthreads(); const int item = s_item; __syncthreads(); if (item >= (n_)) break; __VA_ARGS__ }
; template <int PHM, int MIXM>
; __global__ void __launch_bounds__(512, 2) mega(Args Aval) {
;     ...
;             for (int r2 = 0; r2 < ((PROBE_DUP & 16) ? 2 : 1); ++r2) if (MIXM & 1) QLOOP2(0, r2, 256, { const int L = 15 - (item >> 4), r = item & 15; flash_unit<0>(A, l, r >> 2, r & 3, L, lds); })
;             for (int r2 = 0; r2 < ((PROBE_DUP & 32) ? 2 : 1); ++r2) if (MIXM & 2) QLOOP2(1, r2, 256, { const int L = 15 - (item >> 4), r = item & 15; flash_unit<2>(A, l, r >> 2, r & 3, L, lds); })
.LBB0_761:
	s_waitcnt lgkmcnt(0)
	s_barrier
	v_readlane_b32 s5, v255, 41
	s_mov_b64 s[2:3], -1
	s_sub_u32 s5, 0xff, s5
	v_readfirstlane_b32 s100, v238
	s_cmp_lt_u32 s100, 0x100
	s_cbranch_scc1 .Lprio_skip_ret
	s_setprio 1

; #define S5_LDS_FENCE() do { __builtin_amdgcn_wave_barrier(); asm volatile("s_waitcnt lgkmcnt(0)" ::: "memory"); } while (0)
; template <bool WRITEH>
; __device__ __forceinline__ void s5_block(const S5Coef& C, const bf16x8 (&bm)[8], u32x4 uw, float* Hs, int lane, float& hr, float& hi) {
;     const bf16x8 ua = __builtin_bit_cast(bf16x8, uw);
; #pragma unroll
;     for (int nb = 0; nb < 8; ++nb) { const f32x4 d = __builtin_amdgcn_mfma_f32_16x16x32_bf16(ua, bm[nb], (f32x4){0.f, 0.f, 0.f, 0.f}, 0, 0, 0);
; #pragma unroll
;         for (int i = 0; i < 4; ++i) Hs[(4 * (lane >> 4) + i) * 132 + 16 * nb + (lane & 15)] = d[i]; }
;     S5_LDS_FENCE();
;     float bur[16], bui[16];
; #pragma unroll
;     for (int tl = 0; tl < 16; ++tl) { bur[tl] = Hs[tl * 132 + lane]; bui[tl] = Hs[tl * 132 + 64 + lane]; }
; #pragma unroll
;     for (int tl = 0; tl < 16; ++tl) { const float nr = C.ar * hr - C.ai * hi + bur[tl], ni = C.ar * hi + C.ai * hr + bui[tl]; hr = nr; hi = ni; bur[tl] = hr; bui[tl] = hi; }
; __device__ __forceinline__ void s5_unit(ArgsP A, int l, int unit, unsigned char* lds, int wave_, int lane_) {
;     ...
;     for (int gi = 0; gi < 4; ++gi) {
;         const int g = 4 * wave + gi;
;         S5Coef C; bf16x8 bm[8]; s5_fetch(A, l, g, lane, C, bm);
;         bf16x8 chl[8];
;         { const bf16x8* ct = (const bf16x8*)(A->ws + WS_S5T + (size_t)(l * 32 + g) * S5T_BYTES + 9216);
; #pragma unroll
;           for (int q = 0; q < 8; ++q) chl[q] = ct[q * 64 + lane]; }
;         const f32x2_t hin = ((const f32x2_t*)(A->ws + WS_S5H))[(size_t)((b * 64 + c) * 32 + g) * 64 + lane]; float hr = hin.x, hi = hin.y;
;         u32x4 uw[4];
; #pragma unroll
;         for (int blk = 0; blk < 4; ++blk) uw[blk] = s5_load_ua(PROJ, rowbase + 16 * blk, g, lane);
;         const float dv = A->in[20][l * 512 + 16 * g + (lane & 15)];
; #pragma unroll
;         for (int blk = 0; blk < 4; ++blk) {
;             unsigned short uraw[4];
; #pragma unroll
;             for (int i = 0; i < 4; ++i) uraw[i] = PROJ[(size_t)(rowbase + 16 * blk + 4 * (lane >> 4) + i) * INWP + C_S5 + 16 * g + (lane & 15)];
;             s5_block<true>(C, bm, uw[blk], Hs, lane, hr, hi);
.LBB0_792:
	s_waitcnt lgkmcnt(0)
	v_lshl_add_u64 v[4:5], s[2:3], 0, v[98:99]
	v_add_co_u32_e32 v0, vcc, 0x2e7b0000, v4
	v_lshl_add_u64 v[66:67], s[2:3], 0, v[96:97]
	s_nop 0
	v_addc_co_u32_e32 v1, vcc, 0, v5, vcc
	global_load_dwordx4 v[32:35], v[0:1], off
	global_load_dwordx4 v[62:65], v[0:1], off offset:1024
	global_load_dwordx4 v[58:61], v[0:1], off offset:2048
	global_load_dwordx4 v[54:57], v[0:1], off offset:3072
	v_add_co_u32_e32 v0, vcc, 0x2e7b1000, v4
	v_ashrrev_i32_e32 v79, 31, v78
	s_nop 0
	v_addc_co_u32_e32 v1, vcc, 0, v5, vcc
	global_load_dwordx4 v[50:53], v[0:1], off
	global_load_dwordx4 v[46:49], v[0:1], off offset:1024
	global_load_dwordx4 v[42:45], v[0:1], off offset:2048
	global_load_dwordx4 v[38:41], v[0:1], off offset:3072
	v_add_co_u32_e32 v0, vcc, 0x2e7b2000, v4
	v_add_u32_e32 v115, 32, v112
	s_nop 0
	v_addc_co_u32_e32 v1, vcc, 0, v5, vcc
	global_load_dwordx4 v[34:37], v[0:1], off
	global_load_dwordx4 v[24:27], v[0:1], off offset:1024
	global_load_dwordx4 v[28:31], v[0:1], off offset:2048
	global_load_dwordx4 v[16:19], v[0:1], off offset:3072
	v_add_co_u32_e32 v0, vcc, 0x2e7b3000, v4
	v_add_u32_e32 v126, 0xd0, v112
	s_nop 0
	v_addc_co_u32_e32 v1, vcc, 0, v5, vcc
	v_add_co_u32_e32 v4, vcc, 0x2e7b4000, v4
	global_load_dwordx4 v[20:23], v[0:1], off
	global_load_dwordx4 v[8:11], v[0:1], off offset:1024
	global_load_dwordx4 v[12:15], v[0:1], off offset:2048
	s_nop 0
	global_load_dwordx4 v[0:3], v[0:1], off offset:3072
	v_addc_co_u32_e32 v5, vcc, 0, v5, vcc
	global_load_dwordx4 v[4:7], v[4:5], off
	s_load_dwordx2 s[6:7], s[26:27], 0xa0
	global_load_dwordx2 v[100:101], v[66:67], off
	v_lshl_add_u64 v[66:67], s[2:3], 0, v[94:95]
	global_load_dwordx4 v[116:119], v[66:67], off
	v_lshl_add_u64 v[66:67], s[2:3], 0, v[92:93]
	s_waitcnt lgkmcnt(0)
	v_lshl_add_u64 v[102:103], v[78:79], 2, s[6:7]
	global_load_dword v79, v[102:103], off
	v_lshl_add_u64 v[102:103], s[2:3], 0, v[86:87]
	v_add_co_u32_e32 v124, vcc, s12, v102
	global_load_dwordx4 v[74:77], v[66:67], off
	s_nop 0
	v_addc_co_u32_e32 v125, vcc, 0, v103, vcc
	global_load_ushort v162, v[124:125], off
	v_add_co_u32_e32 v124, vcc, s13, v102
	v_lshl_add_u64 v[66:67], s[2:3], 0, v[90:91]
	s_nop 0
	v_addc_co_u32_e32 v125, vcc, 0, v103, vcc
	global_load_ushort v131, v[124:125], off offset:512
	v_add_co_u32_e32 v124, vcc, s33, v102
	global_load_dwordx4 v[70:73], v[66:67], off
	s_nop 0
	v_addc_co_u32_e32 v125, vcc, 0, v103, vcc
	v_add_co_u32_e32 v102, vcc, s28, v102
	v_lshl_add_u64 v[66:67], s[2:3], 0, v[88:89]
	s_nop 0
	v_addc_co_u32_e32 v103, vcc, 0, v103, vcc
	global_load_dwordx4 v[66:69], v[66:67], off
	v_add_u32_e32 v127, 0xe0, v112
	global_load_ushort v130, v[124:125], off offset:1024
	global_load_ushort v129, v[102:103], off offset:1536
	v_add_u32_e32 v124, 0xb0, v112
	v_add_u32_e32 v125, 0xc0, v112
	v_add_u32_e32 v128, 0xf0, v112
	s_mov_b64 s[6:7], 0x4400
	v_add_u32_e32 v78, 16, v78
	v_lshl_add_u64 v[86:87], v[86:87], 0, 32
	v_lshl_add_u64 v[88:89], v[88:89], 0, 32
	v_lshl_add_u64 v[90:91], v[90:91], 0, 32
	v_lshl_add_u64 v[92:93], v[92:93], 0, 32
	v_lshl_add_u64 v[94:95], v[94:95], 0, 32
	v_lshl_add_u64 v[96:97], v[96:97], 0, s[14:15]
	v_lshl_add_u64 v[98:99], v[98:99], 0, s[6:7]
	s_waitcnt vmcnt(8)
	v_mfma_f32_16x16x32_bf16 v[120:123], v[116:119], v[62:65], 0
	s_nop 7
	ds_write_b32 v106, v120
	ds_write_b32 v106, v121 offset:528
	ds_write_b32 v106, v122 offset:1056
	ds_write_b32 v107, v123
	v_mfma_f32_16x16x32_bf16 v[120:123], v[116:119], v[58:61], 0
	s_nop 7
	ds_write_b32 v106, v120 offset:64
	ds_write_b32 v106, v121 offset:592
	ds_write_b32 v106, v122 offset:1120
	ds_write_b32 v107, v123 offset:64
	v_mfma_f32_16x16x32_bf16 v[120:123], v[116:119], v[54:57], 0
	s_nop 7
	ds_write_b32 v106, v120 offset:128
	ds_write_b32 v106, v121 offset:656
	ds_write_b32 v106, v122 offset:1184
	ds_write_b32 v107, v123 offset:128
	v_mfma_f32_16x16x32_bf16 v[120:123], v[116:119], v[50:53], 0
	s_nop 7
	ds_write2_b32 v108, v120, v121 offset1:132
	ds_write_b32 v108, v122 offset:1056
	ds_write_b32 v109, v123
	v_mfma_f32_16x16x32_bf16 v[120:123], v[116:119], v[46:49], 0
	s_nop 7
	ds_write_b32 v106, v120 offset:256
	ds_write_b32 v106, v121 offset:784
	ds_write_b32 v106, v122 offset:1312
	ds_write_b32 v107, v123 offset:256
	v_mfma_f32_16x16x32_bf16 v[120:123], v[116:119], v[42:45], 0
	s_nop 7
	ds_write_b32 v106, v120 offset:320
	ds_write_b32 v106, v121 offset:848
	ds_write_b32 v106, v122 offset:1376
	ds_write_b32 v107, v123 offset:320
	v_mfma_f32_16x16x32_bf16 v[120:123], v[116:119], v[38:41], 0
	s_nop 7
	ds_write_b32 v106, v120 offset:384
	ds_write_b32 v106, v121 offset:912
	ds_write_b32 v106, v122 offset:1440
	ds_write_b32 v107, v123 offset:384
	v_mfma_f32_16x16x32_bf16 v[116:119], v[116:119], v[34:37], 0
	s_nop 7
	ds_write2_b32 v110, v116, v117 offset1:132
	ds_write_b32 v110, v118 offset:1056
	ds_write_b32 v111, v119
	s_waitcnt lgkmcnt(0)
	ds_read2st64_b32 v[102:103], v112 offset1:1
	ds_read2_b32 v[132:133], v112 offset0:132 offset1:196
	v_mul_f32_e32 v163, v33, v101
	v_mul_f32_e32 v101, v32, v101
	v_fmac_f32_e32 v101, v33, v100
	v_fma_f32 v163, v32, v100, -v163
	s_waitcnt lgkmcnt(1)
	v_add_f32_e32 v100, v101, v103
	ds_read2st64_b32 v[134:135], v115 offset0:4 offset1:5
	v_add_f32_e32 v102, v163, v102
	v_mul_f32_e32 v103, v32, v100
	v_mul_f32_e32 v101, v33, v100
	v_fmac_f32_e32 v103, v33, v102
	v_fma_f32 v101, v32, v102, -v101
	s_waitcnt lgkmcnt(1)
	v_add_f32_e32 v103, v133, v103
	v_add_f32_e32 v101, v132, v101
	v_mul_f32_e32 v132, v33, v103
	v_add_u32_e32 v116, 48, v112
	v_fma_f32 v132, v32, v101, -v132
	ds_read2st64_b32 v[136:137], v116 offset0:6 offset1:7
	s_waitcnt lgkmcnt(1)
; __device__ __forceinline__ unsigned cvt_pk(float lo, float hi) { f32x2_t v = {lo, hi}; bf16x2_t b = __builtin_convertvector(v, bf16x2_t); return __builtin_bit_cast(unsigned, b); }
; __device__ __forceinline__ float bflo(unsigned w) { return __uint_as_float(w << 16); }
; __device__ __forceinline__ float bfhi(unsigned w) { return __uint_as_float(w & 0xffff0000u); }
; #define S5_LDS_FENCE() do { __builtin_amdgcn_wave_barrier(); asm volatile("s_waitcnt lgkmcnt(0)" ::: "memory"); } while (0)
; template <bool WRITEH>
; __device__ __forceinline__ void s5_block(const S5Coef& C, const bf16x8 (&bm)[8], u32x4 uw, float* Hs, int lane, float& hr, float& hi) {
;     ...
;     for (int tl = 0; tl < 16; ++tl) { bur[tl] = Hs[tl * 132 + lane]; bui[tl] = Hs[tl * 132 + 64 + lane]; }
; #pragma unroll
;     for (int tl = 0; tl < 16; ++tl) { const float nr = C.ar * hr - C.ai * hi + bur[tl], ni = C.ar * hi + C.ai * hr + bui[tl]; hr = nr; hi = ni; bur[tl] = hr; bui[tl] = hi; }
;     if (WRITEH) {
; #pragma unroll
;         for (int tl = 0; tl < 16; ++tl) { Hs[tl * 132 + lane] = bur[tl]; Hs[tl * 132 + 64 + lane] = bui[tl]; }
;     }
;     S5_LDS_FENCE();
; __device__ __forceinline__ void s5_unit(ArgsP A, int l, int unit, unsigned char* lds, int wave_, int lane_) {
;     ...
;             for (int ks = 0; ks < 4; ++ks) { const float* hp = Hs + (lane & 15) * 132 + 32 * ks + 8 * (lane >> 4); const f32x4 h0 = *(const f32x4*)hp, h1 = *(const f32x4*)(hp + 4);
;                 u32x4 wh; wh.x = cvt_pk(h0[0], h0[1]); wh.y = cvt_pk(h0[2], h0[3]); wh.z = cvt_pk(h1[0], h1[1]); wh.w = cvt_pk(h1[2], h1[3]);
;                 u32x4 wl; wl.x = cvt_pk(h0[0] - bflo(wh.x), h0[1] - bfhi(wh.x)); wl.y = cvt_pk(h0[2] - bflo(wh.y), h0[3] - bfhi(wh.y)); wl.z = cvt_pk(h1[0] - bflo(wh.z), h1[1] - bfhi(wh.z)); wl.w = cvt_pk(h1[2] - bflo(wh.w), h1[3] - bfhi(wh.w));
;                 const bf16x8 hh_ = __builtin_bit_cast(bf16x8, wh), hl_ = __builtin_bit_cast(bf16x8, wl);
	v_add_f32_e32 v134, v134, v132
	v_mul_f32_e32 v132, v32, v103
	v_fmac_f32_e32 v132, v33, v101
	v_add_f32_e32 v135, v135, v132
	v_mul_f32_e32 v132, v33, v135
	v_add_u32_e32 v117, 64, v112
	v_fma_f32 v132, v32, v134, -v132
	ds_read2st64_b32 v[138:139], v117 offset0:8 offset1:9
	s_waitcnt lgkmcnt(1)
	v_add_f32_e32 v136, v136, v132
	v_mul_f32_e32 v132, v32, v135
	v_fmac_f32_e32 v132, v33, v134
	v_add_f32_e32 v137, v137, v132
	v_mul_f32_e32 v132, v33, v137
	v_add_u32_e32 v118, 0x50, v112
	v_fma_f32 v132, v32, v136, -v132
	ds_read2st64_b32 v[140:141], v118 offset0:10 offset1:11
	s_waitcnt lgkmcnt(1)
	v_add_f32_e32 v138, v138, v132
	v_mul_f32_e32 v132, v32, v137
	v_fmac_f32_e32 v132, v33, v136
	v_add_f32_e32 v139, v139, v132
	v_mul_f32_e32 v132, v33, v139
	v_add_u32_e32 v119, 0x60, v112
	v_fma_f32 v132, v32, v138, -v132
	ds_read2st64_b32 v[142:143], v119 offset0:12 offset1:13
	s_waitcnt lgkmcnt(1)
	v_add_f32_e32 v140, v140, v132
	v_mul_f32_e32 v132, v32, v139
	v_fmac_f32_e32 v132, v33, v138
	v_add_f32_e32 v141, v141, v132
	v_mul_f32_e32 v132, v33, v141
	v_add_u32_e32 v120, 0x70, v112
	v_fma_f32 v132, v32, v140, -v132
	ds_read2st64_b32 v[144:145], v120 offset0:14 offset1:15
	s_waitcnt lgkmcnt(1)
	v_add_f32_e32 v142, v142, v132
	v_mul_f32_e32 v132, v32, v141
	v_fmac_f32_e32 v132, v33, v140
	v_add_f32_e32 v143, v143, v132
	v_mul_f32_e32 v132, v33, v143
	v_add_u32_e32 v121, 0x80, v112
	v_fma_f32 v132, v32, v142, -v132
	ds_read2st64_b32 v[146:147], v121 offset0:16 offset1:17
	s_waitcnt lgkmcnt(1)
	v_add_f32_e32 v144, v144, v132
	v_mul_f32_e32 v132, v32, v143
	v_fmac_f32_e32 v132, v33, v142
	v_add_f32_e32 v145, v145, v132
	v_mul_f32_e32 v132, v33, v145
	v_add_u32_e32 v122, 0x90, v112
	v_fma_f32 v132, v32, v144, -v132
	ds_read2st64_b32 v[148:149], v122 offset0:18 offset1:19
	s_waitcnt lgkmcnt(1)
	v_add_f32_e32 v146, v146, v132
	v_mul_f32_e32 v132, v32, v145
	v_fmac_f32_e32 v132, v33, v144
	v_add_f32_e32 v147, v147, v132
	v_mul_f32_e32 v132, v33, v147
	v_add_u32_e32 v123, 0xa0, v112
	v_fma_f32 v132, v32, v146, -v132
	ds_read2st64_b32 v[150:151], v123 offset0:20 offset1:21
	s_waitcnt lgkmcnt(1)
	v_add_f32_e32 v148, v148, v132
	v_mul_f32_e32 v132, v32, v147
	v_fmac_f32_e32 v132, v33, v146
	v_add_f32_e32 v149, v149, v132
	v_mul_f32_e32 v132, v33, v149
	v_fma_f32 v132, v32, v148, -v132
	ds_read2st64_b32 v[152:153], v124 offset0:22 offset1:23
	s_waitcnt lgkmcnt(1)
	v_add_f32_e32 v150, v150, v132
	v_mul_f32_e32 v132, v32, v149
	v_fmac_f32_e32 v132, v33, v148
	v_add_f32_e32 v151, v151, v132
	v_mul_f32_e32 v132, v33, v151
	v_fma_f32 v132, v32, v150, -v132
	ds_read2st64_b32 v[154:155], v125 offset0:24 offset1:25
	s_waitcnt lgkmcnt(1)
	v_add_f32_e32 v152, v152, v132
	v_mul_f32_e32 v132, v32, v151
	v_fmac_f32_e32 v132, v33, v150
	v_add_f32_e32 v153, v153, v132
	v_mul_f32_e32 v132, v33, v153
	v_fma_f32 v132, v32, v152, -v132
	ds_read2st64_b32 v[156:157], v126 offset0:26 offset1:27
	s_waitcnt lgkmcnt(1)
	v_add_f32_e32 v154, v154, v132
	v_mul_f32_e32 v132, v32, v153
	v_fmac_f32_e32 v132, v33, v152
	v_add_f32_e32 v155, v155, v132
	v_mul_f32_e32 v132, v33, v155
	v_fma_f32 v132, v32, v154, -v132
	ds_read2st64_b32 v[158:159], v127 offset0:28 offset1:29
	s_waitcnt lgkmcnt(1)
	v_add_f32_e32 v156, v156, v132
	v_mul_f32_e32 v132, v32, v155
	v_fmac_f32_e32 v132, v33, v154
	v_add_f32_e32 v157, v157, v132
	v_mul_f32_e32 v132, v33, v157
	v_fma_f32 v132, v32, v156, -v132
	ds_read2st64_b32 v[160:161], v128 offset0:30 offset1:31
	s_waitcnt lgkmcnt(1)
	v_add_f32_e32 v158, v158, v132
	v_mul_f32_e32 v132, v32, v157
	v_fmac_f32_e32 v132, v33, v156
	v_add_f32_e32 v159, v159, v132
	v_mul_f32_e32 v132, v33, v159
	v_mul_f32_e32 v133, v32, v159
	v_fma_f32 v132, v32, v158, -v132
	v_fmac_f32_e32 v133, v33, v158
	s_waitcnt lgkmcnt(0)
	v_add_f32_e32 v132, v160, v132
	v_add_f32_e32 v133, v161, v133
	ds_write2st64_b32 v112, v102, v100 offset1:1
	ds_write2_b32 v112, v101, v103 offset0:132 offset1:196
	ds_write2st64_b32 v115, v134, v135 offset0:4 offset1:5
	ds_write2st64_b32 v116, v136, v137 offset0:6 offset1:7
	ds_write2st64_b32 v117, v138, v139 offset0:8 offset1:9
	ds_write2st64_b32 v118, v140, v141 offset0:10 offset1:11
	ds_write2st64_b32 v119, v142, v143 offset0:12 offset1:13
	ds_write2st64_b32 v120, v144, v145 offset0:14 offset1:15
	ds_write2st64_b32 v121, v146, v147 offset0:16 offset1:17
	ds_write2st64_b32 v122, v148, v149 offset0:18 offset1:19
	ds_write2st64_b32 v123, v150, v151 offset0:20 offset1:21
	ds_write2st64_b32 v124, v152, v153 offset0:22 offset1:23
	ds_write2st64_b32 v125, v154, v155 offset0:24 offset1:25
	ds_write2st64_b32 v126, v156, v157 offset0:26 offset1:27
	ds_write2st64_b32 v127, v158, v159 offset0:28 offset1:29
	ds_write2st64_b32 v128, v132, v133 offset0:30 offset1:31
	s_waitcnt lgkmcnt(0)
	ds_read_b128 v[100:103], v113
	ds_read_b128 v[134:137], v113 offset:16
	s_waitcnt vmcnt(4)
	v_lshlrev_b32_e32 v131, 16, v131
	v_mul_f32_e32 v160, v33, v133
	v_fma_f32 v160, v32, v132, -v160
	s_waitcnt lgkmcnt(1)
	v_cvt_pk_bf16_f32 v138, v100, v101
	v_cvt_pk_bf16_f32 v139, v102, v103
	v_lshlrev_b32_e32 v142, 16, v138
	v_and_b32_e32 v143, 0xffff0000, v138
	v_pk_add_f32 v[100:101], v[100:101], v[142:143] neg_lo:[0,1] neg_hi:[0,1]
	v_lshlrev_b32_e32 v142, 16, v139
	v_and_b32_e32 v143, 0xffff0000, v139
	s_waitcnt lgkmcnt(0)
; __device__ __forceinline__ unsigned cvt_pk(float lo, float hi) { f32x2_t v = {lo, hi}; bf16x2_t b = __builtin_convertvector(v, bf16x2_t); return __builtin_bit_cast(unsigned, b); }
; __device__ __forceinline__ float bf2f(unsigned short h) { return __uint_as_float(((unsigned)h) << 16); }
; __device__ __forceinline__ float bflo(unsigned w) { return __uint_as_float(w << 16); }
; __device__ __forceinline__ float bfhi(unsigned w) { return __uint_as_float(w & 0xffff0000u); }
; __device__ __forceinline__ unsigned short f2bf(float f) { return (unsigned short)(cvt_pk(f, 0.f) & 0xffffu); }
; __device__ __forceinline__ void s5_unit(ArgsP A, int l, int unit, unsigned char* lds, int wave_, int lane_) {
;     ...
;             f32x4 y = (f32x4){0.f, 0.f, 0.f, 0.f}, y2 = (f32x4){0.f, 0.f, 0.f, 0.f};
; #pragma unroll
;             for (int ks = 0; ks < 4; ++ks) { const float* hp = Hs + (lane & 15) * 132 + 32 * ks + 8 * (lane >> 4); const f32x4 h0 = *(const f32x4*)hp, h1 = *(const f32x4*)(hp + 4);
;                 u32x4 wh; wh.x = cvt_pk(h0[0], h0[1]); wh.y = cvt_pk(h0[2], h0[3]); wh.z = cvt_pk(h1[0], h1[1]); wh.w = cvt_pk(h1[2], h1[3]);
;                 u32x4 wl; wl.x = cvt_pk(h0[0] - bflo(wh.x), h0[1] - bfhi(wh.x)); wl.y = cvt_pk(h0[2] - bflo(wh.y), h0[3] - bfhi(wh.y)); wl.z = cvt_pk(h1[0] - bflo(wh.z), h1[1] - bfhi(wh.z)); wl.w = cvt_pk(h1[2] - bflo(wh.w), h1[3] - bfhi(wh.w));
;                 const bf16x8 hh_ = __builtin_bit_cast(bf16x8, wh), hl_ = __builtin_bit_cast(bf16x8, wl);
;                 y = __builtin_amdgcn_mfma_f32_16x16x32_bf16(hh_, chl[2 * ks], y, 0, 0, 0); y2 = __builtin_amdgcn_mfma_f32_16x16x32_bf16(hh_, chl[2 * ks + 1], y2, 0, 0, 0);
;                 y2 = __builtin_amdgcn_mfma_f32_16x16x32_bf16(hl_, chl[2 * ks], y2, 0, 0, 0); }
;             y = y + y2;
; #pragma unroll
;             for (int i = 0; i < 4; ++i) { const int t = 16 * blk + 4 * (lane >> 4) + i; const int col = 16 * g + (lane & 15);
;                 const float uval = bf2f(uraw[i]); const float v = gelu_tanh(y[i] + dv * uval); ys[t * YS_STRIDE + col] = f2bf(v); }
	v_cvt_pk_bf16_f32 v140, v134, v135
	v_cvt_pk_bf16_f32 v141, v136, v137
	v_pk_add_f32 v[102:103], v[102:103], v[142:143] neg_lo:[0,1] neg_hi:[0,1]
	v_cvt_pk_bf16_f32 v100, v100, v101
	v_cvt_pk_bf16_f32 v101, v102, v103
	v_lshlrev_b32_e32 v102, 16, v140
	v_and_b32_e32 v103, 0xffff0000, v140
	v_pk_add_f32 v[102:103], v[134:135], v[102:103] neg_lo:[0,1] neg_hi:[0,1]
	v_lshlrev_b32_e32 v134, 16, v141
	v_and_b32_e32 v135, 0xffff0000, v141
	v_pk_add_f32 v[134:135], v[136:137], v[134:135] neg_lo:[0,1] neg_hi:[0,1]
	v_cvt_pk_bf16_f32 v102, v102, v103
	v_cvt_pk_bf16_f32 v103, v134, v135
	v_mfma_f32_16x16x32_bf16 v[134:137], v[138:141], v[24:27], 0
	v_mfma_f32_16x16x32_bf16 v[138:141], v[138:141], v[28:31], 0
	v_mfma_f32_16x16x32_bf16 v[100:103], v[100:103], v[24:27], v[138:141]
	s_nop 6
	ds_read_b128 v[138:141], v113 offset:128
	ds_read_b128 v[142:145], v113 offset:144
	s_waitcnt lgkmcnt(1)
	v_cvt_pk_bf16_f32 v146, v138, v139
	v_cvt_pk_bf16_f32 v147, v140, v141
	v_lshlrev_b32_e32 v150, 16, v146
	v_and_b32_e32 v151, 0xffff0000, v146
	v_pk_add_f32 v[138:139], v[138:139], v[150:151] neg_lo:[0,1] neg_hi:[0,1]
	v_lshlrev_b32_e32 v150, 16, v147
	v_and_b32_e32 v151, 0xffff0000, v147
	s_waitcnt lgkmcnt(0)
	v_cvt_pk_bf16_f32 v148, v142, v143
	v_cvt_pk_bf16_f32 v149, v144, v145
	v_pk_add_f32 v[140:141], v[140:141], v[150:151] neg_lo:[0,1] neg_hi:[0,1]
	v_cvt_pk_bf16_f32 v138, v138, v139
	v_cvt_pk_bf16_f32 v139, v140, v141
	v_lshlrev_b32_e32 v140, 16, v148
	v_and_b32_e32 v141, 0xffff0000, v148
	v_pk_add_f32 v[140:141], v[142:143], v[140:141] neg_lo:[0,1] neg_hi:[0,1]
	v_lshlrev_b32_e32 v142, 16, v149
	v_and_b32_e32 v143, 0xffff0000, v149
	v_pk_add_f32 v[142:143], v[144:145], v[142:143] neg_lo:[0,1] neg_hi:[0,1]
	v_cvt_pk_bf16_f32 v140, v140, v141
	v_cvt_pk_bf16_f32 v141, v142, v143
	v_mfma_f32_16x16x32_bf16 v[100:103], v[146:149], v[20:23], v[100:103]
	s_nop 0
	v_mfma_f32_16x16x32_bf16 v[100:103], v[138:141], v[16:19], v[100:103]
	ds_read_b128 v[138:141], v113 offset:256
	ds_read_b128 v[142:145], v113 offset:272
	v_mfma_f32_16x16x32_bf16 v[134:137], v[146:149], v[16:19], v[134:137]
	s_waitcnt lgkmcnt(1)
	v_cvt_pk_bf16_f32 v146, v138, v139
	v_cvt_pk_bf16_f32 v147, v140, v141
	v_lshlrev_b32_e32 v150, 16, v146
	v_and_b32_e32 v151, 0xffff0000, v146
	v_pk_add_f32 v[138:139], v[138:139], v[150:151] neg_lo:[0,1] neg_hi:[0,1]
	v_lshlrev_b32_e32 v150, 16, v147
	v_and_b32_e32 v151, 0xffff0000, v147
	s_waitcnt lgkmcnt(0)
	v_cvt_pk_bf16_f32 v148, v142, v143
	v_cvt_pk_bf16_f32 v149, v144, v145
	v_pk_add_f32 v[140:141], v[140:141], v[150:151] neg_lo:[0,1] neg_hi:[0,1]
	v_cvt_pk_bf16_f32 v138, v138, v139
	v_cvt_pk_bf16_f32 v139, v140, v141
	v_lshlrev_b32_e32 v140, 16, v148
	v_and_b32_e32 v141, 0xffff0000, v148
	v_pk_add_f32 v[140:141], v[142:143], v[140:141] neg_lo:[0,1] neg_hi:[0,1]
	v_lshlrev_b32_e32 v142, 16, v149
	v_and_b32_e32 v143, 0xffff0000, v149
	v_pk_add_f32 v[142:143], v[144:145], v[142:143] neg_lo:[0,1] neg_hi:[0,1]
	v_cvt_pk_bf16_f32 v140, v140, v141
	v_cvt_pk_bf16_f32 v141, v142, v143
	v_mfma_f32_16x16x32_bf16 v[100:103], v[146:149], v[12:15], v[100:103]
	s_nop 0
	v_mfma_f32_16x16x32_bf16 v[100:103], v[138:141], v[8:11], v[100:103]
	ds_read_b128 v[138:141], v113 offset:384
	ds_read_b128 v[142:145], v113 offset:400
	v_mfma_f32_16x16x32_bf16 v[134:137], v[146:149], v[8:11], v[134:137]
	s_waitcnt lgkmcnt(1)
	v_cvt_pk_bf16_f32 v146, v138, v139
	v_cvt_pk_bf16_f32 v147, v140, v141
	v_lshlrev_b32_e32 v150, 16, v146
	v_and_b32_e32 v151, 0xffff0000, v146
	v_pk_add_f32 v[138:139], v[138:139], v[150:151] neg_lo:[0,1] neg_hi:[0,1]
	v_lshlrev_b32_e32 v150, 16, v147
	v_and_b32_e32 v151, 0xffff0000, v147
	s_waitcnt lgkmcnt(0)
	v_cvt_pk_bf16_f32 v148, v142, v143
	v_cvt_pk_bf16_f32 v149, v144, v145
	v_pk_add_f32 v[140:141], v[140:141], v[150:151] neg_lo:[0,1] neg_hi:[0,1]
	v_cvt_pk_bf16_f32 v138, v138, v139
	v_cvt_pk_bf16_f32 v139, v140, v141
	v_lshlrev_b32_e32 v140, 16, v148
	v_and_b32_e32 v141, 0xffff0000, v148
	v_pk_add_f32 v[140:141], v[142:143], v[140:141] neg_lo:[0,1] neg_hi:[0,1]
	v_lshlrev_b32_e32 v142, 16, v149
	v_and_b32_e32 v143, 0xffff0000, v149
	v_pk_add_f32 v[142:143], v[144:145], v[142:143] neg_lo:[0,1] neg_hi:[0,1]
	v_cvt_pk_bf16_f32 v140, v140, v141
	v_cvt_pk_bf16_f32 v141, v142, v143
	v_mfma_f32_16x16x32_bf16 v[100:103], v[146:149], v[4:7], v[100:103]
	v_mfma_f32_16x16x32_bf16 v[134:137], v[146:149], v[0:3], v[134:137]
	v_mfma_f32_16x16x32_bf16 v[138:141], v[138:141], v[0:3], v[100:103]
	s_nop 7
	v_pk_add_f32 v[102:103], v[134:135], v[138:139]
	v_lshlrev_b32_e32 v134, 16, v162
	v_fma_f32 v102, v79, v134, v102
	v_fmac_f32_e32 v103, v79, v131
	v_mul_f32_e32 v134, 0x3d372713, v102
	v_mul_f32_e32 v131, 0x3d372713, v103
	v_mul_f32_e32 v134, v102, v134
	v_mul_f32_e32 v131, v103, v131
	v_fma_f32 v134, v102, v134, v102
	v_fma_f32 v131, v103, v131, v103
	v_mul_f32_e32 v134, 0x3f4c422a, v134
	v_mul_f32_e32 v131, 0x3f4c422a, v131
	v_add_f32_e32 v134, v134, v134
	v_add_f32_e32 v131, v131, v131
	v_mul_f32_e32 v134, 0x3fb8aa3b, v134
	v_mul_f32_e32 v131, 0x3fb8aa3b, v131
	v_exp_f32_e32 v134, v134
	v_exp_f32_e32 v131, v131
	v_mul_f32_e32 v102, 0.5, v102
	v_mul_f32_e32 v103, 0.5, v103
	v_add_f32_e32 v134, 1.0, v134
	v_add_f32_e32 v131, 1.0, v131
	v_rcp_f32_e32 v134, v134
	v_rcp_f32_e32 v131, v131
	v_pk_add_f32 v[100:101], v[136:137], v[140:141]
	v_fma_f32 v134, v134, -2.0, 1.0
	v_fma_f32 v131, v131, -2.0, 1.0
	v_add_f32_e32 v134, 1.0, v134
	v_add_f32_e32 v131, 1.0, v131
	v_mul_f32_e32 v102, v102, v134
	v_mul_f32_e32 v103, v103, v131
	v_cvt_pk_bf16_f32 v134, v102, s0
	v_add_u32_e32 v102, s5, v114
	v_cvt_pk_bf16_f32 v103, v103, s0
	ds_write_b16 v102, v103 offset:1040
	s_waitcnt vmcnt(1)
; template <bool WRITEH>
; __device__ __forceinline__ void s5_block(const S5Coef& C, const bf16x8 (&bm)[8], u32x4 uw, float* Hs, int lane, float& hr, float& hi) {
;     const bf16x8 ua = __builtin_bit_cast(bf16x8, uw);
; #pragma unroll
;     for (int nb = 0; nb < 8; ++nb) { const f32x4 d = __builtin_amdgcn_mfma_f32_16x16x32_bf16(ua, bm[nb], (f32x4){0.f, 0.f, 0.f, 0.f}, 0, 0, 0);
; #pragma unroll
;         for (int i = 0; i < 4; ++i) Hs[(4 * (lane >> 4) + i) * 132 + 16 * nb + (lane & 15)] = d[i]; }
;     S5_LDS_FENCE();
;     float bur[16], bui[16];
; #pragma unroll
; __device__ __forceinline__ void s5_unit(ArgsP A, int l, int unit, unsigned char* lds, int wave_, int lane_) {
;     ...
;         for (int blk = 0; blk < 4; ++blk) {
;             unsigned short uraw[4];
; #pragma unroll
;             for (int i = 0; i < 4; ++i) uraw[i] = PROJ[(size_t)(rowbase + 16 * blk + 4 * (lane >> 4) + i) * INWP + C_S5 + 16 * g + (lane & 15)];
;             s5_block<true>(C, bm, uw[blk], Hs, lane, hr, hi);
;             f32x4 y = (f32x4){0.f, 0.f, 0.f, 0.f}, y2 = (f32x4){0.f, 0.f, 0.f, 0.f};
; #pragma unroll
;             for (int ks = 0; ks < 4; ++ks) { const float* hp = Hs + (lane & 15) * 132 + 32 * ks + 8 * (lane >> 4); const f32x4 h0 = *(const f32x4*)hp, h1 = *(const f32x4*)(hp + 4);
;                 u32x4 wh; wh.x = cvt_pk(h0[0], h0[1]); wh.y = cvt_pk(h0[2], h0[3]); wh.z = cvt_pk(h1[0], h1[1]); wh.w = cvt_pk(h1[2], h1[3]);
;                 u32x4 wl; wl.x = cvt_pk(h0[0] - bflo(wh.x), h0[1] - bfhi(wh.x)); wl.y = cvt_pk(h0[2] - bflo(wh.y), h0[3] - bfhi(wh.y)); wl.z = cvt_pk(h1[0] - bflo(wh.z), h1[1] - bfhi(wh.z)); wl.w = cvt_pk(h1[2] - bflo(wh.w), h1[3] - bfhi(wh.w));
;                 const bf16x8 hh_ = __builtin_bit_cast(bf16x8, wh), hl_ = __builtin_bit_cast(bf16x8, wl);
;                 y = __builtin_amdgcn_mfma_f32_16x16x32_bf16(hh_, chl[2 * ks], y, 0, 0, 0); y2 = __builtin_amdgcn_mfma_f32_16x16x32_bf16(hh_, chl[2 * ks + 1], y2, 0, 0, 0);
;                 y2 = __builtin_amdgcn_mfma_f32_16x16x32_bf16(hl_, chl[2 * ks], y2, 0, 0, 0); }
;             y = y + y2;
; #pragma unroll
;             for (int i = 0; i < 4; ++i) { const int t = 16 * blk + 4 * (lane >> 4) + i; const int col = 16 * g + (lane & 15);
;                 const float uval = bf2f(uraw[i]); const float v = gelu_tanh(y[i] + dv * uval); ys[t * YS_STRIDE + col] = f2bf(v); }
	v_lshlrev_b32_e32 v103, 16, v130
	v_fma_f32 v100, v79, v103, v100
	v_mul_f32_e32 v103, 0x3d372713, v100
	v_mul_f32_e32 v103, v100, v103
	v_fma_f32 v103, v100, v103, v100
	v_mul_f32_e32 v103, 0x3f4c422a, v103
	v_add_f32_e32 v103, v103, v103
	v_mul_f32_e32 v103, 0x3fb8aa3b, v103
	v_exp_f32_e32 v103, v103
	v_mul_f32_e32 v100, 0.5, v100
	ds_write_b16 v102, v134
	v_mfma_f32_16x16x32_bf16 v[134:137], v[74:77], v[62:65], 0
	v_add_f32_e32 v103, 1.0, v103
	v_rcp_f32_e32 v103, v103
	s_add_i32 s5, s5, 32
	s_cmpk_lg_i32 s5, 0x80
	v_fma_f32 v103, v103, -2.0, 1.0
	v_add_f32_e32 v103, 1.0, v103
	v_mul_f32_e32 v100, v100, v103
	v_cvt_pk_bf16_f32 v100, v100, s0
	ds_write_b16 v102, v100 offset:2080
	s_waitcnt vmcnt(0)
	v_lshlrev_b32_e32 v100, 16, v129
	v_fmac_f32_e32 v101, v79, v100
	v_mul_f32_e32 v100, 0x3d372713, v101
	v_mul_f32_e32 v100, v101, v100
	v_fma_f32 v100, v101, v100, v101
	v_mul_f32_e32 v100, 0x3f4c422a, v100
	v_add_f32_e32 v100, v100, v100
	v_mul_f32_e32 v100, 0x3fb8aa3b, v100
	v_exp_f32_e32 v100, v100
	v_mul_f32_e32 v101, 0.5, v101
	v_add_f32_e32 v100, 1.0, v100
	v_rcp_f32_e32 v100, v100
	s_nop 0
	v_fma_f32 v100, v100, -2.0, 1.0
	v_add_f32_e32 v100, 1.0, v100
	v_mul_f32_e32 v100, v101, v100
	v_cvt_pk_bf16_f32 v100, v100, s0
	ds_write_b16 v102, v100 offset:3120
	s_waitcnt lgkmcnt(0)
	ds_write_b32 v106, v134
	ds_write_b32 v106, v135 offset:528
	ds_write_b32 v106, v136 offset:1056
	ds_write_b32 v107, v137
	v_mfma_f32_16x16x32_bf16 v[134:137], v[74:77], v[58:61], 0
	s_nop 7
	ds_write_b32 v106, v134 offset:64
	ds_write_b32 v106, v135 offset:592
	ds_write_b32 v106, v136 offset:1120
	ds_write_b32 v107, v137 offset:64
	v_mfma_f32_16x16x32_bf16 v[134:137], v[74:77], v[54:57], 0
	s_nop 7
	ds_write_b32 v106, v134 offset:128
	ds_write_b32 v106, v135 offset:656
	ds_write_b32 v106, v136 offset:1184
	ds_write_b32 v107, v137 offset:128
	v_mfma_f32_16x16x32_bf16 v[134:137], v[74:77], v[50:53], 0
	s_nop 7
	ds_write2_b32 v108, v134, v135 offset1:132
	ds_write_b32 v108, v136 offset:1056
	ds_write_b32 v109, v137
	v_mfma_f32_16x16x32_bf16 v[134:137], v[74:77], v[46:49], 0
	s_nop 7
	ds_write_b32 v106, v134 offset:256
	ds_write_b32 v106, v135 offset:784
	ds_write_b32 v106, v136 offset:1312
	ds_write_b32 v107, v137 offset:256
	v_mfma_f32_16x16x32_bf16 v[134:137], v[74:77], v[42:45], 0
	s_nop 7
	ds_write_b32 v106, v134 offset:320
	ds_write_b32 v106, v135 offset:848
	ds_write_b32 v106, v136 offset:1376
	ds_write_b32 v107, v137 offset:320
	v_mfma_f32_16x16x32_bf16 v[134:137], v[74:77], v[38:41], 0
	v_lshl_add_u64 v[100:101], s[2:3], 0, v[84:85]
	s_nop 6
	ds_write_b32 v106, v134 offset:384
	ds_write_b32 v106, v135 offset:912
	ds_write_b32 v106, v136 offset:1440
	ds_write_b32 v107, v137 offset:384
	v_mfma_f32_16x16x32_bf16 v[74:77], v[74:77], v[34:37], 0
	s_nop 7
	ds_write2_b32 v110, v74, v75 offset1:132
	ds_write_b32 v110, v76 offset:1056
	ds_write_b32 v111, v77
	v_add_co_u32_e32 v74, vcc, s12, v100
	v_lshl_add_u64 v[84:85], v[84:85], 0, 32
	s_nop 0
	v_addc_co_u32_e32 v75, vcc, 0, v101, vcc
	global_load_ushort v103, v[74:75], off
	v_add_co_u32_e32 v74, vcc, s13, v100
	s_waitcnt vmcnt(0)
	v_lshlrev_b32_e32 v103, 16, v103
	v_addc_co_u32_e32 v75, vcc, 0, v101, vcc
	global_load_ushort v129, v[74:75], off offset:512
	v_add_co_u32_e32 v74, vcc, s33, v100
	s_nop 1
	v_addc_co_u32_e32 v75, vcc, 0, v101, vcc
	global_load_ushort v158, v[74:75], off offset:1024
	v_add_co_u32_e32 v74, vcc, s28, v100
	s_nop 1
	v_addc_co_u32_e32 v75, vcc, 0, v101, vcc
	global_load_ushort v159, v[74:75], off offset:1536
	s_waitcnt lgkmcnt(0)
	ds_read2st64_b32 v[74:75], v112 offset1:1
	ds_read2_b32 v[76:77], v112 offset0:132 offset1:196
	ds_read2st64_b32 v[100:101], v115 offset0:4 offset1:5
	ds_read2st64_b32 v[130:131], v116 offset0:6 offset1:7
	ds_read2st64_b32 v[134:135], v117 offset0:8 offset1:9
	ds_read2st64_b32 v[136:137], v118 offset0:10 offset1:11
	ds_read2st64_b32 v[138:139], v119 offset0:12 offset1:13
	ds_read2st64_b32 v[140:141], v120 offset0:14 offset1:15
	ds_read2st64_b32 v[142:143], v121 offset0:16 offset1:17
	ds_read2st64_b32 v[144:145], v122 offset0:18 offset1:19
	ds_read2st64_b32 v[146:147], v123 offset0:20 offset1:21
	ds_read2st64_b32 v[148:149], v124 offset0:22 offset1:23
	ds_read2st64_b32 v[150:151], v125 offset0:24 offset1:25
	ds_read2st64_b32 v[152:153], v126 offset0:26 offset1:27
	ds_read2st64_b32 v[154:155], v127 offset0:28 offset1:29
	ds_read2st64_b32 v[156:157], v128 offset0:30 offset1:31
	s_waitcnt lgkmcnt(14)
	v_add_f32_e32 v160, v160, v74
	v_mul_f32_e32 v74, v32, v133
	v_fmac_f32_e32 v74, v33, v132
	v_add_f32_e32 v132, v74, v75
	v_mul_f32_e32 v74, v33, v132
	v_fma_f32 v74, v32, v160, -v74
	v_add_f32_e32 v76, v76, v74
	v_mul_f32_e32 v74, v32, v132
	v_fmac_f32_e32 v74, v33, v160
	v_add_f32_e32 v77, v77, v74
	v_mul_f32_e32 v74, v33, v77
	v_fma_f32 v74, v32, v76, -v74
	s_waitcnt lgkmcnt(13)
	v_add_f32_e32 v100, v100, v74
	v_mul_f32_e32 v74, v32, v77
	v_fmac_f32_e32 v74, v33, v76
	v_add_f32_e32 v101, v101, v74
	v_mul_f32_e32 v74, v33, v101
	v_fma_f32 v74, v32, v100, -v74
	s_waitcnt lgkmcnt(12)
	v_add_f32_e32 v130, v130, v74
	v_mul_f32_e32 v74, v32, v101
	v_fmac_f32_e32 v74, v33, v100
	v_add_f32_e32 v131, v131, v74
	v_mul_f32_e32 v74, v33, v131
	v_fma_f32 v74, v32, v130, -v74
	s_waitcnt lgkmcnt(11)
	v_add_f32_e32 v133, v134, v74
	v_mul_f32_e32 v74, v32, v131
	v_fmac_f32_e32 v74, v33, v130
	v_add_f32_e32 v134, v135, v74
	v_mul_f32_e32 v74, v33, v134
	v_fma_f32 v74, v32, v133, -v74
	s_waitcnt lgkmcnt(10)
	v_add_f32_e32 v135, v136, v74
	v_mul_f32_e32 v74, v32, v134
	v_fmac_f32_e32 v74, v33, v133
	v_add_f32_e32 v136, v137, v74
	v_mul_f32_e32 v74, v33, v136
	v_fma_f32 v74, v32, v135, -v74
	s_waitcnt lgkmcnt(9)
; __device__ __forceinline__ unsigned cvt_pk(float lo, float hi) { f32x2_t v = {lo, hi}; bf16x2_t b = __builtin_convertvector(v, bf16x2_t); return __builtin_bit_cast(unsigned, b); }
; __device__ __forceinline__ float bflo(unsigned w) { return __uint_as_float(w << 16); }
; __device__ __forceinline__ float bfhi(unsigned w) { return __uint_as_float(w & 0xffff0000u); }
; #define S5_LDS_FENCE() do { __builtin_amdgcn_wave_barrier(); asm volatile("s_waitcnt lgkmcnt(0)" ::: "memory"); } while (0)
; template <bool WRITEH>
; __device__ __forceinline__ void s5_block(const S5Coef& C, const bf16x8 (&bm)[8], u32x4 uw, float* Hs, int lane, float& hr, float& hi) {
;     ...
;     for (int tl = 0; tl < 16; ++tl) { bur[tl] = Hs[tl * 132 + lane]; bui[tl] = Hs[tl * 132 + 64 + lane]; }
; #pragma unroll
;     for (int tl = 0; tl < 16; ++tl) { const float nr = C.ar * hr - C.ai * hi + bur[tl], ni = C.ar * hi + C.ai * hr + bui[tl]; hr = nr; hi = ni; bur[tl] = hr; bui[tl] = hi; }
;     if (WRITEH) {
; #pragma unroll
;         for (int tl = 0; tl < 16; ++tl) { Hs[tl * 132 + lane] = bur[tl]; Hs[tl * 132 + 64 + lane] = bui[tl]; }
;     }
;     S5_LDS_FENCE();
; __device__ __forceinline__ void s5_unit(ArgsP A, int l, int unit, unsigned char* lds, int wave_, int lane_) {
;     ...
;             for (int ks = 0; ks < 4; ++ks) { const float* hp = Hs + (lane & 15) * 132 + 32 * ks + 8 * (lane >> 4); const f32x4 h0 = *(const f32x4*)hp, h1 = *(const f32x4*)(hp + 4);
;                 u32x4 wh; wh.x = cvt_pk(h0[0], h0[1]); wh.y = cvt_pk(h0[2], h0[3]); wh.z = cvt_pk(h1[0], h1[1]); wh.w = cvt_pk(h1[2], h1[3]);
;                 u32x4 wl; wl.x = cvt_pk(h0[0] - bflo(wh.x), h0[1] - bfhi(wh.x)); wl.y = cvt_pk(h0[2] - bflo(wh.y), h0[3] - bfhi(wh.y)); wl.z = cvt_pk(h1[0] - bflo(wh.z), h1[1] - bfhi(wh.z)); wl.w = cvt_pk(h1[2] - bflo(wh.w), h1[3] - bfhi(wh.w));
;                 const bf16x8 hh_ = __builtin_bit_cast(bf16x8, wh), hl_ = __builtin_bit_cast(bf16x8, wl);
;                 y = __builtin_amdgcn_mfma_f32_16x16x32_bf16(hh_, chl[2 * ks], y, 0, 0, 0); y2 = __builtin_amdgcn_mfma_f32_16x16x32_bf16(hh_, chl[2 * ks + 1], y2, 0, 0, 0);
;                 y2 = __builtin_amdgcn_mfma_f32_16x16x32_bf16(hl_, chl[2 * ks], y2, 0, 0, 0); }
	v_add_f32_e32 v137, v138, v74
	v_mul_f32_e32 v74, v32, v136
	v_fmac_f32_e32 v74, v33, v135
	v_add_f32_e32 v138, v139, v74
	v_mul_f32_e32 v74, v33, v138
	v_fma_f32 v74, v32, v137, -v74
	s_waitcnt lgkmcnt(8)
	v_add_f32_e32 v139, v140, v74
	v_mul_f32_e32 v74, v32, v138
	v_fmac_f32_e32 v74, v33, v137
	v_add_f32_e32 v140, v141, v74
	v_mul_f32_e32 v74, v33, v140
	v_fma_f32 v74, v32, v139, -v74
	s_waitcnt lgkmcnt(7)
	v_add_f32_e32 v141, v142, v74
	v_mul_f32_e32 v74, v32, v140
	v_fmac_f32_e32 v74, v33, v139
	v_add_f32_e32 v142, v143, v74
	v_mul_f32_e32 v74, v33, v142
	v_fma_f32 v74, v32, v141, -v74
	s_waitcnt lgkmcnt(6)
	v_add_f32_e32 v143, v144, v74
	v_mul_f32_e32 v74, v32, v142
	v_fmac_f32_e32 v74, v33, v141
	v_add_f32_e32 v144, v145, v74
	v_mul_f32_e32 v74, v33, v144
	v_fma_f32 v74, v32, v143, -v74
	s_waitcnt lgkmcnt(5)
	v_add_f32_e32 v145, v146, v74
	v_mul_f32_e32 v74, v32, v144
	v_fmac_f32_e32 v74, v33, v143
	v_add_f32_e32 v146, v147, v74
	v_mul_f32_e32 v74, v33, v146
	v_fma_f32 v74, v32, v145, -v74
	s_waitcnt lgkmcnt(4)
	v_add_f32_e32 v147, v148, v74
	v_mul_f32_e32 v74, v32, v146
	v_fmac_f32_e32 v74, v33, v145
	v_add_f32_e32 v148, v149, v74
	v_mul_f32_e32 v74, v33, v148
	v_fma_f32 v74, v32, v147, -v74
	s_waitcnt lgkmcnt(3)
	v_add_f32_e32 v149, v150, v74
	v_mul_f32_e32 v74, v32, v148
	v_fmac_f32_e32 v74, v33, v147
	v_add_f32_e32 v150, v151, v74
	v_mul_f32_e32 v74, v33, v150
	v_fma_f32 v74, v32, v149, -v74
	s_waitcnt lgkmcnt(2)
	v_add_f32_e32 v151, v152, v74
	v_mul_f32_e32 v74, v32, v150
	v_fmac_f32_e32 v74, v33, v149
	v_add_f32_e32 v152, v153, v74
	v_mul_f32_e32 v74, v33, v152
	v_fma_f32 v74, v32, v151, -v74
	s_waitcnt lgkmcnt(1)
	v_add_f32_e32 v153, v154, v74
	v_mul_f32_e32 v74, v32, v152
	v_fmac_f32_e32 v74, v33, v151
	v_add_f32_e32 v154, v155, v74
	v_mul_f32_e32 v74, v33, v154
	v_mul_f32_e32 v75, v32, v154
	v_fma_f32 v74, v32, v153, -v74
	v_fmac_f32_e32 v75, v33, v153
	s_waitcnt lgkmcnt(0)
	v_add_f32_e32 v74, v156, v74
	v_add_f32_e32 v75, v157, v75
	ds_write2st64_b32 v112, v160, v132 offset1:1
	ds_write2_b32 v112, v76, v77 offset0:132 offset1:196
	ds_write2st64_b32 v115, v100, v101 offset0:4 offset1:5
	ds_write2st64_b32 v116, v130, v131 offset0:6 offset1:7
	ds_write2st64_b32 v117, v133, v134 offset0:8 offset1:9
	ds_write2st64_b32 v118, v135, v136 offset0:10 offset1:11
	ds_write2st64_b32 v119, v137, v138 offset0:12 offset1:13
	ds_write2st64_b32 v120, v139, v140 offset0:14 offset1:15
	ds_write2st64_b32 v121, v141, v142 offset0:16 offset1:17
	ds_write2st64_b32 v122, v143, v144 offset0:18 offset1:19
	ds_write2st64_b32 v123, v145, v146 offset0:20 offset1:21
	ds_write2st64_b32 v124, v147, v148 offset0:22 offset1:23
	ds_write2st64_b32 v125, v149, v150 offset0:24 offset1:25
	ds_write2st64_b32 v126, v151, v152 offset0:26 offset1:27
	ds_write2st64_b32 v127, v153, v154 offset0:28 offset1:29
	ds_write2st64_b32 v128, v74, v75 offset0:30 offset1:31
	s_waitcnt lgkmcnt(0)
	ds_read_b128 v[130:133], v113
	ds_read_b128 v[134:137], v113 offset:16
	v_mul_f32_e32 v156, v33, v75
	v_fma_f32 v156, v32, v74, -v156
	s_waitcnt lgkmcnt(1)
	v_cvt_pk_bf16_f32 v138, v130, v131
	v_lshlrev_b32_e32 v76, 16, v138
	v_and_b32_e32 v77, 0xffff0000, v138
	v_cvt_pk_bf16_f32 v139, v132, v133
	v_pk_add_f32 v[76:77], v[130:131], v[76:77] neg_lo:[0,1] neg_hi:[0,1]
	s_waitcnt lgkmcnt(0)
	v_cvt_pk_bf16_f32 v140, v134, v135
	v_cvt_pk_bf16_f32 v130, v76, v77
	v_lshlrev_b32_e32 v76, 16, v139
	v_and_b32_e32 v77, 0xffff0000, v139
	v_pk_add_f32 v[76:77], v[132:133], v[76:77] neg_lo:[0,1] neg_hi:[0,1]
	v_cvt_pk_bf16_f32 v141, v136, v137
	v_cvt_pk_bf16_f32 v131, v76, v77
	v_lshlrev_b32_e32 v76, 16, v140
	v_and_b32_e32 v77, 0xffff0000, v140
	v_pk_add_f32 v[76:77], v[134:135], v[76:77] neg_lo:[0,1] neg_hi:[0,1]
	s_nop 0
	v_cvt_pk_bf16_f32 v132, v76, v77
	v_lshlrev_b32_e32 v76, 16, v141
	v_and_b32_e32 v77, 0xffff0000, v141
	v_pk_add_f32 v[76:77], v[136:137], v[76:77] neg_lo:[0,1] neg_hi:[0,1]
	v_mfma_f32_16x16x32_bf16 v[134:137], v[138:141], v[24:27], 0
	v_cvt_pk_bf16_f32 v133, v76, v77
	v_mfma_f32_16x16x32_bf16 v[138:141], v[138:141], v[28:31], 0
	s_nop 0
	v_mfma_f32_16x16x32_bf16 v[130:133], v[130:133], v[24:27], v[138:141]
	s_nop 5
	ds_read_b128 v[138:141], v113 offset:128
	ds_read_b128 v[142:145], v113 offset:144
	s_waitcnt lgkmcnt(1)
	v_cvt_pk_bf16_f32 v146, v138, v139
	v_lshlrev_b32_e32 v76, 16, v146
	v_and_b32_e32 v77, 0xffff0000, v146
	v_cvt_pk_bf16_f32 v147, v140, v141
	v_pk_add_f32 v[76:77], v[138:139], v[76:77] neg_lo:[0,1] neg_hi:[0,1]
	s_waitcnt lgkmcnt(0)
	v_cvt_pk_bf16_f32 v148, v142, v143
	v_cvt_pk_bf16_f32 v138, v76, v77
	v_lshlrev_b32_e32 v76, 16, v147
	v_and_b32_e32 v77, 0xffff0000, v147
	v_pk_add_f32 v[76:77], v[140:141], v[76:77] neg_lo:[0,1] neg_hi:[0,1]
	v_cvt_pk_bf16_f32 v149, v144, v145
	v_cvt_pk_bf16_f32 v139, v76, v77
	v_lshlrev_b32_e32 v76, 16, v148
	v_and_b32_e32 v77, 0xffff0000, v148
	v_pk_add_f32 v[76:77], v[142:143], v[76:77] neg_lo:[0,1] neg_hi:[0,1]
	v_mfma_f32_16x16x32_bf16 v[130:133], v[146:149], v[20:23], v[130:133]
	v_cvt_pk_bf16_f32 v140, v76, v77
	v_lshlrev_b32_e32 v76, 16, v149
	v_and_b32_e32 v77, 0xffff0000, v149
	v_pk_add_f32 v[76:77], v[144:145], v[76:77] neg_lo:[0,1] neg_hi:[0,1]
	v_mfma_f32_16x16x32_bf16 v[134:137], v[146:149], v[16:19], v[134:137]
	v_cvt_pk_bf16_f32 v141, v76, v77
	s_nop 1
	v_mfma_f32_16x16x32_bf16 v[130:133], v[138:141], v[16:19], v[130:133]
	ds_read_b128 v[138:141], v113 offset:256
	ds_read_b128 v[142:145], v113 offset:272
	s_waitcnt lgkmcnt(1)
	v_cvt_pk_bf16_f32 v146, v138, v139
	v_lshlrev_b32_e32 v76, 16, v146
	v_and_b32_e32 v77, 0xffff0000, v146
	v_cvt_pk_bf16_f32 v147, v140, v141
	v_pk_add_f32 v[76:77], v[138:139], v[76:77] neg_lo:[0,1] neg_hi:[0,1]
	s_waitcnt lgkmcnt(0)
; __device__ __forceinline__ unsigned cvt_pk(float lo, float hi) { f32x2_t v = {lo, hi}; bf16x2_t b = __builtin_convertvector(v, bf16x2_t); return __builtin_bit_cast(unsigned, b); }
; __device__ __forceinline__ float bf2f(unsigned short h) { return __uint_as_float(((unsigned)h) << 16); }
; __device__ __forceinline__ float bflo(unsigned w) { return __uint_as_float(w << 16); }
; __device__ __forceinline__ float bfhi(unsigned w) { return __uint_as_float(w & 0xffff0000u); }
; __device__ __forceinline__ unsigned short f2bf(float f) { return (unsigned short)(cvt_pk(f, 0.f) & 0xffffu); }
; template <bool WRITEH>
; __device__ __forceinline__ void s5_block(const S5Coef& C, const bf16x8 (&bm)[8], u32x4 uw, float* Hs, int lane, float& hr, float& hi) {
;     ...
;     for (int nb = 0; nb < 8; ++nb) { const f32x4 d = __builtin_amdgcn_mfma_f32_16x16x32_bf16(ua, bm[nb], (f32x4){0.f, 0.f, 0.f, 0.f}, 0, 0, 0);
; #pragma unroll
;         for (int i = 0; i < 4; ++i) Hs[(4 * (lane >> 4) + i) * 132 + 16 * nb + (lane & 15)] = d[i]; }
; __device__ __forceinline__ void s5_unit(ArgsP A, int l, int unit, unsigned char* lds, int wave_, int lane_) {
;     ...
;             for (int ks = 0; ks < 4; ++ks) { const float* hp = Hs + (lane & 15) * 132 + 32 * ks + 8 * (lane >> 4); const f32x4 h0 = *(const f32x4*)hp, h1 = *(const f32x4*)(hp + 4);
;                 u32x4 wh; wh.x = cvt_pk(h0[0], h0[1]); wh.y = cvt_pk(h0[2], h0[3]); wh.z = cvt_pk(h1[0], h1[1]); wh.w = cvt_pk(h1[2], h1[3]);
;                 u32x4 wl; wl.x = cvt_pk(h0[0] - bflo(wh.x), h0[1] - bfhi(wh.x)); wl.y = cvt_pk(h0[2] - bflo(wh.y), h0[3] - bfhi(wh.y)); wl.z = cvt_pk(h1[0] - bflo(wh.z), h1[1] - bfhi(wh.z)); wl.w = cvt_pk(h1[2] - bflo(wh.w), h1[3] - bfhi(wh.w));
;                 const bf16x8 hh_ = __builtin_bit_cast(bf16x8, wh), hl_ = __builtin_bit_cast(bf16x8, wl);
;                 y = __builtin_amdgcn_mfma_f32_16x16x32_bf16(hh_, chl[2 * ks], y, 0, 0, 0); y2 = __builtin_amdgcn_mfma_f32_16x16x32_bf16(hh_, chl[2 * ks + 1], y2, 0, 0, 0);
;                 y2 = __builtin_amdgcn_mfma_f32_16x16x32_bf16(hl_, chl[2 * ks], y2, 0, 0, 0); }
;             y = y + y2;
; #pragma unroll
;             for (int i = 0; i < 4; ++i) { const int t = 16 * blk + 4 * (lane >> 4) + i; const int col = 16 * g + (lane & 15);
;                 const float uval = bf2f(uraw[i]); const float v = gelu_tanh(y[i] + dv * uval); ys[t * YS_STRIDE + col] = f2bf(v); }
	v_cvt_pk_bf16_f32 v148, v142, v143
	v_cvt_pk_bf16_f32 v138, v76, v77
	v_lshlrev_b32_e32 v76, 16, v147
	v_and_b32_e32 v77, 0xffff0000, v147
	v_pk_add_f32 v[76:77], v[140:141], v[76:77] neg_lo:[0,1] neg_hi:[0,1]
	v_cvt_pk_bf16_f32 v149, v144, v145
	v_cvt_pk_bf16_f32 v139, v76, v77
	v_lshlrev_b32_e32 v76, 16, v148
	v_and_b32_e32 v77, 0xffff0000, v148
	v_pk_add_f32 v[76:77], v[142:143], v[76:77] neg_lo:[0,1] neg_hi:[0,1]
	v_mfma_f32_16x16x32_bf16 v[130:133], v[146:149], v[12:15], v[130:133]
	v_cvt_pk_bf16_f32 v140, v76, v77
	v_lshlrev_b32_e32 v76, 16, v149
	v_and_b32_e32 v77, 0xffff0000, v149
	v_pk_add_f32 v[76:77], v[144:145], v[76:77] neg_lo:[0,1] neg_hi:[0,1]
	v_mfma_f32_16x16x32_bf16 v[134:137], v[146:149], v[8:11], v[134:137]
	v_cvt_pk_bf16_f32 v141, v76, v77
	s_nop 1
	v_mfma_f32_16x16x32_bf16 v[130:133], v[138:141], v[8:11], v[130:133]
	ds_read_b128 v[138:141], v113 offset:384
	ds_read_b128 v[142:145], v113 offset:400
	s_waitcnt lgkmcnt(1)
	v_cvt_pk_bf16_f32 v146, v138, v139
	v_lshlrev_b32_e32 v76, 16, v146
	v_and_b32_e32 v77, 0xffff0000, v146
	v_cvt_pk_bf16_f32 v147, v140, v141
	v_pk_add_f32 v[76:77], v[138:139], v[76:77] neg_lo:[0,1] neg_hi:[0,1]
	s_waitcnt lgkmcnt(0)
	v_cvt_pk_bf16_f32 v148, v142, v143
	v_cvt_pk_bf16_f32 v138, v76, v77
	v_lshlrev_b32_e32 v76, 16, v147
	v_and_b32_e32 v77, 0xffff0000, v147
	v_pk_add_f32 v[76:77], v[140:141], v[76:77] neg_lo:[0,1] neg_hi:[0,1]
	v_cvt_pk_bf16_f32 v149, v144, v145
	v_cvt_pk_bf16_f32 v139, v76, v77
	v_lshlrev_b32_e32 v76, 16, v148
	v_and_b32_e32 v77, 0xffff0000, v148
	v_pk_add_f32 v[76:77], v[142:143], v[76:77] neg_lo:[0,1] neg_hi:[0,1]
	v_mfma_f32_16x16x32_bf16 v[130:133], v[146:149], v[4:7], v[130:133]
	v_cvt_pk_bf16_f32 v140, v76, v77
	v_lshlrev_b32_e32 v76, 16, v149
	v_and_b32_e32 v77, 0xffff0000, v149
	v_pk_add_f32 v[76:77], v[144:145], v[76:77] neg_lo:[0,1] neg_hi:[0,1]
	v_mfma_f32_16x16x32_bf16 v[134:137], v[146:149], v[0:3], v[134:137]
	v_cvt_pk_bf16_f32 v141, v76, v77
	s_nop 1
	v_mfma_f32_16x16x32_bf16 v[130:133], v[138:141], v[0:3], v[130:133]
	s_nop 7
	v_pk_add_f32 v[100:101], v[134:135], v[130:131]
	v_pk_add_f32 v[76:77], v[136:137], v[132:133]
	v_fma_f32 v100, v79, v103, v100
	v_mul_f32_e32 v103, 0x3d372713, v100
	v_mul_f32_e32 v103, v100, v103
	v_fma_f32 v103, v100, v103, v100
	v_mul_f32_e32 v103, 0x3f4c422a, v103
	v_add_f32_e32 v103, v103, v103
	v_mul_f32_e32 v103, 0x3fb8aa3b, v103
	v_exp_f32_e32 v103, v103
	v_mul_f32_e32 v100, 0.5, v100
	v_mfma_f32_16x16x32_bf16 v[130:133], v[70:73], v[62:65], 0
	v_add_f32_e32 v103, 1.0, v103
	v_rcp_f32_e32 v103, v103
	v_mfma_f32_16x16x32_bf16 v[62:65], v[66:69], v[62:65], 0
	v_fma_f32 v103, v103, -2.0, 1.0
	v_add_f32_e32 v103, 1.0, v103
	v_mul_f32_e32 v100, v100, v103
	v_cvt_pk_bf16_f32 v100, v100, s0
	ds_write_b16 v102, v100 offset:16640
	s_waitcnt vmcnt(2)
	v_lshlrev_b32_e32 v100, 16, v129
	v_fmac_f32_e32 v101, v79, v100
	v_mul_f32_e32 v100, 0x3d372713, v101
	v_mul_f32_e32 v100, v101, v100
	v_fma_f32 v100, v101, v100, v101
	v_mul_f32_e32 v100, 0x3f4c422a, v100
	v_add_f32_e32 v100, v100, v100
	v_mul_f32_e32 v100, 0x3fb8aa3b, v100
	v_exp_f32_e32 v100, v100
	v_mul_f32_e32 v101, 0.5, v101
	v_add_f32_e32 v100, 1.0, v100
	v_rcp_f32_e32 v100, v100
	s_nop 0
	v_fma_f32 v100, v100, -2.0, 1.0
	v_add_f32_e32 v100, 1.0, v100
	v_mul_f32_e32 v100, v101, v100
	v_cvt_pk_bf16_f32 v100, v100, s0
	ds_write_b16 v102, v100 offset:17680
	s_waitcnt vmcnt(1)
	v_lshlrev_b32_e32 v100, 16, v158
	v_fma_f32 v76, v79, v100, v76
	v_mul_f32_e32 v100, 0x3d372713, v76
	v_mul_f32_e32 v100, v76, v100
	v_fma_f32 v100, v76, v100, v76
	v_mul_f32_e32 v100, 0x3f4c422a, v100
	v_add_f32_e32 v100, v100, v100
	v_mul_f32_e32 v100, 0x3fb8aa3b, v100
	v_exp_f32_e32 v100, v100
	v_mul_f32_e32 v76, 0.5, v76
	v_add_f32_e32 v100, 1.0, v100
	v_rcp_f32_e32 v100, v100
	s_nop 0
	v_fma_f32 v100, v100, -2.0, 1.0
	v_add_f32_e32 v100, 1.0, v100
	v_mul_f32_e32 v76, v76, v100
	v_cvt_pk_bf16_f32 v76, v76, s0
	ds_write_b16 v102, v76 offset:18720
	s_waitcnt vmcnt(0)
	v_lshlrev_b32_e32 v76, 16, v159
	v_fmac_f32_e32 v77, v79, v76
	v_mul_f32_e32 v76, 0x3d372713, v77
	v_mul_f32_e32 v76, v77, v76
	v_fma_f32 v76, v77, v76, v77
	v_mul_f32_e32 v76, 0x3f4c422a, v76
	v_add_f32_e32 v76, v76, v76
	v_mul_f32_e32 v76, 0x3fb8aa3b, v76
	v_exp_f32_e32 v76, v76
	v_mul_f32_e32 v77, 0.5, v77
	v_add_f32_e32 v76, 1.0, v76
	v_rcp_f32_e32 v76, v76
	s_nop 0
	v_fma_f32 v76, v76, -2.0, 1.0
	v_add_f32_e32 v76, 1.0, v76
	v_mul_f32_e32 v76, v77, v76
	v_cvt_pk_bf16_f32 v76, v76, s0
	ds_write_b16 v102, v76 offset:19760
	s_waitcnt lgkmcnt(0)
; #define S5_LDS_FENCE() do { __builtin_amdgcn_wave_barrier(); asm volatile("s_waitcnt lgkmcnt(0)" ::: "memory"); } while (0)
; template <bool WRITEH>
; __device__ __forceinline__ void s5_block(const S5Coef& C, const bf16x8 (&bm)[8], u32x4 uw, float* Hs, int lane, float& hr, float& hi) {
;     ...
;     for (int nb = 0; nb < 8; ++nb) { const f32x4 d = __builtin_amdgcn_mfma_f32_16x16x32_bf16(ua, bm[nb], (f32x4){0.f, 0.f, 0.f, 0.f}, 0, 0, 0);
; #pragma unroll
;         for (int i = 0; i < 4; ++i) Hs[(4 * (lane >> 4) + i) * 132 + 16 * nb + (lane & 15)] = d[i]; }
;     S5_LDS_FENCE();
;     float bur[16], bui[16];
; #pragma unroll
;     for (int tl = 0; tl < 16; ++tl) { bur[tl] = Hs[tl * 132 + lane]; bui[tl] = Hs[tl * 132 + 64 + lane]; }
; #pragma unroll
;     for (int tl = 0; tl < 16; ++tl) { const float nr = C.ar * hr - C.ai * hi + bur[tl], ni = C.ar * hi + C.ai * hr + bui[tl]; hr = nr; hi = ni; bur[tl] = hr; bui[tl] = hi; }
; __device__ __forceinline__ void s5_unit(ArgsP A, int l, int unit, unsigned char* lds, int wave_, int lane_) {
;     ...
;             for (int i = 0; i < 4; ++i) uraw[i] = PROJ[(size_t)(rowbase + 16 * blk + 4 * (lane >> 4) + i) * INWP + C_S5 + 16 * g + (lane & 15)];
	ds_write_b32 v106, v130
	ds_write_b32 v106, v131 offset:528
	ds_write_b32 v106, v132 offset:1056
	ds_write_b32 v107, v133
	v_mfma_f32_16x16x32_bf16 v[130:133], v[70:73], v[58:61], 0
	s_nop 7
	ds_write_b32 v106, v130 offset:64
	ds_write_b32 v106, v131 offset:592
	ds_write_b32 v106, v132 offset:1120
	ds_write_b32 v107, v133 offset:64
	v_mfma_f32_16x16x32_bf16 v[130:133], v[70:73], v[54:57], 0
	s_nop 7
	ds_write_b32 v106, v130 offset:128
	ds_write_b32 v106, v131 offset:656
	ds_write_b32 v106, v132 offset:1184
	ds_write_b32 v107, v133 offset:128
	v_mfma_f32_16x16x32_bf16 v[130:133], v[70:73], v[50:53], 0
	s_nop 7
	ds_write2_b32 v108, v130, v131 offset1:132
	ds_write_b32 v108, v132 offset:1056
	ds_write_b32 v109, v133
	v_mfma_f32_16x16x32_bf16 v[130:133], v[70:73], v[46:49], 0
	s_nop 7
	ds_write_b32 v106, v130 offset:256
	ds_write_b32 v106, v131 offset:784
	ds_write_b32 v106, v132 offset:1312
	ds_write_b32 v107, v133 offset:256
	v_mfma_f32_16x16x32_bf16 v[130:133], v[70:73], v[42:45], 0
	s_nop 7
	ds_write_b32 v106, v130 offset:320
	ds_write_b32 v106, v131 offset:848
	ds_write_b32 v106, v132 offset:1376
	ds_write_b32 v107, v133 offset:320
	v_mfma_f32_16x16x32_bf16 v[130:133], v[70:73], v[38:41], 0
	v_lshl_add_u64 v[76:77], s[2:3], 0, v[82:83]
	s_nop 6
	ds_write_b32 v106, v130 offset:384
	ds_write_b32 v106, v131 offset:912
	ds_write_b32 v106, v132 offset:1440
	ds_write_b32 v107, v133 offset:384
	v_mfma_f32_16x16x32_bf16 v[70:73], v[70:73], v[34:37], 0
	s_nop 7
	ds_write2_b32 v110, v70, v71 offset1:132
	ds_write_b32 v110, v72 offset:1056
	ds_write_b32 v111, v73
	v_add_co_u32_e32 v70, vcc, s12, v76
	v_mfma_f32_16x16x32_bf16 v[58:61], v[66:69], v[58:61], 0
	s_nop 0
	v_addc_co_u32_e32 v71, vcc, 0, v77, vcc
	global_load_ushort v103, v[70:71], off
	v_add_co_u32_e32 v70, vcc, s13, v76
	v_mfma_f32_16x16x32_bf16 v[54:57], v[66:69], v[54:57], 0
	s_nop 0
	v_addc_co_u32_e32 v71, vcc, 0, v77, vcc
	global_load_ushort v129, v[70:71], off offset:512
	v_add_co_u32_e32 v70, vcc, s33, v76
	v_mfma_f32_16x16x32_bf16 v[50:53], v[66:69], v[50:53], 0
	s_nop 0
	v_addc_co_u32_e32 v71, vcc, 0, v77, vcc
	global_load_ushort v154, v[70:71], off offset:1024
	v_add_co_u32_e32 v70, vcc, s28, v76
	v_mfma_f32_16x16x32_bf16 v[46:49], v[66:69], v[46:49], 0
	s_nop 0
	v_addc_co_u32_e32 v71, vcc, 0, v77, vcc
	global_load_ushort v155, v[70:71], off offset:1536
	s_waitcnt lgkmcnt(0)
	ds_read2st64_b32 v[70:71], v112 offset1:1
	ds_read2_b32 v[72:73], v112 offset0:132 offset1:196
	ds_read2st64_b32 v[76:77], v115 offset0:4 offset1:5
	ds_read2st64_b32 v[100:101], v116 offset0:6 offset1:7
	ds_read2st64_b32 v[130:131], v117 offset0:8 offset1:9
	ds_read2st64_b32 v[132:133], v118 offset0:10 offset1:11
	ds_read2st64_b32 v[134:135], v119 offset0:12 offset1:13
	ds_read2st64_b32 v[136:137], v120 offset0:14 offset1:15
	ds_read2st64_b32 v[138:139], v121 offset0:16 offset1:17
	ds_read2st64_b32 v[140:141], v122 offset0:18 offset1:19
	ds_read2st64_b32 v[142:143], v123 offset0:20 offset1:21
	ds_read2st64_b32 v[144:145], v124 offset0:22 offset1:23
	ds_read2st64_b32 v[146:147], v125 offset0:24 offset1:25
	ds_read2st64_b32 v[148:149], v126 offset0:26 offset1:27
	ds_read2st64_b32 v[150:151], v127 offset0:28 offset1:29
	ds_read2st64_b32 v[152:153], v128 offset0:30 offset1:31
	s_waitcnt lgkmcnt(14)
	v_add_f32_e32 v156, v156, v70
	v_mul_f32_e32 v70, v32, v75
	v_fmac_f32_e32 v70, v33, v74
	v_add_f32_e32 v74, v70, v71
	v_mul_f32_e32 v70, v33, v74
	v_fma_f32 v70, v32, v156, -v70
	v_add_f32_e32 v72, v72, v70
	v_mul_f32_e32 v70, v32, v74
	v_fmac_f32_e32 v70, v33, v156
	v_add_f32_e32 v73, v73, v70
	v_mul_f32_e32 v70, v33, v73
	v_fma_f32 v70, v32, v72, -v70
	s_waitcnt lgkmcnt(13)
	v_add_f32_e32 v75, v76, v70
	v_mul_f32_e32 v70, v32, v73
	v_fmac_f32_e32 v70, v33, v72
	v_add_f32_e32 v76, v77, v70
	v_mul_f32_e32 v70, v33, v76
	v_fma_f32 v70, v32, v75, -v70
	s_waitcnt lgkmcnt(12)
	v_add_f32_e32 v77, v100, v70
	v_mul_f32_e32 v70, v32, v76
	v_fmac_f32_e32 v70, v33, v75
	v_add_f32_e32 v100, v101, v70
	v_mul_f32_e32 v70, v33, v100
	v_fma_f32 v70, v32, v77, -v70
	s_waitcnt lgkmcnt(11)
	v_add_f32_e32 v101, v130, v70
	v_mul_f32_e32 v70, v32, v100
	v_fmac_f32_e32 v70, v33, v77
	v_add_f32_e32 v130, v131, v70
	v_mul_f32_e32 v70, v33, v130
	v_fma_f32 v70, v32, v101, -v70
	s_waitcnt lgkmcnt(10)
	v_add_f32_e32 v131, v132, v70
	v_mul_f32_e32 v70, v32, v130
	v_fmac_f32_e32 v70, v33, v101
	v_add_f32_e32 v132, v133, v70
	v_mul_f32_e32 v70, v33, v132
	v_fma_f32 v70, v32, v131, -v70
	s_waitcnt lgkmcnt(9)
	v_add_f32_e32 v133, v134, v70
	v_mul_f32_e32 v70, v32, v132
	v_fmac_f32_e32 v70, v33, v131
	v_add_f32_e32 v134, v135, v70
	v_mul_f32_e32 v70, v33, v134
	v_fma_f32 v70, v32, v133, -v70
	s_waitcnt lgkmcnt(8)
	v_add_f32_e32 v135, v136, v70
	v_mul_f32_e32 v70, v32, v134
	v_fmac_f32_e32 v70, v33, v133
	v_add_f32_e32 v136, v137, v70
	v_mul_f32_e32 v70, v33, v136
	v_fma_f32 v70, v32, v135, -v70
	s_waitcnt lgkmcnt(7)
	v_add_f32_e32 v137, v138, v70
	v_mul_f32_e32 v70, v32, v136
	v_fmac_f32_e32 v70, v33, v135
	v_add_f32_e32 v138, v139, v70
	v_mul_f32_e32 v70, v33, v138
	v_fma_f32 v70, v32, v137, -v70
	s_waitcnt lgkmcnt(6)
	v_add_f32_e32 v139, v140, v70
	v_mul_f32_e32 v70, v32, v138
	v_fmac_f32_e32 v70, v33, v137
	v_add_f32_e32 v140, v141, v70
	v_mul_f32_e32 v70, v33, v140
	v_fma_f32 v70, v32, v139, -v70
	s_waitcnt lgkmcnt(5)
	v_add_f32_e32 v141, v142, v70
	v_mul_f32_e32 v70, v32, v140
	v_fmac_f32_e32 v70, v33, v139
	v_add_f32_e32 v142, v143, v70
	v_mul_f32_e32 v70, v33, v142
	v_fma_f32 v70, v32, v141, -v70
	s_waitcnt lgkmcnt(4)
	v_add_f32_e32 v143, v144, v70
	v_mul_f32_e32 v70, v32, v142
	v_fmac_f32_e32 v70, v33, v141
	v_add_f32_e32 v144, v145, v70
	v_mul_f32_e32 v70, v33, v144
	v_fma_f32 v70, v32, v143, -v70
	s_waitcnt lgkmcnt(3)
; __device__ __forceinline__ unsigned cvt_pk(float lo, float hi) { f32x2_t v = {lo, hi}; bf16x2_t b = __builtin_convertvector(v, bf16x2_t); return __builtin_bit_cast(unsigned, b); }
; __device__ __forceinline__ float bflo(unsigned w) { return __uint_as_float(w << 16); }
; __device__ __forceinline__ float bfhi(unsigned w) { return __uint_as_float(w & 0xffff0000u); }
; #define S5_LDS_FENCE() do { __builtin_amdgcn_wave_barrier(); asm volatile("s_waitcnt lgkmcnt(0)" ::: "memory"); } while (0)
; template <bool WRITEH>
; __device__ __forceinline__ void s5_block(const S5Coef& C, const bf16x8 (&bm)[8], u32x4 uw, float* Hs, int lane, float& hr, float& hi) {
;     ...
;     for (int tl = 0; tl < 16; ++tl) { const float nr = C.ar * hr - C.ai * hi + bur[tl], ni = C.ar * hi + C.ai * hr + bui[tl]; hr = nr; hi = ni; bur[tl] = hr; bui[tl] = hi; }
;     if (WRITEH) {
; #pragma unroll
;         for (int tl = 0; tl < 16; ++tl) { Hs[tl * 132 + lane] = bur[tl]; Hs[tl * 132 + 64 + lane] = bui[tl]; }
;     }
;     S5_LDS_FENCE();
; __device__ __forceinline__ void s5_unit(ArgsP A, int l, int unit, unsigned char* lds, int wave_, int lane_) {
;     ...
;             for (int ks = 0; ks < 4; ++ks) { const float* hp = Hs + (lane & 15) * 132 + 32 * ks + 8 * (lane >> 4); const f32x4 h0 = *(const f32x4*)hp, h1 = *(const f32x4*)(hp + 4);
;                 u32x4 wh; wh.x = cvt_pk(h0[0], h0[1]); wh.y = cvt_pk(h0[2], h0[3]); wh.z = cvt_pk(h1[0], h1[1]); wh.w = cvt_pk(h1[2], h1[3]);
;                 u32x4 wl; wl.x = cvt_pk(h0[0] - bflo(wh.x), h0[1] - bfhi(wh.x)); wl.y = cvt_pk(h0[2] - bflo(wh.y), h0[3] - bfhi(wh.y)); wl.z = cvt_pk(h1[0] - bflo(wh.z), h1[1] - bfhi(wh.z)); wl.w = cvt_pk(h1[2] - bflo(wh.w), h1[3] - bfhi(wh.w));
;                 const bf16x8 hh_ = __builtin_bit_cast(bf16x8, wh), hl_ = __builtin_bit_cast(bf16x8, wl);
;                 y = __builtin_amdgcn_mfma_f32_16x16x32_bf16(hh_, chl[2 * ks], y, 0, 0, 0); y2 = __builtin_amdgcn_mfma_f32_16x16x32_bf16(hh_, chl[2 * ks + 1], y2, 0, 0, 0);
;                 y2 = __builtin_amdgcn_mfma_f32_16x16x32_bf16(hl_, chl[2 * ks], y2, 0, 0, 0); }
	v_add_f32_e32 v145, v146, v70
	v_mul_f32_e32 v70, v32, v144
	v_fmac_f32_e32 v70, v33, v143
	v_add_f32_e32 v146, v147, v70
	v_mul_f32_e32 v70, v33, v146
	v_fma_f32 v70, v32, v145, -v70
	s_waitcnt lgkmcnt(2)
	v_add_f32_e32 v147, v148, v70
	v_mul_f32_e32 v70, v32, v146
	v_fmac_f32_e32 v70, v33, v145
	v_add_f32_e32 v148, v149, v70
	v_mul_f32_e32 v70, v33, v148
	v_fma_f32 v70, v32, v147, -v70
	s_waitcnt lgkmcnt(1)
	v_add_f32_e32 v149, v150, v70
	v_mul_f32_e32 v70, v32, v148
	v_fmac_f32_e32 v70, v33, v147
	v_add_f32_e32 v150, v151, v70
	v_mul_f32_e32 v70, v33, v150
	v_mul_f32_e32 v71, v32, v150
	v_fma_f32 v70, v32, v149, -v70
	v_fmac_f32_e32 v71, v33, v149
	s_waitcnt lgkmcnt(0)
	v_add_f32_e32 v70, v152, v70
	v_add_f32_e32 v71, v153, v71
	ds_write2st64_b32 v112, v156, v74 offset1:1
	ds_write2_b32 v112, v72, v73 offset0:132 offset1:196
	ds_write2st64_b32 v115, v75, v76 offset0:4 offset1:5
	ds_write2st64_b32 v116, v77, v100 offset0:6 offset1:7
	ds_write2st64_b32 v117, v101, v130 offset0:8 offset1:9
	ds_write2st64_b32 v118, v131, v132 offset0:10 offset1:11
	ds_write2st64_b32 v119, v133, v134 offset0:12 offset1:13
	ds_write2st64_b32 v120, v135, v136 offset0:14 offset1:15
	ds_write2st64_b32 v121, v137, v138 offset0:16 offset1:17
	ds_write2st64_b32 v122, v139, v140 offset0:18 offset1:19
	ds_write2st64_b32 v123, v141, v142 offset0:20 offset1:21
	ds_write2st64_b32 v124, v143, v144 offset0:22 offset1:23
	ds_write2st64_b32 v125, v145, v146 offset0:24 offset1:25
	ds_write2st64_b32 v126, v147, v148 offset0:26 offset1:27
	ds_write2st64_b32 v127, v149, v150 offset0:28 offset1:29
	ds_write2st64_b32 v128, v70, v71 offset0:30 offset1:31
	s_waitcnt lgkmcnt(0)
	ds_read_b128 v[72:75], v113
	ds_read_b128 v[130:133], v113 offset:16
	v_mfma_f32_16x16x32_bf16 v[42:45], v[66:69], v[42:45], 0
	v_lshl_add_u64 v[82:83], v[82:83], 0, 32
	s_waitcnt lgkmcnt(1)
	v_cvt_pk_bf16_f32 v134, v72, v73
	v_cvt_pk_bf16_f32 v135, v74, v75
	v_lshlrev_b32_e32 v76, 16, v134
	v_and_b32_e32 v77, 0xffff0000, v134
	s_waitcnt lgkmcnt(0)
	v_cvt_pk_bf16_f32 v136, v130, v131
	v_cvt_pk_bf16_f32 v137, v132, v133
	v_pk_add_f32 v[72:73], v[72:73], v[76:77] neg_lo:[0,1] neg_hi:[0,1]
	v_lshlrev_b32_e32 v76, 16, v135
	v_and_b32_e32 v77, 0xffff0000, v135
	v_pk_add_f32 v[74:75], v[74:75], v[76:77] neg_lo:[0,1] neg_hi:[0,1]
	v_cvt_pk_bf16_f32 v72, v72, v73
	v_cvt_pk_bf16_f32 v73, v74, v75
	v_lshlrev_b32_e32 v74, 16, v136
	v_and_b32_e32 v75, 0xffff0000, v136
	v_lshlrev_b32_e32 v76, 16, v137
	v_and_b32_e32 v77, 0xffff0000, v137
	v_pk_add_f32 v[74:75], v[130:131], v[74:75] neg_lo:[0,1] neg_hi:[0,1]
	v_pk_add_f32 v[76:77], v[132:133], v[76:77] neg_lo:[0,1] neg_hi:[0,1]
	v_cvt_pk_bf16_f32 v74, v74, v75
	v_cvt_pk_bf16_f32 v75, v76, v77
	v_mfma_f32_16x16x32_bf16 v[130:133], v[134:137], v[24:27], 0
	v_mfma_f32_16x16x32_bf16 v[134:137], v[134:137], v[28:31], 0
	v_mfma_f32_16x16x32_bf16 v[72:75], v[72:75], v[24:27], v[134:137]
	s_nop 6
	ds_read_b128 v[134:137], v113 offset:128
	ds_read_b128 v[138:141], v113 offset:144
	s_waitcnt lgkmcnt(1)
	v_cvt_pk_bf16_f32 v142, v134, v135
	v_lshlrev_b32_e32 v76, 16, v142
	v_and_b32_e32 v77, 0xffff0000, v142
	v_cvt_pk_bf16_f32 v143, v136, v137
	v_pk_add_f32 v[76:77], v[134:135], v[76:77] neg_lo:[0,1] neg_hi:[0,1]
	s_waitcnt lgkmcnt(0)
	v_cvt_pk_bf16_f32 v144, v138, v139
	v_cvt_pk_bf16_f32 v134, v76, v77
	v_lshlrev_b32_e32 v76, 16, v143
	v_and_b32_e32 v77, 0xffff0000, v143
	v_pk_add_f32 v[76:77], v[136:137], v[76:77] neg_lo:[0,1] neg_hi:[0,1]
	v_cvt_pk_bf16_f32 v145, v140, v141
	v_cvt_pk_bf16_f32 v135, v76, v77
	v_lshlrev_b32_e32 v76, 16, v144
	v_and_b32_e32 v77, 0xffff0000, v144
	v_pk_add_f32 v[76:77], v[138:139], v[76:77] neg_lo:[0,1] neg_hi:[0,1]
	v_mfma_f32_16x16x32_bf16 v[72:75], v[142:145], v[20:23], v[72:75]
	v_cvt_pk_bf16_f32 v136, v76, v77
	v_lshlrev_b32_e32 v76, 16, v145
	v_and_b32_e32 v77, 0xffff0000, v145
	v_pk_add_f32 v[76:77], v[140:141], v[76:77] neg_lo:[0,1] neg_hi:[0,1]
	v_mfma_f32_16x16x32_bf16 v[130:133], v[142:145], v[16:19], v[130:133]
	v_cvt_pk_bf16_f32 v137, v76, v77
	s_nop 1
	v_mfma_f32_16x16x32_bf16 v[72:75], v[134:137], v[16:19], v[72:75]
	ds_read_b128 v[134:137], v113 offset:256
	ds_read_b128 v[138:141], v113 offset:272
	s_waitcnt lgkmcnt(1)
	v_cvt_pk_bf16_f32 v142, v134, v135
	v_lshlrev_b32_e32 v76, 16, v142
	v_and_b32_e32 v77, 0xffff0000, v142
	v_cvt_pk_bf16_f32 v143, v136, v137
	v_pk_add_f32 v[76:77], v[134:135], v[76:77] neg_lo:[0,1] neg_hi:[0,1]
	s_waitcnt lgkmcnt(0)
	v_cvt_pk_bf16_f32 v144, v138, v139
	v_cvt_pk_bf16_f32 v134, v76, v77
	v_lshlrev_b32_e32 v76, 16, v143
	v_and_b32_e32 v77, 0xffff0000, v143
	v_pk_add_f32 v[76:77], v[136:137], v[76:77] neg_lo:[0,1] neg_hi:[0,1]
	v_cvt_pk_bf16_f32 v145, v140, v141
	v_cvt_pk_bf16_f32 v135, v76, v77
	v_lshlrev_b32_e32 v76, 16, v144
	v_and_b32_e32 v77, 0xffff0000, v144
	v_pk_add_f32 v[76:77], v[138:139], v[76:77] neg_lo:[0,1] neg_hi:[0,1]
	v_mfma_f32_16x16x32_bf16 v[72:75], v[142:145], v[12:15], v[72:75]
	v_cvt_pk_bf16_f32 v136, v76, v77
	v_lshlrev_b32_e32 v76, 16, v145
	v_and_b32_e32 v77, 0xffff0000, v145
	v_pk_add_f32 v[76:77], v[140:141], v[76:77] neg_lo:[0,1] neg_hi:[0,1]
	v_mfma_f32_16x16x32_bf16 v[130:133], v[142:145], v[8:11], v[130:133]
	v_cvt_pk_bf16_f32 v137, v76, v77
	s_nop 1
	v_mfma_f32_16x16x32_bf16 v[72:75], v[134:137], v[8:11], v[72:75]
	ds_read_b128 v[134:137], v113 offset:384
	ds_read_b128 v[138:141], v113 offset:400
	s_waitcnt lgkmcnt(1)
	v_cvt_pk_bf16_f32 v142, v134, v135
	v_lshlrev_b32_e32 v76, 16, v142
	v_and_b32_e32 v77, 0xffff0000, v142
	v_cvt_pk_bf16_f32 v143, v136, v137
	v_pk_add_f32 v[76:77], v[134:135], v[76:77] neg_lo:[0,1] neg_hi:[0,1]
	s_waitcnt lgkmcnt(0)
; __device__ __forceinline__ float bf2f(unsigned short h) { return __uint_as_float(((unsigned)h) << 16); }
; __device__ __forceinline__ unsigned short f2bf(float f) { return (unsigned short)(cvt_pk(f, 0.f) & 0xffffu); }
; #define S5_LDS_FENCE() do { __builtin_amdgcn_wave_barrier(); asm volatile("s_waitcnt lgkmcnt(0)" ::: "memory"); } while (0)
; template <bool WRITEH>
; __device__ __forceinline__ void s5_block(const S5Coef& C, const bf16x8 (&bm)[8], u32x4 uw, float* Hs, int lane, float& hr, float& hi) {
;     ...
;     for (int nb = 0; nb < 8; ++nb) { const f32x4 d = __builtin_amdgcn_mfma_f32_16x16x32_bf16(ua, bm[nb], (f32x4){0.f, 0.f, 0.f, 0.f}, 0, 0, 0);
; #pragma unroll
;         for (int i = 0; i < 4; ++i) Hs[(4 * (lane >> 4) + i) * 132 + 16 * nb + (lane & 15)] = d[i]; }
;     S5_LDS_FENCE();
;     float bur[16], bui[16];
; #pragma unroll
;     for (int tl = 0; tl < 16; ++tl) { bur[tl] = Hs[tl * 132 + lane]; bui[tl] = Hs[tl * 132 + 64 + lane]; }
; #pragma unroll
;     for (int tl = 0; tl < 16; ++tl) { const float nr = C.ar * hr - C.ai * hi + bur[tl], ni = C.ar * hi + C.ai * hr + bui[tl]; hr = nr; hi = ni; bur[tl] = hr; bui[tl] = hi; }
; __device__ __forceinline__ void s5_unit(ArgsP A, int l, int unit, unsigned char* lds, int wave_, int lane_) {
;     ...
;                 y = __builtin_amdgcn_mfma_f32_16x16x32_bf16(hh_, chl[2 * ks], y, 0, 0, 0); y2 = __builtin_amdgcn_mfma_f32_16x16x32_bf16(hh_, chl[2 * ks + 1], y2, 0, 0, 0);
;                 y2 = __builtin_amdgcn_mfma_f32_16x16x32_bf16(hl_, chl[2 * ks], y2, 0, 0, 0); }
;             y = y + y2;
; #pragma unroll
;             for (int i = 0; i < 4; ++i) { const int t = 16 * blk + 4 * (lane >> 4) + i; const int col = 16 * g + (lane & 15);
;                 const float uval = bf2f(uraw[i]); const float v = gelu_tanh(y[i] + dv * uval); ys[t * YS_STRIDE + col] = f2bf(v); }
;             __builtin_amdgcn_wave_barrier(); asm volatile("s_waitcnt lgkmcnt(0)" ::: "memory");
	v_cvt_pk_bf16_f32 v144, v138, v139
	v_cvt_pk_bf16_f32 v134, v76, v77
	v_lshlrev_b32_e32 v76, 16, v143
	v_and_b32_e32 v77, 0xffff0000, v143
	v_pk_add_f32 v[76:77], v[136:137], v[76:77] neg_lo:[0,1] neg_hi:[0,1]
	v_cvt_pk_bf16_f32 v145, v140, v141
	v_cvt_pk_bf16_f32 v135, v76, v77
	v_lshlrev_b32_e32 v76, 16, v144
	v_and_b32_e32 v77, 0xffff0000, v144
	v_pk_add_f32 v[76:77], v[138:139], v[76:77] neg_lo:[0,1] neg_hi:[0,1]
	v_mfma_f32_16x16x32_bf16 v[72:75], v[142:145], v[4:7], v[72:75]
	v_cvt_pk_bf16_f32 v136, v76, v77
	v_lshlrev_b32_e32 v76, 16, v145
	v_and_b32_e32 v77, 0xffff0000, v145
	v_pk_add_f32 v[76:77], v[140:141], v[76:77] neg_lo:[0,1] neg_hi:[0,1]
	v_mfma_f32_16x16x32_bf16 v[130:133], v[142:145], v[0:3], v[130:133]
	v_cvt_pk_bf16_f32 v137, v76, v77
	s_waitcnt vmcnt(3)
	v_lshlrev_b32_e32 v76, 16, v103
	v_mfma_f32_16x16x32_bf16 v[72:75], v[134:137], v[0:3], v[72:75]
	v_mfma_f32_16x16x32_bf16 v[38:41], v[66:69], v[38:41], 0
	s_nop 6
	v_add_f32_e64 v72, v130, v72
	v_add_f32_e64 v73, v131, v73
	v_pk_add_f32 v[74:75], v[132:133], v[74:75]
	v_fma_f32 v72, v79, v76, v72
	v_mul_f32_e32 v76, 0x3d372713, v72
	v_mul_f32_e32 v76, v72, v76
	v_fma_f32 v76, v72, v76, v72
	v_mul_f32_e32 v76, 0x3f4c422a, v76
	v_add_f32_e32 v76, v76, v76
	v_mul_f32_e32 v76, 0x3fb8aa3b, v76
	v_exp_f32_e32 v76, v76
	v_mul_f32_e32 v72, 0.5, v72
	v_mfma_f32_16x16x32_bf16 v[34:37], v[66:69], v[34:37], 0
	v_add_f32_e32 v76, 1.0, v76
	v_rcp_f32_e32 v76, v76
	s_nop 0
	v_fma_f32 v76, v76, -2.0, 1.0
	v_add_f32_e32 v76, 1.0, v76
	v_mul_f32_e32 v72, v72, v76
	v_cvt_pk_bf16_f32 v72, v72, s0
	ds_write_b16 v102, v72 offset:33280
	s_waitcnt vmcnt(2)
	v_lshlrev_b32_e32 v72, 16, v129
	v_fmac_f32_e32 v73, v79, v72
	v_mul_f32_e32 v72, 0x3d372713, v73
	v_mul_f32_e32 v72, v73, v72
	v_fma_f32 v72, v73, v72, v73
	v_mul_f32_e32 v72, 0x3f4c422a, v72
	v_add_f32_e32 v72, v72, v72
	v_mul_f32_e32 v72, 0x3fb8aa3b, v72
	v_exp_f32_e32 v72, v72
	v_mul_f32_e32 v73, 0.5, v73
	v_add_f32_e32 v72, 1.0, v72
	v_rcp_f32_e32 v72, v72
	s_nop 0
	v_fma_f32 v72, v72, -2.0, 1.0
	v_add_f32_e32 v72, 1.0, v72
	v_mul_f32_e32 v72, v73, v72
	v_cvt_pk_bf16_f32 v72, v72, s0
	ds_write_b16 v102, v72 offset:34320
	s_waitcnt vmcnt(1)
	v_lshlrev_b32_e32 v72, 16, v154
	v_fma_f32 v72, v79, v72, v74
	v_mul_f32_e32 v73, 0x3d372713, v72
	v_mul_f32_e32 v73, v72, v73
	v_fma_f32 v73, v72, v73, v72
	v_mul_f32_e32 v73, 0x3f4c422a, v73
	v_add_f32_e32 v73, v73, v73
	v_mul_f32_e32 v73, 0x3fb8aa3b, v73
	v_exp_f32_e32 v73, v73
	v_mul_f32_e32 v72, 0.5, v72
	v_add_f32_e32 v73, 1.0, v73
	v_rcp_f32_e32 v73, v73
	s_nop 0
	v_fma_f32 v73, v73, -2.0, 1.0
	v_add_f32_e32 v73, 1.0, v73
	v_mul_f32_e32 v72, v72, v73
	v_cvt_pk_bf16_f32 v72, v72, s0
	ds_write_b16 v102, v72 offset:35360
	s_waitcnt vmcnt(0)
	v_lshlrev_b32_e32 v72, 16, v155
	v_fmac_f32_e32 v75, v79, v72
	v_mul_f32_e32 v72, 0x3d372713, v75
	v_mul_f32_e32 v72, v75, v72
	v_fma_f32 v72, v75, v72, v75
	v_mul_f32_e32 v72, 0x3f4c422a, v72
	v_add_f32_e32 v72, v72, v72
	v_mul_f32_e32 v72, 0x3fb8aa3b, v72
	v_exp_f32_e32 v72, v72
	v_mul_f32_e32 v73, 0.5, v75
	v_add_f32_e32 v72, 1.0, v72
	v_rcp_f32_e32 v72, v72
	s_nop 0
	v_fma_f32 v72, v72, -2.0, 1.0
	v_add_f32_e32 v72, 1.0, v72
	v_mul_f32_e32 v72, v73, v72
	v_cvt_pk_bf16_f32 v72, v72, s0
	ds_write_b16 v102, v72 offset:36400
	v_lshl_add_u64 v[72:73], s[2:3], 0, v[80:81]
	s_waitcnt lgkmcnt(0)
	ds_write_b32 v106, v62
	ds_write_b32 v106, v63 offset:528
	ds_write_b32 v106, v64 offset:1056
	ds_write_b32 v107, v65
	ds_write_b32 v106, v58 offset:64
	ds_write_b32 v106, v59 offset:592
	ds_write_b32 v106, v60 offset:1120
	ds_write_b32 v107, v61 offset:64
	ds_write_b32 v106, v54 offset:128
	ds_write_b32 v106, v55 offset:656
	ds_write_b32 v106, v56 offset:1184
	ds_write_b32 v107, v57 offset:128
	ds_write2_b32 v108, v50, v51 offset1:132
	ds_write_b32 v108, v52 offset:1056
	ds_write_b32 v109, v53
	ds_write_b32 v106, v46 offset:256
	ds_write_b32 v106, v47 offset:784
	ds_write_b32 v106, v48 offset:1312
	ds_write_b32 v107, v49 offset:256
	ds_write_b32 v106, v42 offset:320
	ds_write_b32 v106, v43 offset:848
	ds_write_b32 v106, v44 offset:1376
	ds_write_b32 v107, v45 offset:320
	ds_write_b32 v106, v38 offset:384
	ds_write_b32 v106, v39 offset:912
	ds_write_b32 v106, v40 offset:1440
	ds_write_b32 v107, v41 offset:384
	ds_write2_b32 v110, v34, v35 offset1:132
	ds_write_b32 v110, v36 offset:1056
	ds_write_b32 v111, v37
	v_add_co_u32_e32 v34, vcc, s12, v72
	v_lshl_add_u64 v[80:81], v[80:81], 0, 32
	s_nop 0
	v_addc_co_u32_e32 v35, vcc, 0, v73, vcc
	global_load_ushort v66, v[34:35], off
	v_add_co_u32_e32 v34, vcc, s13, v72
	s_nop 1
	v_addc_co_u32_e32 v35, vcc, 0, v73, vcc
	global_load_ushort v67, v[34:35], off offset:512
	v_add_co_u32_e32 v34, vcc, s33, v72
	s_nop 1
	v_addc_co_u32_e32 v35, vcc, 0, v73, vcc
	global_load_ushort v68, v[34:35], off offset:1024
	v_add_co_u32_e32 v34, vcc, s28, v72
	v_mul_f32_e32 v72, v33, v71
	s_nop 0
	v_addc_co_u32_e32 v35, vcc, 0, v73, vcc
	global_load_ushort v69, v[34:35], off offset:1536
	s_waitcnt lgkmcnt(0)
	v_mul_f32_e32 v71, v32, v71
	ds_read2st64_b32 v[34:35], v112 offset1:1
	ds_read2_b32 v[36:37], v112 offset0:132 offset1:196
	ds_read2st64_b32 v[38:39], v115 offset0:4 offset1:5
	ds_read2st64_b32 v[40:41], v116 offset0:6 offset1:7
	ds_read2st64_b32 v[42:43], v117 offset0:8 offset1:9
	ds_read2st64_b32 v[44:45], v118 offset0:10 offset1:11
	ds_read2st64_b32 v[46:47], v119 offset0:12 offset1:13
	ds_read2st64_b32 v[48:49], v120 offset0:14 offset1:15
	ds_read2st64_b32 v[50:51], v121 offset0:16 offset1:17
	ds_read2st64_b32 v[52:53], v122 offset0:18 offset1:19
	ds_read2st64_b32 v[54:55], v123 offset0:20 offset1:21
	ds_read2st64_b32 v[56:57], v124 offset0:22 offset1:23
	ds_read2st64_b32 v[58:59], v125 offset0:24 offset1:25
	ds_read2st64_b32 v[60:61], v126 offset0:26 offset1:27
	ds_read2st64_b32 v[62:63], v127 offset0:28 offset1:29
	ds_read2st64_b32 v[64:65], v128 offset0:30 offset1:31
	v_fmac_f32_e32 v71, v33, v70
	v_fma_f32 v72, v32, v70, -v72
	s_waitcnt lgkmcnt(14)
; __device__ __forceinline__ unsigned cvt_pk(float lo, float hi) { f32x2_t v = {lo, hi}; bf16x2_t b = __builtin_convertvector(v, bf16x2_t); return __builtin_bit_cast(unsigned, b); }
; __device__ __forceinline__ float bflo(unsigned w) { return __uint_as_float(w << 16); }
; __device__ __forceinline__ float bfhi(unsigned w) { return __uint_as_float(w & 0xffff0000u); }
; #define S5_LDS_FENCE() do { __builtin_amdgcn_wave_barrier(); asm volatile("s_waitcnt lgkmcnt(0)" ::: "memory"); } while (0)
; template <bool WRITEH>
; __device__ __forceinline__ void s5_block(const S5Coef& C, const bf16x8 (&bm)[8], u32x4 uw, float* Hs, int lane, float& hr, float& hi) {
;     ...
;     for (int tl = 0; tl < 16; ++tl) { bur[tl] = Hs[tl * 132 + lane]; bui[tl] = Hs[tl * 132 + 64 + lane]; }
; #pragma unroll
;     for (int tl = 0; tl < 16; ++tl) { const float nr = C.ar * hr - C.ai * hi + bur[tl], ni = C.ar * hi + C.ai * hr + bui[tl]; hr = nr; hi = ni; bur[tl] = hr; bui[tl] = hi; }
;     if (WRITEH) {
; #pragma unroll
;         for (int tl = 0; tl < 16; ++tl) { Hs[tl * 132 + lane] = bur[tl]; Hs[tl * 132 + 64 + lane] = bui[tl]; }
;     }
;     S5_LDS_FENCE();
; __device__ __forceinline__ void s5_unit(ArgsP A, int l, int unit, unsigned char* lds, int wave_, int lane_) {
;     ...
;             for (int ks = 0; ks < 4; ++ks) { const float* hp = Hs + (lane & 15) * 132 + 32 * ks + 8 * (lane >> 4); const f32x4 h0 = *(const f32x4*)hp, h1 = *(const f32x4*)(hp + 4);
;                 u32x4 wh; wh.x = cvt_pk(h0[0], h0[1]); wh.y = cvt_pk(h0[2], h0[3]); wh.z = cvt_pk(h1[0], h1[1]); wh.w = cvt_pk(h1[2], h1[3]);
;                 u32x4 wl; wl.x = cvt_pk(h0[0] - bflo(wh.x), h0[1] - bfhi(wh.x)); wl.y = cvt_pk(h0[2] - bflo(wh.y), h0[3] - bfhi(wh.y)); wl.z = cvt_pk(h1[0] - bflo(wh.z), h1[1] - bfhi(wh.z)); wl.w = cvt_pk(h1[2] - bflo(wh.w), h1[3] - bfhi(wh.w));
;                 const bf16x8 hh_ = __builtin_bit_cast(bf16x8, wh), hl_ = __builtin_bit_cast(bf16x8, wl);
;                 y = __builtin_amdgcn_mfma_f32_16x16x32_bf16(hh_, chl[2 * ks], y, 0, 0, 0); y2 = __builtin_amdgcn_mfma_f32_16x16x32_bf16(hh_, chl[2 * ks + 1], y2, 0, 0, 0);
;                 y2 = __builtin_amdgcn_mfma_f32_16x16x32_bf16(hl_, chl[2 * ks], y2, 0, 0, 0); }
	v_add_f32_e32 v35, v71, v35
	v_add_f32_e32 v34, v72, v34
	v_mul_f32_e32 v70, v33, v35
	v_fma_f32 v70, v32, v34, -v70
	v_add_f32_e32 v36, v36, v70
	v_mul_f32_e32 v70, v32, v35
	v_fmac_f32_e32 v70, v33, v34
	v_add_f32_e32 v37, v37, v70
	v_mul_f32_e32 v70, v33, v37
	v_fma_f32 v70, v32, v36, -v70
	s_waitcnt lgkmcnt(13)
	v_add_f32_e32 v38, v38, v70
	v_mul_f32_e32 v70, v32, v37
	v_fmac_f32_e32 v70, v33, v36
	v_add_f32_e32 v39, v39, v70
	v_mul_f32_e32 v70, v33, v39
	v_fma_f32 v70, v32, v38, -v70
	s_waitcnt lgkmcnt(12)
	v_add_f32_e32 v40, v40, v70
	v_mul_f32_e32 v70, v32, v39
	v_fmac_f32_e32 v70, v33, v38
	v_add_f32_e32 v41, v41, v70
	v_mul_f32_e32 v70, v33, v41
	v_fma_f32 v70, v32, v40, -v70
	s_waitcnt lgkmcnt(11)
	v_add_f32_e32 v42, v42, v70
	v_mul_f32_e32 v70, v32, v41
	v_fmac_f32_e32 v70, v33, v40
	v_add_f32_e32 v43, v43, v70
	v_mul_f32_e32 v70, v33, v43
	v_fma_f32 v70, v32, v42, -v70
	s_waitcnt lgkmcnt(10)
	v_add_f32_e32 v44, v44, v70
	v_mul_f32_e32 v70, v32, v43
	v_fmac_f32_e32 v70, v33, v42
	v_add_f32_e32 v45, v45, v70
	v_mul_f32_e32 v70, v33, v45
	v_fma_f32 v70, v32, v44, -v70
	s_waitcnt lgkmcnt(9)
	v_add_f32_e32 v46, v46, v70
	v_mul_f32_e32 v70, v32, v45
	v_fmac_f32_e32 v70, v33, v44
	v_add_f32_e32 v47, v47, v70
	v_mul_f32_e32 v70, v33, v47
	v_fma_f32 v70, v32, v46, -v70
	s_waitcnt lgkmcnt(8)
	v_add_f32_e32 v48, v48, v70
	v_mul_f32_e32 v70, v32, v47
	v_fmac_f32_e32 v70, v33, v46
	v_add_f32_e32 v49, v49, v70
	v_mul_f32_e32 v70, v33, v49
	v_fma_f32 v70, v32, v48, -v70
	s_waitcnt lgkmcnt(7)
	v_add_f32_e32 v50, v50, v70
	v_mul_f32_e32 v70, v32, v49
	v_fmac_f32_e32 v70, v33, v48
	v_add_f32_e32 v51, v51, v70
	v_mul_f32_e32 v70, v33, v51
	v_fma_f32 v70, v32, v50, -v70
	s_waitcnt lgkmcnt(6)
	v_add_f32_e32 v52, v52, v70
	v_mul_f32_e32 v70, v32, v51
	v_fmac_f32_e32 v70, v33, v50
	v_add_f32_e32 v53, v53, v70
	v_mul_f32_e32 v70, v33, v53
	v_fma_f32 v70, v32, v52, -v70
	s_waitcnt lgkmcnt(5)
	v_add_f32_e32 v54, v54, v70
	v_mul_f32_e32 v70, v32, v53
	v_fmac_f32_e32 v70, v33, v52
	v_add_f32_e32 v55, v55, v70
	v_mul_f32_e32 v70, v33, v55
	v_fma_f32 v70, v32, v54, -v70
	s_waitcnt lgkmcnt(4)
	v_add_f32_e32 v56, v56, v70
	v_mul_f32_e32 v70, v32, v55
	v_fmac_f32_e32 v70, v33, v54
	v_add_f32_e32 v57, v57, v70
	v_mul_f32_e32 v70, v33, v57
	v_fma_f32 v70, v32, v56, -v70
	s_waitcnt lgkmcnt(3)
	v_add_f32_e32 v58, v58, v70
	v_mul_f32_e32 v70, v32, v57
	v_fmac_f32_e32 v70, v33, v56
	v_add_f32_e32 v59, v59, v70
	v_mul_f32_e32 v70, v33, v59
	v_fma_f32 v70, v32, v58, -v70
	s_waitcnt lgkmcnt(2)
	v_add_f32_e32 v60, v60, v70
	v_mul_f32_e32 v70, v32, v59
	v_fmac_f32_e32 v70, v33, v58
	v_add_f32_e32 v61, v61, v70
	v_mul_f32_e32 v70, v33, v61
	v_fma_f32 v70, v32, v60, -v70
	s_waitcnt lgkmcnt(1)
	v_add_f32_e32 v62, v62, v70
	v_mul_f32_e32 v70, v32, v61
	v_fmac_f32_e32 v70, v33, v60
	v_add_f32_e32 v63, v63, v70
	v_mul_f32_e32 v70, v33, v63
	v_fma_f32 v70, v32, v62, -v70
	v_mul_f32_e32 v32, v32, v63
	v_fmac_f32_e32 v32, v33, v62
	s_waitcnt lgkmcnt(0)
	v_add_f32_e32 v64, v64, v70
	v_add_f32_e32 v32, v65, v32
	ds_write2st64_b32 v112, v34, v35 offset1:1
	ds_write2_b32 v112, v36, v37 offset0:132 offset1:196
	ds_write2st64_b32 v115, v38, v39 offset0:4 offset1:5
	ds_write2st64_b32 v116, v40, v41 offset0:6 offset1:7
	ds_write2st64_b32 v117, v42, v43 offset0:8 offset1:9
	ds_write2st64_b32 v118, v44, v45 offset0:10 offset1:11
	ds_write2st64_b32 v119, v46, v47 offset0:12 offset1:13
	ds_write2st64_b32 v120, v48, v49 offset0:14 offset1:15
	ds_write2st64_b32 v121, v50, v51 offset0:16 offset1:17
	ds_write2st64_b32 v122, v52, v53 offset0:18 offset1:19
	ds_write2st64_b32 v123, v54, v55 offset0:20 offset1:21
	ds_write2st64_b32 v124, v56, v57 offset0:22 offset1:23
	ds_write2st64_b32 v125, v58, v59 offset0:24 offset1:25
	ds_write2st64_b32 v126, v60, v61 offset0:26 offset1:27
	ds_write2st64_b32 v127, v62, v63 offset0:28 offset1:29
	ds_write2st64_b32 v128, v64, v32 offset0:30 offset1:31
	s_waitcnt lgkmcnt(0)
	ds_read_b128 v[32:35], v113
	ds_read_b128 v[36:39], v113 offset:16
	s_waitcnt lgkmcnt(1)
	v_cvt_pk_bf16_f32 v40, v32, v33
	v_cvt_pk_bf16_f32 v41, v34, v35
	v_lshlrev_b32_e32 v44, 16, v40
	v_and_b32_e32 v45, 0xffff0000, v40
	v_pk_add_f32 v[32:33], v[32:33], v[44:45] neg_lo:[0,1] neg_hi:[0,1]
	v_lshlrev_b32_e32 v44, 16, v41
	v_and_b32_e32 v45, 0xffff0000, v41
	s_waitcnt lgkmcnt(0)
	v_cvt_pk_bf16_f32 v42, v36, v37
	v_cvt_pk_bf16_f32 v43, v38, v39
	v_pk_add_f32 v[34:35], v[34:35], v[44:45] neg_lo:[0,1] neg_hi:[0,1]
	v_cvt_pk_bf16_f32 v32, v32, v33
	v_cvt_pk_bf16_f32 v33, v34, v35
	v_lshlrev_b32_e32 v34, 16, v42
	v_and_b32_e32 v35, 0xffff0000, v42
	v_pk_add_f32 v[34:35], v[36:37], v[34:35] neg_lo:[0,1] neg_hi:[0,1]
	v_lshlrev_b32_e32 v36, 16, v43
	v_and_b32_e32 v37, 0xffff0000, v43
	v_pk_add_f32 v[36:37], v[38:39], v[36:37] neg_lo:[0,1] neg_hi:[0,1]
	v_cvt_pk_bf16_f32 v34, v34, v35
	v_cvt_pk_bf16_f32 v35, v36, v37
	v_mfma_f32_16x16x32_bf16 v[28:31], v[40:43], v[28:31], 0
	v_mfma_f32_16x16x32_bf16 v[36:39], v[40:43], v[24:27], 0
	v_mfma_f32_16x16x32_bf16 v[24:27], v[32:35], v[24:27], v[28:31]
	s_nop 5
	ds_read_b128 v[28:31], v113 offset:128
	ds_read_b128 v[32:35], v113 offset:144
	s_waitcnt lgkmcnt(1)
	v_cvt_pk_bf16_f32 v40, v28, v29
	v_cvt_pk_bf16_f32 v41, v30, v31
	v_lshlrev_b32_e32 v44, 16, v40
	v_and_b32_e32 v45, 0xffff0000, v40
	v_pk_add_f32 v[28:29], v[28:29], v[44:45] neg_lo:[0,1] neg_hi:[0,1]
	v_lshlrev_b32_e32 v44, 16, v41
	v_and_b32_e32 v45, 0xffff0000, v41
	s_waitcnt lgkmcnt(0)
; __device__ __forceinline__ unsigned cvt_pk(float lo, float hi) { f32x2_t v = {lo, hi}; bf16x2_t b = __builtin_convertvector(v, bf16x2_t); return __builtin_bit_cast(unsigned, b); }
; __device__ __forceinline__ float bf2f(unsigned short h) { return __uint_as_float(((unsigned)h) << 16); }
; __device__ __forceinline__ float bflo(unsigned w) { return __uint_as_float(w << 16); }
; __device__ __forceinline__ float bfhi(unsigned w) { return __uint_as_float(w & 0xffff0000u); }
; __device__ __forceinline__ unsigned short f2bf(float f) { return (unsigned short)(cvt_pk(f, 0.f) & 0xffffu); }
; __device__ __forceinline__ void s5_unit(ArgsP A, int l, int unit, unsigned char* lds, int wave_, int lane_) {
;     ...
;             for (int ks = 0; ks < 4; ++ks) { const float* hp = Hs + (lane & 15) * 132 + 32 * ks + 8 * (lane >> 4); const f32x4 h0 = *(const f32x4*)hp, h1 = *(const f32x4*)(hp + 4);
;                 u32x4 wh; wh.x = cvt_pk(h0[0], h0[1]); wh.y = cvt_pk(h0[2], h0[3]); wh.z = cvt_pk(h1[0], h1[1]); wh.w = cvt_pk(h1[2], h1[3]);
;                 u32x4 wl; wl.x = cvt_pk(h0[0] - bflo(wh.x), h0[1] - bfhi(wh.x)); wl.y = cvt_pk(h0[2] - bflo(wh.y), h0[3] - bfhi(wh.y)); wl.z = cvt_pk(h1[0] - bflo(wh.z), h1[1] - bfhi(wh.z)); wl.w = cvt_pk(h1[2] - bflo(wh.w), h1[3] - bfhi(wh.w));
;                 const bf16x8 hh_ = __builtin_bit_cast(bf16x8, wh), hl_ = __builtin_bit_cast(bf16x8, wl);
;                 y = __builtin_amdgcn_mfma_f32_16x16x32_bf16(hh_, chl[2 * ks], y, 0, 0, 0); y2 = __builtin_amdgcn_mfma_f32_16x16x32_bf16(hh_, chl[2 * ks + 1], y2, 0, 0, 0);
;                 y2 = __builtin_amdgcn_mfma_f32_16x16x32_bf16(hl_, chl[2 * ks], y2, 0, 0, 0); }
;             y = y + y2;
; #pragma unroll
;             for (int i = 0; i < 4; ++i) { const int t = 16 * blk + 4 * (lane >> 4) + i; const int col = 16 * g + (lane & 15);
;                 const float uval = bf2f(uraw[i]); const float v = gelu_tanh(y[i] + dv * uval); ys[t * YS_STRIDE + col] = f2bf(v); }
;             __builtin_amdgcn_wave_barrier(); asm volatile("s_waitcnt lgkmcnt(0)" ::: "memory");
;         }
	v_cvt_pk_bf16_f32 v42, v32, v33
	v_cvt_pk_bf16_f32 v43, v34, v35
	v_pk_add_f32 v[30:31], v[30:31], v[44:45] neg_lo:[0,1] neg_hi:[0,1]
	v_cvt_pk_bf16_f32 v28, v28, v29
	v_cvt_pk_bf16_f32 v29, v30, v31
	v_lshlrev_b32_e32 v30, 16, v42
	v_and_b32_e32 v31, 0xffff0000, v42
	v_pk_add_f32 v[30:31], v[32:33], v[30:31] neg_lo:[0,1] neg_hi:[0,1]
	v_lshlrev_b32_e32 v32, 16, v43
	v_and_b32_e32 v33, 0xffff0000, v43
	v_pk_add_f32 v[32:33], v[34:35], v[32:33] neg_lo:[0,1] neg_hi:[0,1]
	v_cvt_pk_bf16_f32 v30, v30, v31
	v_cvt_pk_bf16_f32 v31, v32, v33
	v_mfma_f32_16x16x32_bf16 v[20:23], v[40:43], v[20:23], v[24:27]
	v_mfma_f32_16x16x32_bf16 v[32:35], v[40:43], v[16:19], v[36:39]
	v_mfma_f32_16x16x32_bf16 v[16:19], v[28:31], v[16:19], v[20:23]
	s_nop 5
	ds_read_b128 v[20:23], v113 offset:256
	ds_read_b128 v[24:27], v113 offset:272
	s_waitcnt lgkmcnt(1)
	v_cvt_pk_bf16_f32 v28, v20, v21
	v_cvt_pk_bf16_f32 v29, v22, v23
	v_lshlrev_b32_e32 v36, 16, v28
	v_and_b32_e32 v37, 0xffff0000, v28
	v_pk_add_f32 v[20:21], v[20:21], v[36:37] neg_lo:[0,1] neg_hi:[0,1]
	v_lshlrev_b32_e32 v36, 16, v29
	v_and_b32_e32 v37, 0xffff0000, v29
	s_waitcnt lgkmcnt(0)
	v_cvt_pk_bf16_f32 v30, v24, v25
	v_cvt_pk_bf16_f32 v31, v26, v27
	v_pk_add_f32 v[22:23], v[22:23], v[36:37] neg_lo:[0,1] neg_hi:[0,1]
	v_cvt_pk_bf16_f32 v20, v20, v21
	v_cvt_pk_bf16_f32 v21, v22, v23
	v_lshlrev_b32_e32 v22, 16, v30
	v_and_b32_e32 v23, 0xffff0000, v30
	v_pk_add_f32 v[22:23], v[24:25], v[22:23] neg_lo:[0,1] neg_hi:[0,1]
	v_lshlrev_b32_e32 v24, 16, v31
	v_and_b32_e32 v25, 0xffff0000, v31
	v_pk_add_f32 v[24:25], v[26:27], v[24:25] neg_lo:[0,1] neg_hi:[0,1]
	v_cvt_pk_bf16_f32 v22, v22, v23
	v_cvt_pk_bf16_f32 v23, v24, v25
	v_mfma_f32_16x16x32_bf16 v[12:15], v[28:31], v[12:15], v[16:19]
	v_mfma_f32_16x16x32_bf16 v[24:27], v[28:31], v[8:11], v[32:35]
	v_mfma_f32_16x16x32_bf16 v[8:11], v[20:23], v[8:11], v[12:15]
	s_nop 5
	ds_read_b128 v[12:15], v113 offset:384
	ds_read_b128 v[16:19], v113 offset:400
	s_waitcnt lgkmcnt(1)
	v_cvt_pk_bf16_f32 v20, v12, v13
	v_cvt_pk_bf16_f32 v21, v14, v15
	v_lshlrev_b32_e32 v28, 16, v20
	v_and_b32_e32 v29, 0xffff0000, v20
	v_pk_add_f32 v[12:13], v[12:13], v[28:29] neg_lo:[0,1] neg_hi:[0,1]
	v_lshlrev_b32_e32 v28, 16, v21
	v_and_b32_e32 v29, 0xffff0000, v21
	s_waitcnt lgkmcnt(0)
	v_cvt_pk_bf16_f32 v22, v16, v17
	v_cvt_pk_bf16_f32 v23, v18, v19
	v_pk_add_f32 v[14:15], v[14:15], v[28:29] neg_lo:[0,1] neg_hi:[0,1]
	v_cvt_pk_bf16_f32 v12, v12, v13
	v_cvt_pk_bf16_f32 v13, v14, v15
	v_lshlrev_b32_e32 v14, 16, v22
	v_and_b32_e32 v15, 0xffff0000, v22
	v_pk_add_f32 v[14:15], v[16:17], v[14:15] neg_lo:[0,1] neg_hi:[0,1]
	v_lshlrev_b32_e32 v16, 16, v23
	v_and_b32_e32 v17, 0xffff0000, v23
	v_pk_add_f32 v[16:17], v[18:19], v[16:17] neg_lo:[0,1] neg_hi:[0,1]
	v_cvt_pk_bf16_f32 v14, v14, v15
	v_cvt_pk_bf16_f32 v15, v16, v17
	v_mfma_f32_16x16x32_bf16 v[4:7], v[20:23], v[4:7], v[8:11]
	v_mfma_f32_16x16x32_bf16 v[16:19], v[20:23], v[0:3], v[24:27]
	v_mfma_f32_16x16x32_bf16 v[0:3], v[12:15], v[0:3], v[4:7]
	s_waitcnt vmcnt(3)
	s_nop 4
	v_lshlrev_b32_e32 v4, 16, v66
	s_nop 0
	v_pk_add_f32 v[0:1], v[16:17], v[0:1]
	v_pk_add_f32 v[2:3], v[18:19], v[2:3]
	v_fma_f32 v0, v79, v4, v0
	v_mul_f32_e32 v4, 0x3d372713, v0
	v_mul_f32_e32 v4, v0, v4
	v_fma_f32 v4, v0, v4, v0
	v_mul_f32_e32 v4, 0x3f4c422a, v4
	v_add_f32_e32 v4, v4, v4
	v_mul_f32_e32 v4, 0x3fb8aa3b, v4
	v_exp_f32_e32 v4, v4
	v_mul_f32_e32 v0, 0.5, v0
	v_add_f32_e32 v4, 1.0, v4
	v_rcp_f32_e32 v4, v4
	s_nop 0
	v_fma_f32 v4, v4, -2.0, 1.0
	v_add_f32_e32 v4, 1.0, v4
	v_mul_f32_e32 v0, v0, v4
	v_cvt_pk_bf16_f32 v0, v0, s0
	ds_write_b16 v102, v0 offset:49920
	s_waitcnt vmcnt(2)
	v_lshlrev_b32_e32 v0, 16, v67
	v_fmac_f32_e32 v1, v79, v0
	v_mul_f32_e32 v0, 0x3d372713, v1
	v_mul_f32_e32 v0, v1, v0
	v_fma_f32 v0, v1, v0, v1
	v_mul_f32_e32 v0, 0x3f4c422a, v0
	v_add_f32_e32 v0, v0, v0
	v_mul_f32_e32 v0, 0x3fb8aa3b, v0
	v_exp_f32_e32 v0, v0
	v_mul_f32_e32 v1, 0.5, v1
	v_add_f32_e32 v0, 1.0, v0
	v_rcp_f32_e32 v0, v0
	s_nop 0
	v_fma_f32 v0, v0, -2.0, 1.0
	v_add_f32_e32 v0, 1.0, v0
	v_mul_f32_e32 v0, v1, v0
	v_cvt_pk_bf16_f32 v0, v0, s0
	ds_write_b16 v102, v0 offset:50960
	s_waitcnt vmcnt(1)
	v_lshlrev_b32_e32 v0, 16, v68
	v_fma_f32 v0, v79, v0, v2
	v_mul_f32_e32 v1, 0x3d372713, v0
	v_mul_f32_e32 v1, v0, v1
	v_fma_f32 v1, v0, v1, v0
	v_mul_f32_e32 v1, 0x3f4c422a, v1
	v_add_f32_e32 v1, v1, v1
	v_mul_f32_e32 v1, 0x3fb8aa3b, v1
	v_exp_f32_e32 v1, v1
	v_mul_f32_e32 v0, 0.5, v0
	v_add_f32_e32 v1, 1.0, v1
	v_rcp_f32_e32 v1, v1
	s_nop 0
	v_fma_f32 v1, v1, -2.0, 1.0
	v_add_f32_e32 v1, 1.0, v1
	v_mul_f32_e32 v0, v0, v1
	v_cvt_pk_bf16_f32 v0, v0, s0
	ds_write_b16 v102, v0 offset:52000
	s_waitcnt vmcnt(0)
	v_lshlrev_b32_e32 v0, 16, v69
	v_fmac_f32_e32 v3, v79, v0
	v_mul_f32_e32 v0, 0x3d372713, v3
	v_mul_f32_e32 v0, v3, v0
	v_fma_f32 v0, v3, v0, v3
	v_mul_f32_e32 v0, 0x3f4c422a, v0
	v_add_f32_e32 v0, v0, v0
	v_mul_f32_e32 v0, 0x3fb8aa3b, v0
	v_exp_f32_e32 v0, v0
	v_mul_f32_e32 v1, 0.5, v3
	v_add_f32_e32 v0, 1.0, v0
	v_rcp_f32_e32 v0, v0
	s_nop 0
	v_fma_f32 v0, v0, -2.0, 1.0
	v_add_f32_e32 v0, 1.0, v0
	v_mul_f32_e32 v0, v1, v0
	v_cvt_pk_bf16_f32 v0, v0, s0
	ds_write_b16 v102, v0 offset:53040
	s_waitcnt lgkmcnt(0)
	s_cbranch_scc1 .LBB0_792
; __device__ __forceinline__ void s5_unit(ArgsP A, int l, int unit, unsigned char* lds, int wave_, int lane_) {
;     ...
;     __syncthreads();
;     const bf16_t* WG = (const bf16_t*)(A->ws + WS_W + (size_t)l * WL_SIZE + WL_WGLU);
;     f32x4 acc[4][4];
; #pragma unroll
;     for (int mb = 0; mb < 4; ++mb)
; #pragma unroll
;         for (int nb = 0; nb < 4; ++nb) acc[mb][nb] = (f32x4){0.f, 0.f, 0.f, 0.f};
;     {
;         const bf16_t* wb = WG + (size_t)(64 * wave + (lane & 15)) * 512 + 8 * (lane >> 4);
;         bf16x8 bq[4][4];
; #pragma unroll
;         for (int p = 0; p < 4; ++p)
; #pragma unroll
;             for (int nb = 0; nb < 4; ++nb) bq[p][nb] = *(const bf16x8*)(wb + (size_t)(16 * nb) * 512 + 32 * p);
; #pragma unroll
;         for (int ks = 0; ks < 16; ++ks) {
;             bf16x8 af[4];
; #pragma unroll
;             for (int mb = 0; mb < 4; ++mb) af[mb] = *(const bf16x8*)(ys + (16 * mb + (lane & 15)) * YS_STRIDE + 32 * ks + 8 * (lane >> 4));
;             asm volatile("" : "+v"(bq[ks & 3][0]), "+v"(bq[ks & 3][1]), "+v"(bq[ks & 3][2]), "+v"(bq[ks & 3][3]) :: "memory");
; #pragma unroll
;             for (int mb = 0; mb < 4; ++mb)
; #pragma unroll
;                 for (int nb = 0; nb < 4; ++nb) acc[mb][nb] = __builtin_amdgcn_mfma_f32_16x16x32_bf16(af[mb], bq[ks & 3][nb], acc[mb][nb], 0, 0, 0);
	v_readlane_b32 s5, v255, 15
	v_or_b32_e32 v64, s4, v104
	s_add_u32 s6, s2, s5
	v_ashrrev_i32_e32 v65, 31, v64
	s_addc_u32 s7, s3, 0
	v_lshlrev_b64 v[0:1], 10, v[64:65]
	v_lshl_add_u64 v[0:1], s[6:7], 0, v[0:1]
	v_and_b32_e32 v176, 48, v105
	v_lshl_add_u64 v[34:35], v[0:1], 0, v[176:177]
	s_mov_b64 s[4:5], 0xa650000
	v_lshl_add_u64 v[48:49], v[34:35], 0, s[4:5]
	s_mov_b32 s4, 0xa65c000
	v_add_co_u32_e32 v16, vcc, s4, v34
	s_mov_b32 s4, 0xa658000
	s_nop 0
	v_addc_co_u32_e32 v17, vcc, 0, v35, vcc
	v_add_co_u32_e32 v18, vcc, s4, v34
	s_mov_b32 s4, 0xa654000
	s_nop 0
	v_addc_co_u32_e32 v19, vcc, 0, v35, vcc
	v_add_co_u32_e32 v32, vcc, s4, v34
	s_mov_b32 s4, 0xa650000
	s_nop 0
	v_addc_co_u32_e32 v33, vcc, 0, v35, vcc
	v_mul_u32_u24_e32 v0, 0x410, v104
	v_add_co_u32_e32 v34, vcc, s4, v34
	v_add3_u32 v67, 16, v176, v0
	s_nop 0
	v_addc_co_u32_e32 v35, vcc, 0, v35, vcc
	s_waitcnt lgkmcnt(0)
	s_barrier
	ds_read_b128 v[0:3], v67
	ds_read_b128 v[4:7], v67 offset:16640
	ds_read_b128 v[8:11], v67 offset:33280
	ds_read_b128 v[12:15], v67 offset:49920
	global_load_dwordx4 v[20:23], v[16:17], off
	global_load_dwordx4 v[24:27], v[18:19], off
	global_load_dwordx4 v[28:31], v[32:33], off
	s_nop 0
	global_load_dwordx4 v[34:37], v[34:35], off
	s_nop 0
	global_load_dwordx4 v[38:41], v[16:17], off offset:64
	global_load_dwordx4 v[42:45], v[18:19], off offset:64
	global_load_dwordx4 v[50:53], v[32:33], off offset:64
	global_load_dwordx4 v[54:57], v[48:49], off offset:64
	global_load_dwordx4 v[58:61], v[16:17], off offset:128
	global_load_dwordx4 v[68:71], v[18:19], off offset:128
	global_load_dwordx4 v[72:75], v[32:33], off offset:128
	global_load_dwordx4 v[76:79], v[48:49], off offset:128
	global_load_dwordx4 v[80:83], v[16:17], off offset:192
	global_load_dwordx4 v[84:87], v[18:19], off offset:192
	global_load_dwordx4 v[88:91], v[32:33], off offset:192
	global_load_dwordx4 v[92:95], v[48:49], off offset:192
	v_lshrrev_b32_e32 v66, 4, v105
	s_add_u32 s2, s2, 0x24f90000
	s_addc_u32 s3, s3, 0
	s_waitcnt vmcnt(12)
	s_waitcnt lgkmcnt(3)
	v_mfma_f32_16x16x32_bf16 v[96:99], v[0:3], v[34:37], 0
	v_mfma_f32_16x16x32_bf16 v[100:103], v[0:3], v[28:31], 0
	v_mfma_f32_16x16x32_bf16 v[106:109], v[0:3], v[24:27], 0
	v_mfma_f32_16x16x32_bf16 v[0:3], v[0:3], v[20:23], 0
	s_waitcnt lgkmcnt(2)
	v_mfma_f32_16x16x32_bf16 v[110:113], v[4:7], v[34:37], 0
	v_mfma_f32_16x16x32_bf16 v[114:117], v[4:7], v[28:31], 0
	v_mfma_f32_16x16x32_bf16 v[118:121], v[4:7], v[24:27], 0
	v_mfma_f32_16x16x32_bf16 v[4:7], v[4:7], v[20:23], 0
	s_waitcnt lgkmcnt(1)
	v_mfma_f32_16x16x32_bf16 v[122:125], v[8:11], v[34:37], 0
	v_mfma_f32_16x16x32_bf16 v[126:129], v[8:11], v[28:31], 0
	v_mfma_f32_16x16x32_bf16 v[130:133], v[8:11], v[24:27], 0
	v_mfma_f32_16x16x32_bf16 v[8:11], v[8:11], v[20:23], 0
	s_waitcnt lgkmcnt(0)
	v_mfma_f32_16x16x32_bf16 v[34:37], v[12:15], v[34:37], 0
	v_mfma_f32_16x16x32_bf16 v[28:31], v[12:15], v[28:31], 0
	v_mfma_f32_16x16x32_bf16 v[24:27], v[12:15], v[24:27], 0
	v_mfma_f32_16x16x32_bf16 v[12:15], v[12:15], v[20:23], 0
	ds_read_b128 v[20:23], v67 offset:64
	ds_read_b128 v[134:137], v67 offset:16704
	ds_read_b128 v[138:141], v67 offset:33344
	ds_read_b128 v[142:145], v67 offset:49984
	global_load_dwordx4 v[146:149], v[16:17], off offset:256
	global_load_dwordx4 v[150:153], v[18:19], off offset:256
	global_load_dwordx4 v[154:157], v[32:33], off offset:256
	global_load_dwordx4 v[158:161], v[48:49], off offset:256
	s_waitcnt vmcnt(12)
	s_waitcnt lgkmcnt(3)
	v_mfma_f32_16x16x32_bf16 v[96:99], v[20:23], v[54:57], v[96:99]
	v_mfma_f32_16x16x32_bf16 v[100:103], v[20:23], v[50:53], v[100:103]
	v_mfma_f32_16x16x32_bf16 v[106:109], v[20:23], v[42:45], v[106:109]
	v_mfma_f32_16x16x32_bf16 v[0:3], v[20:23], v[38:41], v[0:3]
	s_waitcnt lgkmcnt(2)
	v_mfma_f32_16x16x32_bf16 v[20:23], v[134:137], v[54:57], v[110:113]
	v_mfma_f32_16x16x32_bf16 v[110:113], v[134:137], v[50:53], v[114:117]
	v_mfma_f32_16x16x32_bf16 v[114:117], v[134:137], v[42:45], v[118:121]
	v_mfma_f32_16x16x32_bf16 v[4:7], v[134:137], v[38:41], v[4:7]
	s_waitcnt lgkmcnt(1)
	v_mfma_f32_16x16x32_bf16 v[118:121], v[138:141], v[54:57], v[122:125]
	v_mfma_f32_16x16x32_bf16 v[122:125], v[138:141], v[50:53], v[126:129]
	v_mfma_f32_16x16x32_bf16 v[126:129], v[138:141], v[42:45], v[130:133]
	v_mfma_f32_16x16x32_bf16 v[8:11], v[138:141], v[38:41], v[8:11]
	s_waitcnt lgkmcnt(0)
	v_mfma_f32_16x16x32_bf16 v[34:37], v[142:145], v[54:57], v[34:37]
	v_mfma_f32_16x16x32_bf16 v[28:31], v[142:145], v[50:53], v[28:31]
	v_mfma_f32_16x16x32_bf16 v[24:27], v[142:145], v[42:45], v[24:27]
	v_mfma_f32_16x16x32_bf16 v[12:15], v[142:145], v[38:41], v[12:15]
	ds_read_b128 v[38:41], v67 offset:128
	ds_read_b128 v[42:45], v67 offset:16768
	ds_read_b128 v[50:53], v67 offset:33408
	ds_read_b128 v[54:57], v67 offset:50048
	global_load_dwordx4 v[130:133], v[16:17], off offset:320
	global_load_dwordx4 v[134:137], v[18:19], off offset:320
	global_load_dwordx4 v[138:141], v[32:33], off offset:320
	global_load_dwordx4 v[142:145], v[48:49], off offset:320
	s_waitcnt vmcnt(12)
	s_waitcnt lgkmcnt(3)
	v_mfma_f32_16x16x32_bf16 v[96:99], v[38:41], v[76:79], v[96:99]
	v_mfma_f32_16x16x32_bf16 v[100:103], v[38:41], v[72:75], v[100:103]
	v_mfma_f32_16x16x32_bf16 v[106:109], v[38:41], v[68:71], v[106:109]
	v_mfma_f32_16x16x32_bf16 v[0:3], v[38:41], v[58:61], v[0:3]
	s_waitcnt lgkmcnt(2)
	v_mfma_f32_16x16x32_bf16 v[20:23], v[42:45], v[76:79], v[20:23]
	v_mfma_f32_16x16x32_bf16 v[38:41], v[42:45], v[72:75], v[110:113]
	v_mfma_f32_16x16x32_bf16 v[110:113], v[42:45], v[68:71], v[114:117]
	v_mfma_f32_16x16x32_bf16 v[4:7], v[42:45], v[58:61], v[4:7]
	s_waitcnt lgkmcnt(1)
; __device__ __forceinline__ void s5_unit(ArgsP A, int l, int unit, unsigned char* lds, int wave_, int lane_) {
;     ...
; #pragma unroll
;         for (int ks = 0; ks < 16; ++ks) {
;             bf16x8 af[4];
; #pragma unroll
;             for (int mb = 0; mb < 4; ++mb) af[mb] = *(const bf16x8*)(ys + (16 * mb + (lane & 15)) * YS_STRIDE + 32 * ks + 8 * (lane >> 4));
;             asm volatile("" : "+v"(bq[ks & 3][0]), "+v"(bq[ks & 3][1]), "+v"(bq[ks & 3][2]), "+v"(bq[ks & 3][3]) :: "memory");
; #pragma unroll
;             for (int mb = 0; mb < 4; ++mb)
; #pragma unroll
;                 for (int nb = 0; nb < 4; ++nb) acc[mb][nb] = __builtin_amdgcn_mfma_f32_16x16x32_bf16(af[mb], bq[ks & 3][nb], acc[mb][nb], 0, 0, 0);
;             if (ks + 4 < 16) {
; #pragma unroll
;                 for (int nb = 0; nb < 4; ++nb) bq[ks & 3][nb] = *(const bf16x8*)(wb + (size_t)(16 * nb) * 512 + 32 * (ks + 4));
;             }
	v_mfma_f32_16x16x32_bf16 v[42:45], v[50:53], v[76:79], v[118:121]
	v_mfma_f32_16x16x32_bf16 v[114:117], v[50:53], v[72:75], v[122:125]
	v_mfma_f32_16x16x32_bf16 v[118:121], v[50:53], v[68:71], v[126:129]
	v_mfma_f32_16x16x32_bf16 v[8:11], v[50:53], v[58:61], v[8:11]
	s_waitcnt lgkmcnt(0)
	v_mfma_f32_16x16x32_bf16 v[34:37], v[54:57], v[76:79], v[34:37]
	v_mfma_f32_16x16x32_bf16 v[28:31], v[54:57], v[72:75], v[28:31]
	v_mfma_f32_16x16x32_bf16 v[24:27], v[54:57], v[68:71], v[24:27]
	v_mfma_f32_16x16x32_bf16 v[12:15], v[54:57], v[58:61], v[12:15]
	ds_read_b128 v[50:53], v67 offset:192
	ds_read_b128 v[54:57], v67 offset:16832
	ds_read_b128 v[58:61], v67 offset:33472
	ds_read_b128 v[68:71], v67 offset:50112
	global_load_dwordx4 v[72:75], v[16:17], off offset:384
	global_load_dwordx4 v[76:79], v[18:19], off offset:384
	global_load_dwordx4 v[122:125], v[32:33], off offset:384
	global_load_dwordx4 v[126:129], v[48:49], off offset:384
	s_waitcnt vmcnt(12)
	s_waitcnt lgkmcnt(3)
	v_mfma_f32_16x16x32_bf16 v[96:99], v[50:53], v[92:95], v[96:99]
	v_mfma_f32_16x16x32_bf16 v[100:103], v[50:53], v[88:91], v[100:103]
	v_mfma_f32_16x16x32_bf16 v[106:109], v[50:53], v[84:87], v[106:109]
	v_mfma_f32_16x16x32_bf16 v[0:3], v[50:53], v[80:83], v[0:3]
	s_waitcnt lgkmcnt(2)
	v_mfma_f32_16x16x32_bf16 v[20:23], v[54:57], v[92:95], v[20:23]
	v_mfma_f32_16x16x32_bf16 v[38:41], v[54:57], v[88:91], v[38:41]
	v_mfma_f32_16x16x32_bf16 v[50:53], v[54:57], v[84:87], v[110:113]
	v_mfma_f32_16x16x32_bf16 v[4:7], v[54:57], v[80:83], v[4:7]
	s_waitcnt lgkmcnt(1)
	v_mfma_f32_16x16x32_bf16 v[42:45], v[58:61], v[92:95], v[42:45]
	v_mfma_f32_16x16x32_bf16 v[54:57], v[58:61], v[88:91], v[114:117]
	v_mfma_f32_16x16x32_bf16 v[110:113], v[58:61], v[84:87], v[118:121]
	v_mfma_f32_16x16x32_bf16 v[8:11], v[58:61], v[80:83], v[8:11]
	s_waitcnt lgkmcnt(0)
	v_mfma_f32_16x16x32_bf16 v[34:37], v[68:71], v[92:95], v[34:37]
	v_mfma_f32_16x16x32_bf16 v[28:31], v[68:71], v[88:91], v[28:31]
	v_mfma_f32_16x16x32_bf16 v[24:27], v[68:71], v[84:87], v[24:27]
	v_mfma_f32_16x16x32_bf16 v[12:15], v[68:71], v[80:83], v[12:15]
	ds_read_b128 v[58:61], v67 offset:256
	ds_read_b128 v[68:71], v67 offset:16896
	ds_read_b128 v[80:83], v67 offset:33536
	ds_read_b128 v[84:87], v67 offset:50176
	global_load_dwordx4 v[88:91], v[16:17], off offset:448
	global_load_dwordx4 v[92:95], v[18:19], off offset:448
	global_load_dwordx4 v[114:117], v[32:33], off offset:448
	global_load_dwordx4 v[118:121], v[48:49], off offset:448
	s_waitcnt vmcnt(12)
	s_waitcnt lgkmcnt(3)
	v_mfma_f32_16x16x32_bf16 v[96:99], v[58:61], v[158:161], v[96:99]
	v_mfma_f32_16x16x32_bf16 v[100:103], v[58:61], v[154:157], v[100:103]
	v_mfma_f32_16x16x32_bf16 v[106:109], v[58:61], v[150:153], v[106:109]
	v_mfma_f32_16x16x32_bf16 v[0:3], v[58:61], v[146:149], v[0:3]
	s_waitcnt lgkmcnt(2)
	v_mfma_f32_16x16x32_bf16 v[20:23], v[68:71], v[158:161], v[20:23]
	v_mfma_f32_16x16x32_bf16 v[38:41], v[68:71], v[154:157], v[38:41]
	v_mfma_f32_16x16x32_bf16 v[50:53], v[68:71], v[150:153], v[50:53]
	v_mfma_f32_16x16x32_bf16 v[4:7], v[68:71], v[146:149], v[4:7]
	s_waitcnt lgkmcnt(1)
	v_mfma_f32_16x16x32_bf16 v[42:45], v[80:83], v[158:161], v[42:45]
	v_mfma_f32_16x16x32_bf16 v[54:57], v[80:83], v[154:157], v[54:57]
	v_mfma_f32_16x16x32_bf16 v[58:61], v[80:83], v[150:153], v[110:113]
	v_mfma_f32_16x16x32_bf16 v[8:11], v[80:83], v[146:149], v[8:11]
	s_waitcnt lgkmcnt(0)
	v_mfma_f32_16x16x32_bf16 v[34:37], v[84:87], v[158:161], v[34:37]
	v_mfma_f32_16x16x32_bf16 v[28:31], v[84:87], v[154:157], v[28:31]
	v_mfma_f32_16x16x32_bf16 v[24:27], v[84:87], v[150:153], v[24:27]
	v_mfma_f32_16x16x32_bf16 v[12:15], v[84:87], v[146:149], v[12:15]
	ds_read_b128 v[68:71], v67 offset:320
	ds_read_b128 v[80:83], v67 offset:16960
	ds_read_b128 v[84:87], v67 offset:33600
	ds_read_b128 v[110:113], v67 offset:50240
	global_load_dwordx4 v[146:149], v[16:17], off offset:512
	global_load_dwordx4 v[150:153], v[18:19], off offset:512
	global_load_dwordx4 v[154:157], v[32:33], off offset:512
	global_load_dwordx4 v[158:161], v[48:49], off offset:512
	s_waitcnt vmcnt(12)
	s_waitcnt lgkmcnt(3)
	v_mfma_f32_16x16x32_bf16 v[96:99], v[68:71], v[142:145], v[96:99]
	v_mfma_f32_16x16x32_bf16 v[100:103], v[68:71], v[138:141], v[100:103]
	v_mfma_f32_16x16x32_bf16 v[106:109], v[68:71], v[134:137], v[106:109]
	v_mfma_f32_16x16x32_bf16 v[0:3], v[68:71], v[130:133], v[0:3]
	s_waitcnt lgkmcnt(2)
	v_mfma_f32_16x16x32_bf16 v[20:23], v[80:83], v[142:145], v[20:23]
	v_mfma_f32_16x16x32_bf16 v[38:41], v[80:83], v[138:141], v[38:41]
	v_mfma_f32_16x16x32_bf16 v[50:53], v[80:83], v[134:137], v[50:53]
	v_mfma_f32_16x16x32_bf16 v[4:7], v[80:83], v[130:133], v[4:7]
	s_waitcnt lgkmcnt(1)
	v_mfma_f32_16x16x32_bf16 v[42:45], v[84:87], v[142:145], v[42:45]
	v_mfma_f32_16x16x32_bf16 v[54:57], v[84:87], v[138:141], v[54:57]
	v_mfma_f32_16x16x32_bf16 v[58:61], v[84:87], v[134:137], v[58:61]
	v_mfma_f32_16x16x32_bf16 v[8:11], v[84:87], v[130:133], v[8:11]
	s_waitcnt lgkmcnt(0)
	v_mfma_f32_16x16x32_bf16 v[34:37], v[110:113], v[142:145], v[34:37]
	v_mfma_f32_16x16x32_bf16 v[28:31], v[110:113], v[138:141], v[28:31]
	v_mfma_f32_16x16x32_bf16 v[24:27], v[110:113], v[134:137], v[24:27]
	v_mfma_f32_16x16x32_bf16 v[12:15], v[110:113], v[130:133], v[12:15]
	ds_read_b128 v[68:71], v67 offset:384
	ds_read_b128 v[80:83], v67 offset:17024
	ds_read_b128 v[84:87], v67 offset:33664
	ds_read_b128 v[110:113], v67 offset:50304
	global_load_dwordx4 v[130:133], v[16:17], off offset:576
	global_load_dwordx4 v[134:137], v[18:19], off offset:576
	global_load_dwordx4 v[138:141], v[32:33], off offset:576
	global_load_dwordx4 v[142:145], v[48:49], off offset:576
	s_waitcnt vmcnt(12)
; __device__ __forceinline__ void s5_unit(ArgsP A, int l, int unit, unsigned char* lds, int wave_, int lane_) {
;     ...
; #pragma unroll
;         for (int ks = 0; ks < 16; ++ks) {
;             bf16x8 af[4];
; #pragma unroll
;             for (int mb = 0; mb < 4; ++mb) af[mb] = *(const bf16x8*)(ys + (16 * mb + (lane & 15)) * YS_STRIDE + 32 * ks + 8 * (lane >> 4));
;             asm volatile("" : "+v"(bq[ks & 3][0]), "+v"(bq[ks & 3][1]), "+v"(bq[ks & 3][2]), "+v"(bq[ks & 3][3]) :: "memory");
; #pragma unroll
;             for (int mb = 0; mb < 4; ++mb)
; #pragma unroll
;                 for (int nb = 0; nb < 4; ++nb) acc[mb][nb] = __builtin_amdgcn_mfma_f32_16x16x32_bf16(af[mb], bq[ks & 3][nb], acc[mb][nb], 0, 0, 0);
;             if (ks + 4 < 16) {
; #pragma unroll
;                 for (int nb = 0; nb < 4; ++nb) bq[ks & 3][nb] = *(const bf16x8*)(wb + (size_t)(16 * nb) * 512 + 32 * (ks + 4));
;             }
	s_waitcnt lgkmcnt(3)
	v_mfma_f32_16x16x32_bf16 v[96:99], v[68:71], v[126:129], v[96:99]
	v_mfma_f32_16x16x32_bf16 v[100:103], v[68:71], v[122:125], v[100:103]
	v_mfma_f32_16x16x32_bf16 v[106:109], v[68:71], v[76:79], v[106:109]
	v_mfma_f32_16x16x32_bf16 v[0:3], v[68:71], v[72:75], v[0:3]
	s_waitcnt lgkmcnt(2)
	v_mfma_f32_16x16x32_bf16 v[20:23], v[80:83], v[126:129], v[20:23]
	v_mfma_f32_16x16x32_bf16 v[38:41], v[80:83], v[122:125], v[38:41]
	v_mfma_f32_16x16x32_bf16 v[50:53], v[80:83], v[76:79], v[50:53]
	v_mfma_f32_16x16x32_bf16 v[4:7], v[80:83], v[72:75], v[4:7]
	s_waitcnt lgkmcnt(1)
	v_mfma_f32_16x16x32_bf16 v[42:45], v[84:87], v[126:129], v[42:45]
	v_mfma_f32_16x16x32_bf16 v[54:57], v[84:87], v[122:125], v[54:57]
	v_mfma_f32_16x16x32_bf16 v[58:61], v[84:87], v[76:79], v[58:61]
	v_mfma_f32_16x16x32_bf16 v[8:11], v[84:87], v[72:75], v[8:11]
	s_waitcnt lgkmcnt(0)
	v_mfma_f32_16x16x32_bf16 v[34:37], v[110:113], v[126:129], v[34:37]
	v_mfma_f32_16x16x32_bf16 v[28:31], v[110:113], v[122:125], v[28:31]
	v_mfma_f32_16x16x32_bf16 v[24:27], v[110:113], v[76:79], v[24:27]
	v_mfma_f32_16x16x32_bf16 v[12:15], v[110:113], v[72:75], v[12:15]
	ds_read_b128 v[68:71], v67 offset:448
	ds_read_b128 v[72:75], v67 offset:17088
	ds_read_b128 v[76:79], v67 offset:33728
	ds_read_b128 v[80:83], v67 offset:50368
	global_load_dwordx4 v[84:87], v[16:17], off offset:640
	global_load_dwordx4 v[110:113], v[18:19], off offset:640
	global_load_dwordx4 v[122:125], v[32:33], off offset:640
	global_load_dwordx4 v[126:129], v[48:49], off offset:640
	s_waitcnt vmcnt(12)
	s_waitcnt lgkmcnt(3)
	v_mfma_f32_16x16x32_bf16 v[96:99], v[68:71], v[118:121], v[96:99]
	v_mfma_f32_16x16x32_bf16 v[100:103], v[68:71], v[114:117], v[100:103]
	v_mfma_f32_16x16x32_bf16 v[106:109], v[68:71], v[92:95], v[106:109]
	v_mfma_f32_16x16x32_bf16 v[0:3], v[68:71], v[88:91], v[0:3]
	s_waitcnt lgkmcnt(2)
	v_mfma_f32_16x16x32_bf16 v[20:23], v[72:75], v[118:121], v[20:23]
	v_mfma_f32_16x16x32_bf16 v[38:41], v[72:75], v[114:117], v[38:41]
	v_mfma_f32_16x16x32_bf16 v[50:53], v[72:75], v[92:95], v[50:53]
	v_mfma_f32_16x16x32_bf16 v[4:7], v[72:75], v[88:91], v[4:7]
	s_waitcnt lgkmcnt(1)
	v_mfma_f32_16x16x32_bf16 v[42:45], v[76:79], v[118:121], v[42:45]
	v_mfma_f32_16x16x32_bf16 v[54:57], v[76:79], v[114:117], v[54:57]
	v_mfma_f32_16x16x32_bf16 v[58:61], v[76:79], v[92:95], v[58:61]
	v_mfma_f32_16x16x32_bf16 v[8:11], v[76:79], v[88:91], v[8:11]
	s_waitcnt lgkmcnt(0)
	v_mfma_f32_16x16x32_bf16 v[34:37], v[80:83], v[118:121], v[34:37]
	v_mfma_f32_16x16x32_bf16 v[28:31], v[80:83], v[114:117], v[28:31]
	v_mfma_f32_16x16x32_bf16 v[24:27], v[80:83], v[92:95], v[24:27]
	v_mfma_f32_16x16x32_bf16 v[12:15], v[80:83], v[88:91], v[12:15]
	ds_read_b128 v[68:71], v67 offset:512
	ds_read_b128 v[72:75], v67 offset:17152
	ds_read_b128 v[76:79], v67 offset:33792
	ds_read_b128 v[80:83], v67 offset:50432
	global_load_dwordx4 v[88:91], v[16:17], off offset:704
	global_load_dwordx4 v[92:95], v[18:19], off offset:704
	global_load_dwordx4 v[114:117], v[32:33], off offset:704
	global_load_dwordx4 v[118:121], v[48:49], off offset:704
	s_waitcnt vmcnt(12)
	s_waitcnt lgkmcnt(3)
	v_mfma_f32_16x16x32_bf16 v[96:99], v[68:71], v[158:161], v[96:99]
	v_mfma_f32_16x16x32_bf16 v[100:103], v[68:71], v[154:157], v[100:103]
	v_mfma_f32_16x16x32_bf16 v[106:109], v[68:71], v[150:153], v[106:109]
	v_mfma_f32_16x16x32_bf16 v[0:3], v[68:71], v[146:149], v[0:3]
	s_waitcnt lgkmcnt(2)
	v_mfma_f32_16x16x32_bf16 v[20:23], v[72:75], v[158:161], v[20:23]
	v_mfma_f32_16x16x32_bf16 v[68:71], v[72:75], v[154:157], v[38:41]
	v_mfma_f32_16x16x32_bf16 v[162:165], v[72:75], v[150:153], v[50:53]
	v_mfma_f32_16x16x32_bf16 v[4:7], v[72:75], v[146:149], v[4:7]
	s_waitcnt lgkmcnt(1)
	v_mfma_f32_16x16x32_bf16 v[72:75], v[76:79], v[158:161], v[42:45]
	v_mfma_f32_16x16x32_bf16 v[166:169], v[76:79], v[154:157], v[54:57]
	v_mfma_f32_16x16x32_bf16 v[56:59], v[76:79], v[150:153], v[58:61]
	v_mfma_f32_16x16x32_bf16 v[8:11], v[76:79], v[146:149], v[8:11]
	s_waitcnt lgkmcnt(0)
	v_mfma_f32_16x16x32_bf16 v[34:37], v[80:83], v[158:161], v[34:37]
	v_mfma_f32_16x16x32_bf16 v[28:31], v[80:83], v[154:157], v[28:31]
	v_mfma_f32_16x16x32_bf16 v[24:27], v[80:83], v[150:153], v[24:27]
	v_mfma_f32_16x16x32_bf16 v[12:15], v[80:83], v[146:149], v[12:15]
	ds_read_b128 v[76:79], v67 offset:576
	ds_read_b128 v[80:83], v67 offset:17216
	ds_read_b128 v[146:149], v67 offset:33856
	ds_read_b128 v[150:153], v67 offset:50496
	global_load_dwordx4 v[40:43], v[16:17], off offset:768
	global_load_dwordx4 v[44:47], v[18:19], off offset:768
	global_load_dwordx4 v[52:55], v[32:33], off offset:768
	global_load_dwordx4 v[60:63], v[48:49], off offset:768
	s_waitcnt vmcnt(12)
	s_waitcnt lgkmcnt(3)
	v_mfma_f32_16x16x32_bf16 v[96:99], v[76:79], v[142:145], v[96:99]
	v_mfma_f32_16x16x32_bf16 v[100:103], v[76:79], v[138:141], v[100:103]
	v_mfma_f32_16x16x32_bf16 v[106:109], v[76:79], v[134:137], v[106:109]
	v_mfma_f32_16x16x32_bf16 v[0:3], v[76:79], v[130:133], v[0:3]
	s_waitcnt lgkmcnt(2)
	v_mfma_f32_16x16x32_bf16 v[20:23], v[80:83], v[142:145], v[20:23]
	v_mfma_f32_16x16x32_bf16 v[68:71], v[80:83], v[138:141], v[68:71]
	v_mfma_f32_16x16x32_bf16 v[76:79], v[80:83], v[134:137], v[162:165]
	v_mfma_f32_16x16x32_bf16 v[4:7], v[80:83], v[130:133], v[4:7]
	s_waitcnt lgkmcnt(1)
	v_mfma_f32_16x16x32_bf16 v[72:75], v[146:149], v[142:145], v[72:75]
	v_mfma_f32_16x16x32_bf16 v[80:83], v[146:149], v[138:141], v[166:169]
	v_mfma_f32_16x16x32_bf16 v[56:59], v[146:149], v[134:137], v[56:59]
	v_mfma_f32_16x16x32_bf16 v[146:149], v[146:149], v[130:133], v[8:11]
	s_waitcnt lgkmcnt(0)
; __device__ __forceinline__ void s5_unit(ArgsP A, int l, int unit, unsigned char* lds, int wave_, int lane_) {
;     ...
; #pragma unroll
;         for (int ks = 0; ks < 16; ++ks) {
;             bf16x8 af[4];
; #pragma unroll
;             for (int mb = 0; mb < 4; ++mb) af[mb] = *(const bf16x8*)(ys + (16 * mb + (lane & 15)) * YS_STRIDE + 32 * ks + 8 * (lane >> 4));
;             asm volatile("" : "+v"(bq[ks & 3][0]), "+v"(bq[ks & 3][1]), "+v"(bq[ks & 3][2]), "+v"(bq[ks & 3][3]) :: "memory");
; #pragma unroll
;             for (int mb = 0; mb < 4; ++mb)
; #pragma unroll
;                 for (int nb = 0; nb < 4; ++nb) acc[mb][nb] = __builtin_amdgcn_mfma_f32_16x16x32_bf16(af[mb], bq[ks & 3][nb], acc[mb][nb], 0, 0, 0);
;             if (ks + 4 < 16) {
; #pragma unroll
;                 for (int nb = 0; nb < 4; ++nb) bq[ks & 3][nb] = *(const bf16x8*)(wb + (size_t)(16 * nb) * 512 + 32 * (ks + 4));
;             }
	v_mfma_f32_16x16x32_bf16 v[142:145], v[150:153], v[142:145], v[34:37]
	v_mfma_f32_16x16x32_bf16 v[138:141], v[150:153], v[138:141], v[28:31]
	v_mfma_f32_16x16x32_bf16 v[134:137], v[150:153], v[134:137], v[24:27]
	v_mfma_f32_16x16x32_bf16 v[12:15], v[150:153], v[130:133], v[12:15]
	ds_read_b128 v[130:133], v67 offset:640
	ds_read_b128 v[150:153], v67 offset:17280
	ds_read_b128 v[154:157], v67 offset:33920
	ds_read_b128 v[158:161], v67 offset:50560
	global_load_dwordx4 v[8:11], v[16:17], off offset:832
	global_load_dwordx4 v[24:27], v[18:19], off offset:832
	global_load_dwordx4 v[28:31], v[32:33], off offset:832
	global_load_dwordx4 v[36:39], v[48:49], off offset:832
	s_waitcnt vmcnt(12)
	s_waitcnt lgkmcnt(3)
	v_mfma_f32_16x16x32_bf16 v[96:99], v[130:133], v[126:129], v[96:99]
	v_mfma_f32_16x16x32_bf16 v[100:103], v[130:133], v[122:125], v[100:103]
	v_mfma_f32_16x16x32_bf16 v[106:109], v[130:133], v[110:113], v[106:109]
	s_waitcnt lgkmcnt(2)
	v_mfma_f32_16x16x32_bf16 v[162:165], v[150:153], v[126:129], v[20:23]
	v_mfma_f32_16x16x32_bf16 v[68:71], v[150:153], v[122:125], v[68:71]
	v_mfma_f32_16x16x32_bf16 v[76:79], v[150:153], v[110:113], v[76:79]
	s_waitcnt lgkmcnt(1)
	v_mfma_f32_16x16x32_bf16 v[72:75], v[154:157], v[126:129], v[72:75]
	v_mfma_f32_16x16x32_bf16 v[80:83], v[154:157], v[122:125], v[80:83]
	v_mfma_f32_16x16x32_bf16 v[56:59], v[154:157], v[110:113], v[56:59]
	v_mfma_f32_16x16x32_bf16 v[146:149], v[154:157], v[84:87], v[146:149]
	s_waitcnt lgkmcnt(0)
	v_mfma_f32_16x16x32_bf16 v[126:129], v[158:161], v[126:129], v[142:145]
	v_mfma_f32_16x16x32_bf16 v[122:125], v[158:161], v[122:125], v[138:141]
	v_mfma_f32_16x16x32_bf16 v[110:113], v[158:161], v[110:113], v[134:137]
	s_nop 2
	ds_read_b128 v[134:137], v67 offset:704
	ds_read_b128 v[138:141], v67 offset:17344
	ds_read_b128 v[142:145], v67 offset:33984
	ds_read_b128 v[154:157], v67 offset:50624
	v_mfma_f32_16x16x32_bf16 v[130:133], v[130:133], v[84:87], v[0:3]
	v_mfma_f32_16x16x32_bf16 v[150:153], v[150:153], v[84:87], v[4:7]
	v_mfma_f32_16x16x32_bf16 v[84:87], v[158:161], v[84:87], v[12:15]
	s_nop 0
	global_load_dwordx4 v[0:3], v[16:17], off offset:896
	global_load_dwordx4 v[4:7], v[18:19], off offset:896
	global_load_dwordx4 v[12:15], v[32:33], off offset:896
	global_load_dwordx4 v[20:23], v[48:49], off offset:896
	s_waitcnt vmcnt(12)
	s_waitcnt lgkmcnt(3)
	v_mfma_f32_16x16x32_bf16 v[96:99], v[134:137], v[118:121], v[96:99]
	v_mfma_f32_16x16x32_bf16 v[100:103], v[134:137], v[114:117], v[100:103]
	v_mfma_f32_16x16x32_bf16 v[106:109], v[134:137], v[92:95], v[106:109]
	v_mfma_f32_16x16x32_bf16 v[130:133], v[134:137], v[88:91], v[130:133]
	s_waitcnt lgkmcnt(2)
	v_mfma_f32_16x16x32_bf16 v[134:137], v[138:141], v[118:121], v[162:165]
	v_mfma_f32_16x16x32_bf16 v[68:71], v[138:141], v[114:117], v[68:71]
	v_mfma_f32_16x16x32_bf16 v[76:79], v[138:141], v[92:95], v[76:79]
	v_mfma_f32_16x16x32_bf16 v[138:141], v[138:141], v[88:91], v[150:153]
	s_waitcnt lgkmcnt(1)
	v_mfma_f32_16x16x32_bf16 v[72:75], v[142:145], v[118:121], v[72:75]
	v_mfma_f32_16x16x32_bf16 v[80:83], v[142:145], v[114:117], v[80:83]
	v_mfma_f32_16x16x32_bf16 v[150:153], v[142:145], v[92:95], v[56:59]
	v_mfma_f32_16x16x32_bf16 v[142:145], v[142:145], v[88:91], v[146:149]
	s_waitcnt lgkmcnt(0)
	v_mfma_f32_16x16x32_bf16 v[118:121], v[154:157], v[118:121], v[126:129]
	v_mfma_f32_16x16x32_bf16 v[114:117], v[154:157], v[114:117], v[122:125]
	v_mfma_f32_16x16x32_bf16 v[92:95], v[154:157], v[92:95], v[110:113]
	v_mfma_f32_16x16x32_bf16 v[84:87], v[154:157], v[88:91], v[84:87]
	ds_read_b128 v[88:91], v67 offset:768
	s_nop 0
	ds_read_b128 v[110:113], v67 offset:17408
	ds_read_b128 v[122:125], v67 offset:34048
	ds_read_b128 v[126:129], v67 offset:50688
	global_load_dwordx4 v[56:59], v[16:17], off offset:960
	s_nop 0
	global_load_dwordx4 v[16:19], v[18:19], off offset:960
	s_nop 0
	global_load_dwordx4 v[32:35], v[32:33], off offset:960
	s_nop 0
	global_load_dwordx4 v[48:51], v[48:49], off offset:960
	s_waitcnt vmcnt(12)
	s_waitcnt lgkmcnt(3)
	v_mfma_f32_16x16x32_bf16 v[96:99], v[88:91], v[60:63], v[96:99]
	v_mfma_f32_16x16x32_bf16 v[100:103], v[88:91], v[52:55], v[100:103]
	v_mfma_f32_16x16x32_bf16 v[106:109], v[88:91], v[44:47], v[106:109]
	v_mfma_f32_16x16x32_bf16 v[88:91], v[88:91], v[40:43], v[130:133]
	s_waitcnt lgkmcnt(2)
	v_mfma_f32_16x16x32_bf16 v[130:133], v[110:113], v[60:63], v[134:137]
	v_mfma_f32_16x16x32_bf16 v[68:71], v[110:113], v[52:55], v[68:71]
	v_mfma_f32_16x16x32_bf16 v[76:79], v[110:113], v[44:47], v[76:79]
	v_mfma_f32_16x16x32_bf16 v[110:113], v[110:113], v[40:43], v[138:141]
	s_waitcnt lgkmcnt(1)
	v_mfma_f32_16x16x32_bf16 v[72:75], v[122:125], v[60:63], v[72:75]
	v_mfma_f32_16x16x32_bf16 v[80:83], v[122:125], v[52:55], v[80:83]
	v_mfma_f32_16x16x32_bf16 v[134:137], v[122:125], v[44:47], v[150:153]
	v_mfma_f32_16x16x32_bf16 v[122:125], v[122:125], v[40:43], v[142:145]
	s_waitcnt lgkmcnt(0)
	v_mfma_f32_16x16x32_bf16 v[60:63], v[126:129], v[60:63], v[118:121]
	v_mfma_f32_16x16x32_bf16 v[52:55], v[126:129], v[52:55], v[114:117]
	v_mfma_f32_16x16x32_bf16 v[44:47], v[126:129], v[44:47], v[92:95]
	v_mfma_f32_16x16x32_bf16 v[40:43], v[126:129], v[40:43], v[84:87]
	s_nop 2
	ds_read_b128 v[84:87], v67 offset:832
	ds_read_b128 v[92:95], v67 offset:17472
	ds_read_b128 v[114:117], v67 offset:34112
	ds_read_b128 v[118:121], v67 offset:50752
	s_waitcnt vmcnt(8)
	s_waitcnt lgkmcnt(3)
	v_mfma_f32_16x16x32_bf16 v[96:99], v[84:87], v[36:39], v[96:99]
	v_mfma_f32_16x16x32_bf16 v[100:103], v[84:87], v[28:31], v[100:103]
	v_mfma_f32_16x16x32_bf16 v[106:109], v[84:87], v[24:27], v[106:109]
	v_mfma_f32_16x16x32_bf16 v[84:87], v[84:87], v[8:11], v[88:91]
	s_waitcnt lgkmcnt(2)
; __device__ __forceinline__ float bf2f(unsigned short h) { return __uint_as_float(((unsigned)h) << 16); }
; __device__ __forceinline__ unsigned short f2bf(float f) { return (unsigned short)(cvt_pk(f, 0.f) & 0xffffu); }
; __device__ __forceinline__ float sigmoidf_(float x) { return fast_rcp(1.f + fast_exp2(-x * LOG2E)); }
; __device__ __forceinline__ void s5_unit(ArgsP A, int l, int unit, unsigned char* lds, int wave_, int lane_) {
;     ...
;                 for (int nb = 0; nb < 4; ++nb) acc[mb][nb] = __builtin_amdgcn_mfma_f32_16x16x32_bf16(af[mb], bq[ks & 3][nb], acc[mb][nb], 0, 0, 0);
;             if (ks + 4 < 16) {
; #pragma unroll
;                 for (int nb = 0; nb < 4; ++nb) bq[ks & 3][nb] = *(const bf16x8*)(wb + (size_t)(16 * nb) * 512 + 32 * (ks + 4));
;             }
;         }
;     }
;     bf16_t* MIX = (bf16_t*)(A->ws + WS_MIX);
;     float bglv[4];
; #pragma unroll
;     for (int nb = 0; nb < 4; ++nb) bglv[nb] = A->in[22][l * 512 + 64 * wave + 16 * nb + (lane & 15)];
; #pragma unroll
;     for (int nb = 0; nb < 4; ++nb) { const int n = 64 * wave + 16 * nb + (lane & 15); const float bgl = bglv[nb];
; #pragma unroll
;         for (int mb = 0; mb < 4; ++mb)
; #pragma unroll
;             for (int i = 0; i < 4; ++i) { const int t = 16 * mb + 4 * (lane >> 4) + i; const float yv = bf2f(ys[t * YS_STRIDE + n]);
;                 MIX[(size_t)(rowbase + t) * DM + n] = f2bf(yv * sigmoidf_(acc[mb][nb][i] + bgl)); } }
	v_mfma_f32_16x16x32_bf16 v[88:91], v[92:95], v[36:39], v[130:133]
	v_mfma_f32_16x16x32_bf16 v[68:71], v[92:95], v[28:31], v[68:71]
	v_mfma_f32_16x16x32_bf16 v[76:79], v[92:95], v[24:27], v[76:79]
	v_mfma_f32_16x16x32_bf16 v[92:95], v[92:95], v[8:11], v[110:113]
	s_waitcnt lgkmcnt(1)
	v_mfma_f32_16x16x32_bf16 v[72:75], v[114:117], v[36:39], v[72:75]
	v_mfma_f32_16x16x32_bf16 v[80:83], v[114:117], v[28:31], v[80:83]
	v_mfma_f32_16x16x32_bf16 v[110:113], v[114:117], v[24:27], v[134:137]
	v_mfma_f32_16x16x32_bf16 v[114:117], v[114:117], v[8:11], v[122:125]
	s_waitcnt lgkmcnt(0)
	v_mfma_f32_16x16x32_bf16 v[36:39], v[118:121], v[36:39], v[60:63]
	v_mfma_f32_16x16x32_bf16 v[28:31], v[118:121], v[28:31], v[52:55]
	v_mfma_f32_16x16x32_bf16 v[24:27], v[118:121], v[24:27], v[44:47]
	v_mfma_f32_16x16x32_bf16 v[8:11], v[118:121], v[8:11], v[40:43]
	s_nop 2
	ds_read_b128 v[40:43], v67 offset:896
	ds_read_b128 v[44:47], v67 offset:17536
	ds_read_b128 v[52:55], v67 offset:34176
	ds_read_b128 v[60:63], v67 offset:50816
	s_waitcnt vmcnt(4)
	s_waitcnt lgkmcnt(3)
	v_mfma_f32_16x16x32_bf16 v[96:99], v[40:43], v[20:23], v[96:99]
	v_mfma_f32_16x16x32_bf16 v[100:103], v[40:43], v[12:15], v[100:103]
	v_mfma_f32_16x16x32_bf16 v[106:109], v[40:43], v[4:7], v[106:109]
	v_mfma_f32_16x16x32_bf16 v[40:43], v[40:43], v[0:3], v[84:87]
	s_waitcnt lgkmcnt(2)
	v_mfma_f32_16x16x32_bf16 v[84:87], v[44:47], v[20:23], v[88:91]
	v_mfma_f32_16x16x32_bf16 v[76:79], v[44:47], v[4:7], v[76:79]
	v_mfma_f32_16x16x32_bf16 v[88:91], v[44:47], v[0:3], v[92:95]
	s_waitcnt lgkmcnt(1)
	v_mfma_f32_16x16x32_bf16 v[92:95], v[52:55], v[4:7], v[110:113]
	v_mfma_f32_16x16x32_bf16 v[110:113], v[52:55], v[0:3], v[114:117]
	s_waitcnt lgkmcnt(0)
	v_mfma_f32_16x16x32_bf16 v[122:125], v[60:63], v[4:7], v[24:27]
	v_mfma_f32_16x16x32_bf16 v[0:3], v[60:63], v[0:3], v[8:11]
	ds_read_b128 v[4:7], v67 offset:960
	s_nop 1
	ds_read_b128 v[8:11], v67 offset:17600
	ds_read_b128 v[126:129], v67 offset:34240
	ds_read_b128 v[130:133], v67 offset:50880
	s_waitcnt vmcnt(0)
	s_load_dwordx2 s[4:5], s[26:27], 0xb0
	v_mfma_f32_16x16x32_bf16 v[68:71], v[44:47], v[12:15], v[68:71]
	v_lshl_add_u32 v67, v64, 1, 16
	v_mfma_f32_16x16x32_bf16 v[80:83], v[52:55], v[12:15], v[80:83]
	v_mfma_f32_16x16x32_bf16 v[114:117], v[60:63], v[20:23], v[36:39]
	v_mfma_f32_16x16x32_bf16 v[118:121], v[60:63], v[12:15], v[28:31]
	s_waitcnt lgkmcnt(0)
	v_mfma_f32_16x16x32_bf16 v[134:137], v[4:7], v[48:51], v[96:99]
	v_mfma_f32_16x16x32_bf16 v[44:47], v[4:7], v[32:35], v[100:103]
	v_mfma_f32_16x16x32_bf16 v[28:31], v[4:7], v[16:19], v[106:109]
	v_mfma_f32_16x16x32_bf16 v[12:15], v[4:7], v[56:59], v[40:43]
	v_mfma_f32_16x16x32_bf16 v[60:63], v[8:11], v[48:51], v[84:87]
	v_mfma_f32_16x16x32_bf16 v[40:43], v[8:11], v[32:35], v[68:71]
	v_mfma_f32_16x16x32_bf16 v[24:27], v[8:11], v[16:19], v[76:79]
	v_mfma_f32_16x16x32_bf16 v[8:11], v[8:11], v[56:59], v[88:91]
	s_nop 1
	v_lshl_add_u64 v[76:77], v[64:65], 1, s[2:3]
	v_mfma_f32_16x16x32_bf16 v[4:7], v[126:129], v[56:59], v[110:113]
	v_mfma_f32_16x16x32_bf16 v[0:3], v[130:133], v[56:59], v[0:3]
	v_or_b32_e32 v56, s11, v104
	v_ashrrev_i32_e32 v57, 31, v56
	v_lshl_add_u64 v[56:57], v[56:57], 2, s[4:5]
	v_mfma_f32_16x16x32_bf16 v[72:75], v[52:55], v[20:23], v[72:75]
	s_movk_i32 s4, 0x1040
	v_mfma_f32_16x16x32_bf16 v[20:23], v[126:129], v[16:19], v[92:95]
	global_load_dword v97, v[56:57], off
	global_load_dword v96, v[56:57], off offset:64
	s_nop 0
	global_load_dword v94, v[56:57], off offset:128
	global_load_dword v92, v[56:57], off offset:192
	v_mad_u32_u24 v95, v66, s4, v67
	ds_read_u16 v57, v95
	v_lshlrev_b32_e32 v56, 2, v66
	v_mfma_f32_16x16x32_bf16 v[52:55], v[126:129], v[48:51], v[72:75]
	v_or_b32_e32 v70, 48, v56
	s_movk_i32 s4, 0x410
	s_waitcnt lgkmcnt(0)
	v_lshlrev_b32_e32 v57, 16, v57
	v_or_b32_e32 v74, s10, v56
	v_ashrrev_i32_e32 v75, 31, v74
	v_mfma_f32_16x16x32_bf16 v[36:39], v[126:129], v[32:35], v[80:83]
	s_waitcnt vmcnt(3)
	v_add_f32_e32 v58, v134, v97
	v_mul_f32_e32 v58, 0xbfb8aa3b, v58
	v_exp_f32_e32 v58, v58
	v_add_f32_e32 v60, v60, v97
	v_mul_f32_e32 v60, 0xbfb8aa3b, v60
	v_exp_f32_e32 v60, v60
	v_add_f32_e32 v58, 1.0, v58
	v_rcp_f32_e32 v58, v58
	v_add_f32_e32 v61, v61, v97
	v_add_f32_e32 v60, 1.0, v60
	v_rcp_f32_e32 v60, v60
	v_mul_f32_e32 v57, v58, v57
	v_cvt_pk_bf16_f32 v65, v57, s0
	v_lshlrev_b64 v[56:57], 12, v[74:75]
	v_lshl_add_u64 v[58:59], v[76:77], 0, v[56:57]
	global_store_short v[58:59], v65, off
	v_add_f32_e32 v59, v135, v97
	v_mul_f32_e32 v59, 0xbfb8aa3b, v59
	v_exp_f32_e32 v59, v59
	v_mad_u32_u24 v65, v70, s4, v67
	v_add_u32_e32 v93, 0xffff4110, v65
	ds_read_u16 v58, v93
	v_add_f32_e32 v59, 1.0, v59
	v_rcp_f32_e32 v59, v59
	v_mul_f32_e32 v61, 0xbfb8aa3b, v61
	v_exp_f32_e32 v61, v61
	s_waitcnt lgkmcnt(0)
	v_lshlrev_b32_e32 v58, 16, v58
	v_mul_f32_e32 v58, v59, v58
	v_cvt_pk_bf16_f32 v68, v58, s0
	v_or_b32_e32 v58, 1, v74
	v_ashrrev_i32_e32 v59, 31, v58
	v_lshlrev_b64 v[58:59], 12, v[58:59]
	v_lshl_add_u64 v[66:67], v[76:77], 0, v[58:59]
	global_store_short v[66:67], v68, off
	v_add_f32_e32 v67, v136, v97
	v_mul_f32_e32 v67, 0xbfb8aa3b, v67
	v_exp_f32_e32 v67, v67
	ds_read_u16 v66, v93 offset:1040
	v_add_f32_e32 v61, 1.0, v61
	v_rcp_f32_e32 v61, v61
	v_add_f32_e32 v67, 1.0, v67
	v_rcp_f32_e32 v67, v67
	s_waitcnt lgkmcnt(0)
	v_lshlrev_b32_e32 v66, 16, v66
	v_add_f32_e32 v62, v62, v97
	v_mul_f32_e32 v62, 0xbfb8aa3b, v62
	v_mul_f32_e32 v66, v67, v66
	v_cvt_pk_bf16_f32 v71, v66, s0
	v_or_b32_e32 v66, 2, v74
	v_ashrrev_i32_e32 v67, 31, v66
	v_lshlrev_b64 v[66:67], 12, v[66:67]
	v_lshl_add_u64 v[68:69], v[76:77], 0, v[66:67]
	global_store_short v[68:69], v71, off
	v_add_f32_e32 v69, v137, v97
	v_mul_f32_e32 v69, 0xbfb8aa3b, v69
	v_exp_f32_e32 v69, v69
	ds_read_u16 v68, v93 offset:2080
	v_exp_f32_e32 v62, v62
	v_add_f32_e32 v63, v63, v97
	v_add_f32_e32 v69, 1.0, v69
	v_rcp_f32_e32 v69, v69
	s_waitcnt lgkmcnt(0)
; __device__ __forceinline__ float bf2f(unsigned short h) { return __uint_as_float(((unsigned)h) << 16); }
; __device__ __forceinline__ unsigned short f2bf(float f) { return (unsigned short)(cvt_pk(f, 0.f) & 0xffffu); }
; __device__ __forceinline__ float sigmoidf_(float x) { return fast_rcp(1.f + fast_exp2(-x * LOG2E)); }
; __device__ __forceinline__ void s5_unit(ArgsP A, int l, int unit, unsigned char* lds, int wave_, int lane_) {
;     ...
;     float bglv[4];
; #pragma unroll
;     for (int nb = 0; nb < 4; ++nb) bglv[nb] = A->in[22][l * 512 + 64 * wave + 16 * nb + (lane & 15)];
; #pragma unroll
;     for (int nb = 0; nb < 4; ++nb) { const int n = 64 * wave + 16 * nb + (lane & 15); const float bgl = bglv[nb];
; #pragma unroll
;         for (int mb = 0; mb < 4; ++mb)
; #pragma unroll
;             for (int i = 0; i < 4; ++i) { const int t = 16 * mb + 4 * (lane >> 4) + i; const float yv = bf2f(ys[t * YS_STRIDE + n]);
;                 MIX[(size_t)(rowbase + t) * DM + n] = f2bf(yv * sigmoidf_(acc[mb][nb][i] + bgl)); } }
	v_lshlrev_b32_e32 v68, 16, v68
	v_add_f32_e32 v62, 1.0, v62
	v_rcp_f32_e32 v62, v62
	v_mul_f32_e32 v68, v69, v68
	v_cvt_pk_bf16_f32 v71, v68, s0
	v_or_b32_e32 v68, 3, v74
	v_ashrrev_i32_e32 v69, 31, v68
	v_lshlrev_b64 v[78:79], 12, v[68:69]
	v_lshl_add_u64 v[68:69], v[76:77], 0, v[78:79]
	global_store_short v[68:69], v71, off
	ds_read_u16 v68, v93 offset:15600
	v_mul_f32_e32 v63, 0xbfb8aa3b, v63
	v_exp_f32_e32 v63, v63
	v_add_f32_e32 v52, v52, v97
	v_mul_f32_e32 v52, 0xbfb8aa3b, v52
	s_waitcnt lgkmcnt(0)
	v_lshlrev_b32_e32 v68, 16, v68
	v_mul_f32_e32 v60, v60, v68
	v_or_b32_e32 v68, 16, v74
	v_ashrrev_i32_e32 v69, 31, v68
	v_lshlrev_b64 v[80:81], 12, v[68:69]
	v_cvt_pk_bf16_f32 v60, v60, s0
	v_lshl_add_u64 v[68:69], v[76:77], 0, v[80:81]
	global_store_short v[68:69], v60, off
	ds_read_u16 v60, v93 offset:16640
	v_add_f32_e32 v63, 1.0, v63
	v_rcp_f32_e32 v63, v63
	v_exp_f32_e32 v52, v52
	v_add_f32_e32 v53, v53, v97
	s_waitcnt lgkmcnt(0)
	v_lshlrev_b32_e32 v60, 16, v60
	v_mul_f32_e32 v60, v61, v60
	v_cvt_pk_bf16_f32 v71, v60, s0
	v_or_b32_e32 v60, 17, v74
	v_ashrrev_i32_e32 v61, 31, v60
	v_lshlrev_b64 v[60:61], 12, v[60:61]
	v_lshl_add_u64 v[68:69], v[76:77], 0, v[60:61]
	global_store_short v[68:69], v71, off
	ds_read_u16 v68, v93 offset:17680
	v_add_f32_e32 v52, 1.0, v52
	v_rcp_f32_e32 v52, v52
	v_mul_f32_e32 v53, 0xbfb8aa3b, v53
	v_exp_f32_e32 v53, v53
	s_waitcnt lgkmcnt(0)
	v_lshlrev_b32_e32 v68, 16, v68
	v_mul_f32_e32 v62, v62, v68
	v_or_b32_e32 v68, 18, v74
	v_ashrrev_i32_e32 v69, 31, v68
	v_lshlrev_b64 v[82:83], 12, v[68:69]
	v_cvt_pk_bf16_f32 v62, v62, s0
	v_lshl_add_u64 v[68:69], v[76:77], 0, v[82:83]
	global_store_short v[68:69], v62, off
	ds_read_u16 v62, v93 offset:18720
	v_add_f32_e32 v53, 1.0, v53
	v_rcp_f32_e32 v53, v53
	v_mfma_f32_16x16x32_bf16 v[48:51], v[130:133], v[48:51], v[114:117]
	s_waitcnt vmcnt(9)
	v_add_f32_e32 v44, v44, v96
	s_waitcnt lgkmcnt(0)
	v_lshlrev_b32_e32 v62, 16, v62
	v_mul_f32_e32 v62, v63, v62
	v_cvt_pk_bf16_f32 v71, v62, s0
	v_or_b32_e32 v62, 19, v74
	v_ashrrev_i32_e32 v63, 31, v62
	v_lshlrev_b64 v[62:63], 12, v[62:63]
	v_lshl_add_u64 v[68:69], v[76:77], 0, v[62:63]
	global_store_short v[68:69], v71, off
	ds_read_u16 v68, v93 offset:32240
	v_add_f32_e32 v48, v48, v97
	v_mul_f32_e32 v48, 0xbfb8aa3b, v48
	v_exp_f32_e32 v48, v48
	v_add_f32_e32 v49, v49, v97
	s_waitcnt lgkmcnt(0)
	v_lshlrev_b32_e32 v68, 16, v68
	v_mul_f32_e32 v52, v52, v68
	v_or_b32_e32 v68, 32, v74
	v_ashrrev_i32_e32 v69, 31, v68
	v_lshlrev_b64 v[84:85], 12, v[68:69]
	v_cvt_pk_bf16_f32 v52, v52, s0
	v_lshl_add_u64 v[68:69], v[76:77], 0, v[84:85]
	global_store_short v[68:69], v52, off
	ds_read_u16 v52, v93 offset:33280
	v_add_f32_e32 v48, 1.0, v48
	v_rcp_f32_e32 v48, v48
	v_mul_f32_e32 v49, 0xbfb8aa3b, v49
	v_exp_f32_e32 v49, v49
	s_waitcnt lgkmcnt(0)
	v_lshlrev_b32_e32 v52, 16, v52
	v_mul_f32_e32 v52, v53, v52
	v_cvt_pk_bf16_f32 v68, v52, s0
	v_or_b32_e32 v52, 33, v74
	v_ashrrev_i32_e32 v53, 31, v52
	v_lshlrev_b64 v[86:87], 12, v[52:53]
	v_lshl_add_u64 v[52:53], v[76:77], 0, v[86:87]
	global_store_short v[52:53], v68, off
	v_add_f32_e32 v53, v54, v97
	v_mul_f32_e32 v53, 0xbfb8aa3b, v53
	v_exp_f32_e32 v53, v53
	ds_read_u16 v52, v93 offset:34320
	v_add_f32_e32 v49, 1.0, v49
	v_rcp_f32_e32 v49, v49
	v_add_f32_e32 v53, 1.0, v53
	v_rcp_f32_e32 v53, v53
	s_waitcnt lgkmcnt(0)
	v_lshlrev_b32_e32 v52, 16, v52
	v_mul_f32_e32 v44, 0xbfb8aa3b, v44
	v_exp_f32_e32 v44, v44
	v_mul_f32_e32 v52, v53, v52
	v_cvt_pk_bf16_f32 v54, v52, s0
	v_or_b32_e32 v52, 34, v74
	v_ashrrev_i32_e32 v53, 31, v52
	v_lshlrev_b64 v[88:89], 12, v[52:53]
	v_lshl_add_u64 v[52:53], v[76:77], 0, v[88:89]
	global_store_short v[52:53], v54, off
	v_add_f32_e32 v53, v55, v97
	v_mul_f32_e32 v53, 0xbfb8aa3b, v53
	v_exp_f32_e32 v53, v53
	ds_read_u16 v52, v93 offset:35360
	v_add_f32_e32 v44, 1.0, v44
	v_rcp_f32_e32 v44, v44
	v_add_f32_e32 v53, 1.0, v53
	v_rcp_f32_e32 v53, v53
	s_waitcnt lgkmcnt(0)
	v_lshlrev_b32_e32 v52, 16, v52
	v_add_f32_e32 v45, v45, v96
	v_mul_f32_e32 v45, 0xbfb8aa3b, v45
	v_mul_f32_e32 v52, v53, v52
	v_cvt_pk_bf16_f32 v54, v52, s0
	v_or_b32_e32 v52, 35, v74
	v_ashrrev_i32_e32 v53, 31, v52
	v_lshlrev_b64 v[90:91], 12, v[52:53]
	v_lshl_add_u64 v[52:53], v[76:77], 0, v[90:91]
	global_store_short v[52:53], v54, off
	ds_read_u16 v52, v65
	v_exp_f32_e32 v45, v45
	v_add_f32_e32 v46, v46, v96
	v_mul_f32_e32 v46, 0xbfb8aa3b, v46
	v_exp_f32_e32 v46, v46
	s_waitcnt lgkmcnt(0)
	v_lshlrev_b32_e32 v52, 16, v52
	v_mul_f32_e32 v48, v48, v52
	v_or_b32_e32 v52, s10, v70
	v_ashrrev_i32_e32 v53, 31, v52
	v_lshlrev_b64 v[68:69], 12, v[52:53]
	v_cvt_pk_bf16_f32 v48, v48, s0
	v_lshl_add_u64 v[52:53], v[76:77], 0, v[68:69]
	global_store_short v[52:53], v48, off
	ds_read_u16 v48, v65 offset:1040
	v_add_f32_e32 v45, 1.0, v45
	v_rcp_f32_e32 v45, v45
	v_add_f32_e32 v46, 1.0, v46
	v_rcp_f32_e32 v46, v46
	s_waitcnt lgkmcnt(0)
	v_lshlrev_b32_e32 v48, 16, v48
	v_mul_f32_e32 v48, v49, v48
	v_cvt_pk_bf16_f32 v52, v48, s0
	v_or_b32_e32 v48, 49, v74
	v_ashrrev_i32_e32 v49, 31, v48
	v_lshlrev_b64 v[70:71], 12, v[48:49]
	v_lshl_add_u64 v[48:49], v[76:77], 0, v[70:71]
	global_store_short v[48:49], v52, off
	v_add_f32_e32 v49, v50, v97
	v_mul_f32_e32 v49, 0xbfb8aa3b, v49
	v_exp_f32_e32 v49, v49
	ds_read_u16 v48, v65 offset:2080
	v_add_f32_e32 v47, v47, v96
	v_mul_f32_e32 v47, 0xbfb8aa3b, v47
	v_add_f32_e32 v49, 1.0, v49
	v_rcp_f32_e32 v49, v49
	s_waitcnt lgkmcnt(0)
; __device__ __forceinline__ float bf2f(unsigned short h) { return __uint_as_float(((unsigned)h) << 16); }
; __device__ __forceinline__ unsigned short f2bf(float f) { return (unsigned short)(cvt_pk(f, 0.f) & 0xffffu); }
; __device__ __forceinline__ float sigmoidf_(float x) { return fast_rcp(1.f + fast_exp2(-x * LOG2E)); }
; __device__ __forceinline__ void s5_unit(ArgsP A, int l, int unit, unsigned char* lds, int wave_, int lane_) {
;     ...
;     float bglv[4];
; #pragma unroll
;     for (int nb = 0; nb < 4; ++nb) bglv[nb] = A->in[22][l * 512 + 64 * wave + 16 * nb + (lane & 15)];
; #pragma unroll
;     for (int nb = 0; nb < 4; ++nb) { const int n = 64 * wave + 16 * nb + (lane & 15); const float bgl = bglv[nb];
; #pragma unroll
;         for (int mb = 0; mb < 4; ++mb)
; #pragma unroll
;             for (int i = 0; i < 4; ++i) { const int t = 16 * mb + 4 * (lane >> 4) + i; const float yv = bf2f(ys[t * YS_STRIDE + n]);
;                 MIX[(size_t)(rowbase + t) * DM + n] = f2bf(yv * sigmoidf_(acc[mb][nb][i] + bgl)); } }
	v_lshlrev_b32_e32 v48, 16, v48
	v_exp_f32_e32 v47, v47
	v_add_f32_e32 v40, v40, v96
	v_mul_f32_e32 v48, v49, v48
	v_cvt_pk_bf16_f32 v50, v48, s0
	v_or_b32_e32 v48, 50, v74
	v_ashrrev_i32_e32 v49, 31, v48
	v_lshlrev_b64 v[72:73], 12, v[48:49]
	v_lshl_add_u64 v[48:49], v[76:77], 0, v[72:73]
	global_store_short v[48:49], v50, off
	v_add_f32_e32 v49, v51, v97
	v_mul_f32_e32 v49, 0xbfb8aa3b, v49
	v_exp_f32_e32 v49, v49
	ds_read_u16 v48, v65 offset:3120
	v_add_f32_e32 v47, 1.0, v47
	v_rcp_f32_e32 v47, v47
	v_add_f32_e32 v49, 1.0, v49
	v_rcp_f32_e32 v49, v49
	s_waitcnt lgkmcnt(0)
	v_lshlrev_b32_e32 v48, 16, v48
	v_mul_f32_e32 v40, 0xbfb8aa3b, v40
	v_exp_f32_e32 v40, v40
	v_mul_f32_e32 v48, v49, v48
	v_cvt_pk_bf16_f32 v50, v48, s0
	v_or_b32_e32 v48, 51, v74
	v_ashrrev_i32_e32 v49, 31, v48
	v_lshlrev_b64 v[74:75], 12, v[48:49]
	v_lshl_add_u64 v[48:49], v[76:77], 0, v[74:75]
	global_store_short v[48:49], v50, off
	ds_read_u16 v48, v95 offset:32
	v_or_b32_e32 v50, 16, v64
	v_ashrrev_i32_e32 v51, 31, v50
	v_lshlrev_b64 v[76:77], 1, v[50:51]
	v_add_f32_e32 v40, 1.0, v40
	s_waitcnt lgkmcnt(0)
	v_lshlrev_b32_e32 v48, 16, v48
	v_mul_f32_e32 v44, v44, v48
	v_lshl_add_u64 v[48:49], s[2:3], 0, v[56:57]
	v_cvt_pk_bf16_f32 v44, v44, s0
	v_lshl_add_u64 v[50:51], v[48:49], 0, v[76:77]
	global_store_short v[50:51], v44, off
	ds_read_u16 v44, v93 offset:32
	v_rcp_f32_e32 v40, v40
	v_add_f32_e32 v41, v41, v96
	v_mul_f32_e32 v41, 0xbfb8aa3b, v41
	v_exp_f32_e32 v41, v41
	s_waitcnt lgkmcnt(0)
	v_lshlrev_b32_e32 v44, 16, v44
	v_mul_f32_e32 v44, v45, v44
	v_cvt_pk_bf16_f32 v52, v44, s0
	v_lshl_add_u64 v[44:45], s[2:3], 0, v[58:59]
	v_lshl_add_u64 v[50:51], v[44:45], 0, v[76:77]
	global_store_short v[50:51], v52, off
	ds_read_u16 v50, v93 offset:1072
	v_add_f32_e32 v41, 1.0, v41
	v_rcp_f32_e32 v41, v41
	v_add_f32_e32 v36, v36, v96
	v_mul_f32_e32 v36, 0xbfb8aa3b, v36
	s_waitcnt lgkmcnt(0)
	v_lshlrev_b32_e32 v50, 16, v50
	v_mul_f32_e32 v46, v46, v50
	v_lshl_add_u64 v[50:51], s[2:3], 0, v[66:67]
	v_cvt_pk_bf16_f32 v46, v46, s0
	v_lshl_add_u64 v[52:53], v[50:51], 0, v[76:77]
	global_store_short v[52:53], v46, off
	ds_read_u16 v46, v93 offset:2112
	v_exp_f32_e32 v36, v36
	v_add_f32_e32 v37, v37, v96
	v_mul_f32_e32 v37, 0xbfb8aa3b, v37
	v_exp_f32_e32 v37, v37
	s_waitcnt lgkmcnt(0)
	v_lshlrev_b32_e32 v46, 16, v46
	v_mul_f32_e32 v46, v47, v46
	v_cvt_pk_bf16_f32 v54, v46, s0
	v_lshl_add_u64 v[46:47], s[2:3], 0, v[78:79]
	v_lshl_add_u64 v[52:53], v[46:47], 0, v[76:77]
	global_store_short v[52:53], v54, off
	ds_read_u16 v52, v93 offset:15632
	v_add_f32_e32 v36, 1.0, v36
	v_rcp_f32_e32 v36, v36
	v_add_f32_e32 v37, 1.0, v37
	v_rcp_f32_e32 v37, v37
	s_waitcnt lgkmcnt(0)
	v_lshlrev_b32_e32 v52, 16, v52
	v_mul_f32_e32 v40, v40, v52
	v_lshl_add_u64 v[52:53], s[2:3], 0, v[80:81]
	v_cvt_pk_bf16_f32 v40, v40, s0
	v_lshl_add_u64 v[54:55], v[52:53], 0, v[76:77]
	global_store_short v[54:55], v40, off
	ds_read_u16 v40, v93 offset:16672
	v_lshl_add_u64 v[54:55], s[2:3], 0, v[60:61]
	v_lshl_add_u64 v[60:61], s[2:3], 0, v[86:87]
	v_mfma_f32_16x16x32_bf16 v[32:35], v[130:133], v[32:35], v[118:121]
	v_lshl_add_u64 v[66:67], s[2:3], 0, v[90:91]
	s_waitcnt lgkmcnt(0)
	v_lshlrev_b32_e32 v40, 16, v40
	v_mul_f32_e32 v40, v41, v40
	v_cvt_pk_bf16_f32 v56, v40, s0
	v_lshl_add_u64 v[40:41], v[54:55], 0, v[76:77]
	global_store_short v[40:41], v56, off
	v_add_f32_e32 v41, v42, v96
	v_mul_f32_e32 v41, 0xbfb8aa3b, v41
	v_exp_f32_e32 v41, v41
	ds_read_u16 v40, v93 offset:17712
	v_lshl_add_u64 v[56:57], s[2:3], 0, v[82:83]
	v_add_f32_e32 v32, v32, v96
	v_add_f32_e32 v41, 1.0, v41
	v_rcp_f32_e32 v41, v41
	s_waitcnt lgkmcnt(0)
	v_lshlrev_b32_e32 v40, 16, v40
	v_mul_f32_e32 v32, 0xbfb8aa3b, v32
	v_exp_f32_e32 v32, v32
	v_mul_f32_e32 v40, v41, v40
	v_cvt_pk_bf16_f32 v42, v40, s0
	v_lshl_add_u64 v[40:41], v[56:57], 0, v[76:77]
	global_store_short v[40:41], v42, off
	v_add_f32_e32 v41, v43, v96
	v_mul_f32_e32 v41, 0xbfb8aa3b, v41
	v_exp_f32_e32 v41, v41
	ds_read_u16 v40, v93 offset:18752
	v_lshl_add_u64 v[42:43], s[2:3], 0, v[62:63]
	v_lshl_add_u64 v[62:63], s[2:3], 0, v[88:89]
	v_add_f32_e32 v41, 1.0, v41
	v_rcp_f32_e32 v41, v41
	s_waitcnt lgkmcnt(0)
	v_lshlrev_b32_e32 v40, 16, v40
	v_add_f32_e32 v32, 1.0, v32
	v_rcp_f32_e32 v32, v32
	v_mul_f32_e32 v40, v41, v40
	v_cvt_pk_bf16_f32 v58, v40, s0
	v_lshl_add_u64 v[40:41], v[42:43], 0, v[76:77]
	global_store_short v[40:41], v58, off
	ds_read_u16 v40, v93 offset:32272
	v_lshl_add_u64 v[58:59], s[2:3], 0, v[84:85]
	v_add_f32_e32 v33, v33, v96
	v_mul_f32_e32 v33, 0xbfb8aa3b, v33
	v_exp_f32_e32 v33, v33
	s_waitcnt lgkmcnt(0)
	v_lshlrev_b32_e32 v40, 16, v40
	v_mul_f32_e32 v36, v36, v40
	v_cvt_pk_bf16_f32 v36, v36, s0
	v_lshl_add_u64 v[40:41], v[58:59], 0, v[76:77]
	global_store_short v[40:41], v36, off
	ds_read_u16 v36, v93 offset:33312
	v_add_f32_e32 v33, 1.0, v33
	v_rcp_f32_e32 v33, v33
	s_waitcnt vmcnt(26)
	v_add_f32_e32 v28, v28, v94
	v_mul_f32_e32 v28, 0xbfb8aa3b, v28
	s_waitcnt lgkmcnt(0)
	v_lshlrev_b32_e32 v36, 16, v36
	v_mul_f32_e32 v36, v37, v36
	v_cvt_pk_bf16_f32 v40, v36, s0
	v_lshl_add_u64 v[36:37], v[60:61], 0, v[76:77]
	global_store_short v[36:37], v40, off
	v_add_f32_e32 v37, v38, v96
	v_mul_f32_e32 v37, 0xbfb8aa3b, v37
	v_exp_f32_e32 v37, v37
	ds_read_u16 v36, v93 offset:34352
	v_exp_f32_e32 v28, v28
	v_add_f32_e32 v29, v29, v94
	v_add_f32_e32 v37, 1.0, v37
	v_rcp_f32_e32 v37, v37
	s_waitcnt lgkmcnt(0)
	v_lshlrev_b32_e32 v36, 16, v36
	v_add_f32_e32 v28, 1.0, v28
	v_rcp_f32_e32 v28, v28
	v_mul_f32_e32 v36, v37, v36
	v_cvt_pk_bf16_f32 v38, v36, s0
	v_lshl_add_u64 v[36:37], v[62:63], 0, v[76:77]
	global_store_short v[36:37], v38, off
	v_add_f32_e32 v37, v39, v96
	v_mul_f32_e32 v37, 0xbfb8aa3b, v37
	v_exp_f32_e32 v37, v37
	ds_read_u16 v36, v93 offset:35392
	v_mul_f32_e32 v29, 0xbfb8aa3b, v29
	v_exp_f32_e32 v29, v29
	v_add_f32_e32 v37, 1.0, v37
	v_rcp_f32_e32 v37, v37
	s_waitcnt lgkmcnt(0)
; __device__ __forceinline__ float bf2f(unsigned short h) { return __uint_as_float(((unsigned)h) << 16); }
; __device__ __forceinline__ unsigned short f2bf(float f) { return (unsigned short)(cvt_pk(f, 0.f) & 0xffffu); }
; __device__ __forceinline__ float sigmoidf_(float x) { return fast_rcp(1.f + fast_exp2(-x * LOG2E)); }
; __device__ __forceinline__ void s5_unit(ArgsP A, int l, int unit, unsigned char* lds, int wave_, int lane_) {
;     ...
;     float bglv[4];
; #pragma unroll
;     for (int nb = 0; nb < 4; ++nb) bglv[nb] = A->in[22][l * 512 + 64 * wave + 16 * nb + (lane & 15)];
; #pragma unroll
;     for (int nb = 0; nb < 4; ++nb) { const int n = 64 * wave + 16 * nb + (lane & 15); const float bgl = bglv[nb];
; #pragma unroll
;         for (int mb = 0; mb < 4; ++mb)
; #pragma unroll
;             for (int i = 0; i < 4; ++i) { const int t = 16 * mb + 4 * (lane >> 4) + i; const float yv = bf2f(ys[t * YS_STRIDE + n]);
;                 MIX[(size_t)(rowbase + t) * DM + n] = f2bf(yv * sigmoidf_(acc[mb][nb][i] + bgl)); } }
	v_lshlrev_b32_e32 v36, 16, v36
	v_add_f32_e32 v29, 1.0, v29
	v_rcp_f32_e32 v29, v29
	v_mul_f32_e32 v36, v37, v36
	v_cvt_pk_bf16_f32 v38, v36, s0
	v_lshl_add_u64 v[36:37], v[66:67], 0, v[76:77]
	global_store_short v[36:37], v38, off
	ds_read_u16 v36, v65 offset:32
	v_add_f32_e32 v24, v24, v94
	v_mul_f32_e32 v24, 0xbfb8aa3b, v24
	v_exp_f32_e32 v24, v24
	v_add_f32_e32 v25, v25, v94
	s_waitcnt lgkmcnt(0)
	v_lshlrev_b32_e32 v36, 16, v36
	v_mul_f32_e32 v32, v32, v36
	v_lshl_add_u64 v[36:37], s[2:3], 0, v[68:69]
	v_cvt_pk_bf16_f32 v32, v32, s0
	v_lshl_add_u64 v[38:39], v[36:37], 0, v[76:77]
	global_store_short v[38:39], v32, off
	ds_read_u16 v32, v65 offset:1072
	v_lshl_add_u64 v[38:39], s[2:3], 0, v[70:71]
	v_add_f32_e32 v24, 1.0, v24
	v_rcp_f32_e32 v24, v24
	v_mul_f32_e32 v25, 0xbfb8aa3b, v25
	s_waitcnt lgkmcnt(0)
	v_lshlrev_b32_e32 v32, 16, v32
	v_mul_f32_e32 v32, v33, v32
	v_cvt_pk_bf16_f32 v40, v32, s0
	v_lshl_add_u64 v[32:33], v[38:39], 0, v[76:77]
	global_store_short v[32:33], v40, off
	v_add_f32_e32 v33, v34, v96
	v_mul_f32_e32 v33, 0xbfb8aa3b, v33
	v_exp_f32_e32 v33, v33
	ds_read_u16 v32, v65 offset:2112
	v_lshl_add_u64 v[40:41], s[2:3], 0, v[72:73]
	v_exp_f32_e32 v25, v25
	v_add_f32_e32 v33, 1.0, v33
	v_rcp_f32_e32 v33, v33
	s_waitcnt lgkmcnt(0)
	v_lshlrev_b32_e32 v32, 16, v32
	v_add_f32_e32 v25, 1.0, v25
	v_rcp_f32_e32 v25, v25
	v_mul_f32_e32 v32, v33, v32
	v_cvt_pk_bf16_f32 v34, v32, s0
	v_lshl_add_u64 v[32:33], v[40:41], 0, v[76:77]
	global_store_short v[32:33], v34, off
	v_add_f32_e32 v33, v35, v96
	v_mul_f32_e32 v33, 0xbfb8aa3b, v33
	v_exp_f32_e32 v33, v33
	ds_read_u16 v32, v65 offset:3152
	v_add_f32_e32 v20, v20, v94
	v_mul_f32_e32 v20, 0xbfb8aa3b, v20
	v_add_f32_e32 v33, 1.0, v33
	v_rcp_f32_e32 v33, v33
	s_waitcnt lgkmcnt(0)
	v_lshlrev_b32_e32 v32, 16, v32
	v_exp_f32_e32 v20, v20
	v_add_f32_e32 v21, v21, v94
	v_mul_f32_e32 v32, v33, v32
	v_cvt_pk_bf16_f32 v68, v32, s0
	v_lshl_add_u64 v[32:33], s[2:3], 0, v[74:75]
	v_lshl_add_u64 v[34:35], v[32:33], 0, v[76:77]
	global_store_short v[34:35], v68, off
	ds_read_u16 v68, v95 offset:64
	v_or_b32_e32 v34, 32, v64
	v_ashrrev_i32_e32 v35, 31, v34
	v_lshlrev_b64 v[34:35], 1, v[34:35]
	v_add_f32_e32 v20, 1.0, v20
	s_waitcnt lgkmcnt(0)
	v_lshlrev_b32_e32 v68, 16, v68
	v_mul_f32_e32 v28, v28, v68
	v_cvt_pk_bf16_f32 v28, v28, s0
	v_lshl_add_u64 v[68:69], v[48:49], 0, v[34:35]
	global_store_short v[68:69], v28, off
	ds_read_u16 v28, v93 offset:64
	v_rcp_f32_e32 v20, v20
	v_mul_f32_e32 v21, 0xbfb8aa3b, v21
	v_exp_f32_e32 v21, v21
	v_mfma_f32_16x16x32_bf16 v[16:19], v[130:133], v[16:19], v[122:125]
	s_waitcnt lgkmcnt(0)
	v_lshlrev_b32_e32 v28, 16, v28
	v_mul_f32_e32 v28, v29, v28
	v_cvt_pk_bf16_f32 v68, v28, s0
	v_lshl_add_u64 v[28:29], v[44:45], 0, v[34:35]
	global_store_short v[28:29], v68, off
	v_add_f32_e32 v29, v30, v94
	v_mul_f32_e32 v29, 0xbfb8aa3b, v29
	v_exp_f32_e32 v29, v29
	ds_read_u16 v28, v93 offset:1104
	v_add_f32_e32 v21, 1.0, v21
	v_rcp_f32_e32 v21, v21
	v_add_f32_e32 v29, 1.0, v29
	v_rcp_f32_e32 v29, v29
	s_waitcnt lgkmcnt(0)
	v_lshlrev_b32_e32 v28, 16, v28
	v_add_f32_e32 v16, v16, v94
	v_mul_f32_e32 v16, 0xbfb8aa3b, v16
	v_mul_f32_e32 v28, v29, v28
	v_cvt_pk_bf16_f32 v30, v28, s0
	v_lshl_add_u64 v[28:29], v[50:51], 0, v[34:35]
	global_store_short v[28:29], v30, off
	v_add_f32_e32 v29, v31, v94
	v_mul_f32_e32 v29, 0xbfb8aa3b, v29
	v_exp_f32_e32 v29, v29
	ds_read_u16 v28, v93 offset:2144
	v_exp_f32_e32 v16, v16
	v_add_f32_e32 v17, v17, v94
	v_add_f32_e32 v29, 1.0, v29
	v_rcp_f32_e32 v29, v29
	s_waitcnt lgkmcnt(0)
	v_lshlrev_b32_e32 v28, 16, v28
	v_add_f32_e32 v16, 1.0, v16
	v_rcp_f32_e32 v16, v16
	v_mul_f32_e32 v28, v29, v28
	v_cvt_pk_bf16_f32 v30, v28, s0
	v_lshl_add_u64 v[28:29], v[46:47], 0, v[34:35]
	global_store_short v[28:29], v30, off
	ds_read_u16 v28, v93 offset:15664
	v_mul_f32_e32 v17, 0xbfb8aa3b, v17
	v_exp_f32_e32 v17, v17
	s_waitcnt vmcnt(36)
	v_add_f32_e32 v12, v12, v92
	v_mul_f32_e32 v12, 0xbfb8aa3b, v12
	s_waitcnt lgkmcnt(0)
	v_lshlrev_b32_e32 v28, 16, v28
	v_mul_f32_e32 v24, v24, v28
	v_cvt_pk_bf16_f32 v24, v24, s0
	v_lshl_add_u64 v[28:29], v[52:53], 0, v[34:35]
	global_store_short v[28:29], v24, off
	ds_read_u16 v24, v93 offset:16704
	v_add_f32_e32 v17, 1.0, v17
	v_rcp_f32_e32 v17, v17
	v_exp_f32_e32 v12, v12
	v_add_f32_e32 v13, v13, v92
	s_waitcnt lgkmcnt(0)
	v_lshlrev_b32_e32 v24, 16, v24
	v_mul_f32_e32 v24, v25, v24
	v_cvt_pk_bf16_f32 v28, v24, s0
	v_lshl_add_u64 v[24:25], v[54:55], 0, v[34:35]
	global_store_short v[24:25], v28, off
	v_add_f32_e32 v25, v26, v94
	v_mul_f32_e32 v25, 0xbfb8aa3b, v25
	v_exp_f32_e32 v25, v25
	ds_read_u16 v24, v93 offset:17744
	v_add_f32_e32 v12, 1.0, v12
	v_rcp_f32_e32 v12, v12
	v_add_f32_e32 v25, 1.0, v25
	v_rcp_f32_e32 v25, v25
	s_waitcnt lgkmcnt(0)
	v_lshlrev_b32_e32 v24, 16, v24
	v_mul_f32_e32 v13, 0xbfb8aa3b, v13
	v_exp_f32_e32 v13, v13
	v_mul_f32_e32 v24, v25, v24
	v_cvt_pk_bf16_f32 v26, v24, s0
	v_lshl_add_u64 v[24:25], v[56:57], 0, v[34:35]
	global_store_short v[24:25], v26, off
	v_add_f32_e32 v25, v27, v94
	v_mul_f32_e32 v25, 0xbfb8aa3b, v25
	v_exp_f32_e32 v25, v25
	ds_read_u16 v24, v93 offset:18784
	v_add_f32_e32 v13, 1.0, v13
	v_rcp_f32_e32 v13, v13
	v_add_f32_e32 v25, 1.0, v25
	v_rcp_f32_e32 v25, v25
	s_waitcnt lgkmcnt(0)
	v_lshlrev_b32_e32 v24, 16, v24
	v_add_f32_e32 v8, v8, v92
	v_mul_f32_e32 v8, 0xbfb8aa3b, v8
	v_mul_f32_e32 v24, v25, v24
	v_cvt_pk_bf16_f32 v26, v24, s0
	v_lshl_add_u64 v[24:25], v[42:43], 0, v[34:35]
	global_store_short v[24:25], v26, off
	ds_read_u16 v24, v93 offset:32304
	v_exp_f32_e32 v8, v8
	v_add_f32_e32 v9, v9, v92
	v_mul_f32_e32 v9, 0xbfb8aa3b, v9
	v_exp_f32_e32 v9, v9
	s_waitcnt lgkmcnt(0)
; __device__ __forceinline__ float bf2f(unsigned short h) { return __uint_as_float(((unsigned)h) << 16); }
; __device__ __forceinline__ unsigned short f2bf(float f) { return (unsigned short)(cvt_pk(f, 0.f) & 0xffffu); }
; __device__ __forceinline__ float sigmoidf_(float x) { return fast_rcp(1.f + fast_exp2(-x * LOG2E)); }
; #define QLOOP2(qi_, r2_, n_, ...) for (;;) { if (tid == 0) s_item = (int)atomicAdd(ctr + 64 * (qi_) + 32 * (r2_), 1u); __syncthreads(); const int item = s_item; __syncthreads(); if (item >= (n_)) break; __VA_ARGS__ }
; __device__ __forceinline__ void s5_unit(ArgsP A, int l, int unit, unsigned char* lds, int wave_, int lane_) {
;     ...
;     for (int nb = 0; nb < 4; ++nb) { const int n = 64 * wave + 16 * nb + (lane & 15); const float bgl = bglv[nb];
; #pragma unroll
;         for (int mb = 0; mb < 4; ++mb)
; #pragma unroll
;             for (int i = 0; i < 4; ++i) { const int t = 16 * mb + 4 * (lane >> 4) + i; const float yv = bf2f(ys[t * YS_STRIDE + n]);
;                 MIX[(size_t)(rowbase + t) * DM + n] = f2bf(yv * sigmoidf_(acc[mb][nb][i] + bgl)); } }
; template <int PHM, int MIXM>
; __global__ void __launch_bounds__(512, 2) mega(Args Aval) {
;     ...
;             for (int r2 = 0; r2 < ((PROBE_DUP & 16) ? 2 : 1); ++r2) if (MIXM & 1) QLOOP2(0, r2, 256, { const int L = 15 - (item >> 4), r = item & 15; flash_unit<0>(A, l, r >> 2, r & 3, L, lds); })
;             for (int r2 = 0; r2 < ((PROBE_DUP & 32) ? 2 : 1); ++r2) if (MIXM & 2) QLOOP2(1, r2, 256, { const int L = 15 - (item >> 4), r = item & 15; flash_unit<2>(A, l, r >> 2, r & 3, L, lds); })
;             for (int r2 = 0; r2 < ((PROBE_DUP & 64) ? 2 : 1); ++r2) if (MIXM & 8) QLOOP2(2, r2, 256, { s5_unit(A, l, item, lds, wave, lane); })
	v_lshlrev_b32_e32 v24, 16, v24
	v_mul_f32_e32 v20, v20, v24
	v_cvt_pk_bf16_f32 v20, v20, s0
	v_lshl_add_u64 v[24:25], v[58:59], 0, v[34:35]
	global_store_short v[24:25], v20, off
	ds_read_u16 v20, v93 offset:33344
	v_add_f32_e32 v8, 1.0, v8
	v_rcp_f32_e32 v8, v8
	v_add_f32_e32 v9, 1.0, v9
	v_rcp_f32_e32 v9, v9
	s_waitcnt lgkmcnt(0)
	v_lshlrev_b32_e32 v20, 16, v20
	v_mul_f32_e32 v20, v21, v20
	v_cvt_pk_bf16_f32 v24, v20, s0
	v_lshl_add_u64 v[20:21], v[60:61], 0, v[34:35]
	global_store_short v[20:21], v24, off
	v_add_f32_e32 v21, v22, v94
	v_mul_f32_e32 v21, 0xbfb8aa3b, v21
	v_exp_f32_e32 v21, v21
	ds_read_u16 v20, v93 offset:34384
	v_add_f32_e32 v4, v4, v92
	v_mul_f32_e32 v4, 0xbfb8aa3b, v4
	v_add_f32_e32 v21, 1.0, v21
	v_rcp_f32_e32 v21, v21
	s_waitcnt lgkmcnt(0)
	v_lshlrev_b32_e32 v20, 16, v20
	v_exp_f32_e32 v4, v4
	v_add_f32_e32 v5, v5, v92
	v_mul_f32_e32 v20, v21, v20
	v_cvt_pk_bf16_f32 v22, v20, s0
	v_lshl_add_u64 v[20:21], v[62:63], 0, v[34:35]
	global_store_short v[20:21], v22, off
	v_add_f32_e32 v21, v23, v94
	v_mul_f32_e32 v21, 0xbfb8aa3b, v21
	v_exp_f32_e32 v21, v21
	ds_read_u16 v20, v93 offset:35424
	v_add_f32_e32 v4, 1.0, v4
	v_rcp_f32_e32 v4, v4
	v_add_f32_e32 v21, 1.0, v21
	v_rcp_f32_e32 v21, v21
	s_waitcnt lgkmcnt(0)
	v_lshlrev_b32_e32 v20, 16, v20
	v_mul_f32_e32 v5, 0xbfb8aa3b, v5
	v_exp_f32_e32 v5, v5
	v_mul_f32_e32 v20, v21, v20
	v_cvt_pk_bf16_f32 v22, v20, s0
	v_lshl_add_u64 v[20:21], v[66:67], 0, v[34:35]
	global_store_short v[20:21], v22, off
	ds_read_u16 v20, v65 offset:64
	v_add_f32_e32 v5, 1.0, v5
	v_rcp_f32_e32 v5, v5
	v_add_f32_e32 v0, v0, v92
	v_mul_f32_e32 v0, 0xbfb8aa3b, v0
	s_waitcnt lgkmcnt(0)
	v_lshlrev_b32_e32 v20, 16, v20
	v_mul_f32_e32 v16, v16, v20
	v_cvt_pk_bf16_f32 v16, v16, s0
	v_lshl_add_u64 v[20:21], v[36:37], 0, v[34:35]
	global_store_short v[20:21], v16, off
	ds_read_u16 v16, v65 offset:1104
	v_exp_f32_e32 v0, v0
	v_add_f32_e32 v1, v1, v92
	v_mul_f32_e32 v1, 0xbfb8aa3b, v1
	v_exp_f32_e32 v1, v1
	s_waitcnt lgkmcnt(0)
	v_lshlrev_b32_e32 v16, 16, v16
	v_mul_f32_e32 v16, v17, v16
	v_cvt_pk_bf16_f32 v20, v16, s0
	v_lshl_add_u64 v[16:17], v[38:39], 0, v[34:35]
	global_store_short v[16:17], v20, off
	v_add_f32_e32 v17, v18, v94
	v_mul_f32_e32 v17, 0xbfb8aa3b, v17
	v_exp_f32_e32 v17, v17
	ds_read_u16 v16, v65 offset:2144
	v_add_f32_e32 v0, 1.0, v0
	v_rcp_f32_e32 v0, v0
	v_add_f32_e32 v17, 1.0, v17
	v_rcp_f32_e32 v17, v17
	s_waitcnt lgkmcnt(0)
	v_lshlrev_b32_e32 v16, 16, v16
	v_add_f32_e32 v1, 1.0, v1
	v_rcp_f32_e32 v1, v1
	v_mul_f32_e32 v16, v17, v16
	v_cvt_pk_bf16_f32 v18, v16, s0
	v_lshl_add_u64 v[16:17], v[40:41], 0, v[34:35]
	global_store_short v[16:17], v18, off
	v_add_f32_e32 v17, v19, v94
	v_mul_f32_e32 v17, 0xbfb8aa3b, v17
	v_exp_f32_e32 v17, v17
	ds_read_u16 v16, v65 offset:3184
	s_mov_b64 s[2:3], -1
	v_add_f32_e32 v17, 1.0, v17
	v_rcp_f32_e32 v17, v17
	s_waitcnt lgkmcnt(0)
	v_lshlrev_b32_e32 v16, 16, v16
	v_mul_f32_e32 v16, v17, v16
	v_cvt_pk_bf16_f32 v18, v16, s0
	v_lshl_add_u64 v[16:17], v[32:33], 0, v[34:35]
	global_store_short v[16:17], v18, off
	ds_read_u16 v18, v95 offset:96
	v_or_b32_e32 v16, 48, v64
	v_ashrrev_i32_e32 v17, 31, v16
	v_lshlrev_b64 v[16:17], 1, v[16:17]
	s_waitcnt lgkmcnt(0)
	v_lshlrev_b32_e32 v18, 16, v18
	v_mul_f32_e32 v12, v12, v18
	v_cvt_pk_bf16_f32 v12, v12, s0
	v_lshl_add_u64 v[18:19], v[48:49], 0, v[16:17]
	global_store_short v[18:19], v12, off
	ds_read_u16 v12, v93 offset:96
	s_waitcnt lgkmcnt(0)
	v_lshlrev_b32_e32 v12, 16, v12
	v_mul_f32_e32 v12, v13, v12
	v_cvt_pk_bf16_f32 v18, v12, s0
	v_lshl_add_u64 v[12:13], v[44:45], 0, v[16:17]
	global_store_short v[12:13], v18, off
	v_add_f32_e32 v13, v14, v92
	v_mul_f32_e32 v13, 0xbfb8aa3b, v13
	v_exp_f32_e32 v13, v13
	ds_read_u16 v12, v93 offset:1136
	v_add_f32_e32 v13, 1.0, v13
	v_rcp_f32_e32 v13, v13
	s_waitcnt lgkmcnt(0)
; __device__ __forceinline__ float bf2f(unsigned short h) { return __uint_as_float(((unsigned)h) << 16); }
; __device__ __forceinline__ unsigned short f2bf(float f) { return (unsigned short)(cvt_pk(f, 0.f) & 0xffffu); }
; __device__ __forceinline__ float sigmoidf_(float x) { return fast_rcp(1.f + fast_exp2(-x * LOG2E)); }
; __device__ __forceinline__ void s5_unit(ArgsP A, int l, int unit, unsigned char* lds, int wave_, int lane_) {
;     ...
;     for (int nb = 0; nb < 4; ++nb) { const int n = 64 * wave + 16 * nb + (lane & 15); const float bgl = bglv[nb];
; #pragma unroll
;         for (int mb = 0; mb < 4; ++mb)
; #pragma unroll
;             for (int i = 0; i < 4; ++i) { const int t = 16 * mb + 4 * (lane >> 4) + i; const float yv = bf2f(ys[t * YS_STRIDE + n]);
;                 MIX[(size_t)(rowbase + t) * DM + n] = f2bf(yv * sigmoidf_(acc[mb][nb][i] + bgl)); } }
;     __syncthreads();
	v_lshlrev_b32_e32 v12, 16, v12
	v_mul_f32_e32 v12, v13, v12
	v_cvt_pk_bf16_f32 v14, v12, s0
	v_lshl_add_u64 v[12:13], v[50:51], 0, v[16:17]
	global_store_short v[12:13], v14, off
	v_add_f32_e32 v13, v15, v92
	v_mul_f32_e32 v13, 0xbfb8aa3b, v13
	v_exp_f32_e32 v13, v13
	ds_read_u16 v12, v93 offset:2176
	v_add_f32_e32 v13, 1.0, v13
	v_rcp_f32_e32 v13, v13
	s_waitcnt lgkmcnt(0)
	v_lshlrev_b32_e32 v12, 16, v12
	v_mul_f32_e32 v12, v13, v12
	v_cvt_pk_bf16_f32 v14, v12, s0
	v_lshl_add_u64 v[12:13], v[46:47], 0, v[16:17]
	global_store_short v[12:13], v14, off
	ds_read_u16 v12, v93 offset:15696
	s_waitcnt lgkmcnt(0)
	v_lshlrev_b32_e32 v12, 16, v12
	v_mul_f32_e32 v8, v8, v12
	v_cvt_pk_bf16_f32 v8, v8, s0
	v_lshl_add_u64 v[12:13], v[52:53], 0, v[16:17]
	global_store_short v[12:13], v8, off
	ds_read_u16 v8, v93 offset:16736
	s_waitcnt lgkmcnt(0)
	v_lshlrev_b32_e32 v8, 16, v8
	v_mul_f32_e32 v8, v9, v8
	v_cvt_pk_bf16_f32 v12, v8, s0
	v_lshl_add_u64 v[8:9], v[54:55], 0, v[16:17]
	global_store_short v[8:9], v12, off
	v_add_f32_e32 v9, v10, v92
	v_mul_f32_e32 v9, 0xbfb8aa3b, v9
	v_exp_f32_e32 v9, v9
	ds_read_u16 v8, v93 offset:17776
	v_add_f32_e32 v9, 1.0, v9
	v_rcp_f32_e32 v9, v9
	s_waitcnt lgkmcnt(0)
	v_lshlrev_b32_e32 v8, 16, v8
	v_mul_f32_e32 v8, v9, v8
	v_cvt_pk_bf16_f32 v10, v8, s0
	v_lshl_add_u64 v[8:9], v[56:57], 0, v[16:17]
	global_store_short v[8:9], v10, off
	v_add_f32_e32 v9, v11, v92
	v_mul_f32_e32 v9, 0xbfb8aa3b, v9
	v_exp_f32_e32 v9, v9
	ds_read_u16 v8, v93 offset:18816
	v_add_f32_e32 v9, 1.0, v9
	v_rcp_f32_e32 v9, v9
	s_waitcnt lgkmcnt(0)
	v_lshlrev_b32_e32 v8, 16, v8
	v_mul_f32_e32 v8, v9, v8
	v_cvt_pk_bf16_f32 v10, v8, s0
	v_lshl_add_u64 v[8:9], v[42:43], 0, v[16:17]
	global_store_short v[8:9], v10, off
	ds_read_u16 v8, v93 offset:32336
	s_waitcnt lgkmcnt(0)
	v_lshlrev_b32_e32 v8, 16, v8
	v_mul_f32_e32 v4, v4, v8
	v_cvt_pk_bf16_f32 v4, v4, s0
	v_lshl_add_u64 v[8:9], v[58:59], 0, v[16:17]
	global_store_short v[8:9], v4, off
	ds_read_u16 v4, v93 offset:33376
	s_waitcnt lgkmcnt(0)
	v_lshlrev_b32_e32 v4, 16, v4
	v_mul_f32_e32 v4, v5, v4
	v_cvt_pk_bf16_f32 v8, v4, s0
	v_lshl_add_u64 v[4:5], v[60:61], 0, v[16:17]
	global_store_short v[4:5], v8, off
	v_add_f32_e32 v5, v6, v92
	v_mul_f32_e32 v5, 0xbfb8aa3b, v5
	v_exp_f32_e32 v5, v5
	ds_read_u16 v4, v93 offset:34416
	v_add_f32_e32 v5, 1.0, v5
	v_rcp_f32_e32 v5, v5
	s_waitcnt lgkmcnt(0)
	v_lshlrev_b32_e32 v4, 16, v4
	v_mul_f32_e32 v4, v5, v4
	v_cvt_pk_bf16_f32 v6, v4, s0
	v_lshl_add_u64 v[4:5], v[62:63], 0, v[16:17]
	global_store_short v[4:5], v6, off
	v_add_f32_e32 v5, v7, v92
	v_mul_f32_e32 v5, 0xbfb8aa3b, v5
	v_exp_f32_e32 v5, v5
	ds_read_u16 v4, v93 offset:35456
	v_add_f32_e32 v5, 1.0, v5
	v_rcp_f32_e32 v5, v5
	s_waitcnt lgkmcnt(0)
	v_lshlrev_b32_e32 v4, 16, v4
	v_mul_f32_e32 v4, v5, v4
	v_cvt_pk_bf16_f32 v6, v4, s0
	v_lshl_add_u64 v[4:5], v[66:67], 0, v[16:17]
	global_store_short v[4:5], v6, off
	ds_read_u16 v4, v65 offset:96
	s_waitcnt lgkmcnt(0)
	v_lshlrev_b32_e32 v4, 16, v4
	v_mul_f32_e32 v0, v0, v4
	v_cvt_pk_bf16_f32 v0, v0, s0
	v_lshl_add_u64 v[4:5], v[36:37], 0, v[16:17]
	global_store_short v[4:5], v0, off
	ds_read_u16 v0, v65 offset:1136
	s_waitcnt lgkmcnt(0)
	v_lshlrev_b32_e32 v0, 16, v0
	v_mul_f32_e32 v0, v1, v0
	v_cvt_pk_bf16_f32 v4, v0, s0
	v_lshl_add_u64 v[0:1], v[38:39], 0, v[16:17]
	global_store_short v[0:1], v4, off
	v_add_f32_e32 v1, v2, v92
	v_mul_f32_e32 v1, 0xbfb8aa3b, v1
	v_exp_f32_e32 v1, v1
	ds_read_u16 v0, v65 offset:2176
	v_add_f32_e32 v1, 1.0, v1
	v_rcp_f32_e32 v1, v1
	s_waitcnt lgkmcnt(0)
	v_lshlrev_b32_e32 v0, 16, v0
	v_mul_f32_e32 v0, v1, v0
	v_cvt_pk_bf16_f32 v2, v0, s0
	v_lshl_add_u64 v[0:1], v[40:41], 0, v[16:17]
	global_store_short v[0:1], v2, off
	v_add_f32_e32 v1, v3, v92
	v_mul_f32_e32 v1, 0xbfb8aa3b, v1
	v_exp_f32_e32 v1, v1
	ds_read_u16 v0, v65 offset:3216
	v_add_f32_e32 v1, 1.0, v1
	v_rcp_f32_e32 v1, v1
	s_waitcnt lgkmcnt(0)
	v_lshlrev_b32_e32 v0, 16, v0
	v_mul_f32_e32 v0, v1, v0
	v_cvt_pk_bf16_f32 v2, v0, s0
	v_lshl_add_u64 v[0:1], v[32:33], 0, v[16:17]
	global_store_short v[0:1], v2, off
	s_waitcnt vmcnt(63) expcnt(7) lgkmcnt(15)
	s_barrier
	s_branch .LBB0_785
